# v7 + GEMM K-loops: first iteration peeled with C=0 MFMAs (no per-unit accumulator zeroing), mid-block setprio 0/1 pairs and duplicate lgkmcnt waits dropped
# speedup vs baseline: 1.0095x; 1.0046x over previous
.LBB0_136:
	s_add_u32 s2, s18, 0x100
	s_addc_u32 s3, s19, 0
	s_mov_b32 s25, -2
	s_waitcnt vmcnt(0) lgkmcnt(0)
	s_add_u32 s0, s16, 0x100
	s_addc_u32 s1, s17, 0
	s_add_i32 s30, 0, 0x10000
	s_cmp_eq_u32 s25, 28
	s_cselect_b32 s21, s61, s1
	s_cselect_b32 s20, s60, s0
	s_cselect_b32 s19, s63, s3
	s_cselect_b32 s18, s62, s2
	s_add_i32 s33, 0, 0x14000
	v_add_u32_e32 v142, s30, v210
	v_add_u32_e32 v172, s33, v210
	ds_read_b128 v[130:133], v142
	ds_read_b128 v[134:137], v142 offset:1024
	ds_read_b128 v[138:141], v142 offset:2048
	ds_read_b128 v[142:145], v142 offset:3072
	ds_read_b128 v[146:149], v172
	ds_read_b128 v[150:153], v172 offset:1024
	ds_read_b128 v[154:157], v172 offset:2048
	ds_read_b128 v[172:175], v172 offset:3072
	v_lshl_add_u64 v[194:195], s[16:17], 0, v[168:169]
	s_add_i32 m0, s27, 0xc000
	ds_read_b128 v[176:179], v212
	ds_read_b128 v[180:183], v212 offset:1024
	ds_read_b128 v[184:187], v212 offset:2048
	ds_read_b128 v[188:191], v212 offset:3072
	ds_read_b128 v[214:217], v212 offset:4096
	ds_read_b128 v[218:221], v212 offset:5120
	ds_read_b128 v[222:225], v212 offset:6144
	ds_read_b128 v[240:243], v212 offset:7168
	global_load_lds_dwordx4 v[194:195], off
	v_lshl_add_u64 v[194:195], s[16:17], 0, v[170:171]
	s_add_i32 m0, s27, 0xe000
	s_nop 0
	global_load_lds_dwordx4 v[194:195], off
	s_waitcnt vmcnt(8)
	s_waitcnt lgkmcnt(0)
	s_barrier
	s_setprio 1
	v_mfma_f32_16x16x32_bf16 v[126:129], v[130:133], v[176:179], 0
	v_mfma_f32_16x16x32_bf16 v[122:125], v[138:141], v[176:179], 0
	v_mfma_f32_16x16x32_bf16 v[110:113], v[130:133], v[184:187], 0
	v_mfma_f32_16x16x32_bf16 v[106:109], v[138:141], v[184:187], 0
	v_mfma_f32_16x16x32_bf16 v[94:97], v[130:133], v[214:217], 0
	v_mfma_f32_16x16x32_bf16 v[90:93], v[138:141], v[214:217], 0
	v_mfma_f32_16x16x32_bf16 v[78:81], v[130:133], v[222:225], 0
	v_mfma_f32_16x16x32_bf16 v[74:77], v[138:141], v[222:225], 0
	v_mfma_f32_16x16x32_bf16 v[126:129], v[134:137], v[180:183], v[126:129]
	v_mfma_f32_16x16x32_bf16 v[122:125], v[142:145], v[180:183], v[122:125]
	v_mfma_f32_16x16x32_bf16 v[110:113], v[134:137], v[188:191], v[110:113]
	v_mfma_f32_16x16x32_bf16 v[106:109], v[142:145], v[188:191], v[106:109]
	v_mfma_f32_16x16x32_bf16 v[94:97], v[134:137], v[218:221], v[94:97]
	v_mfma_f32_16x16x32_bf16 v[90:93], v[142:145], v[218:221], v[90:93]
	v_mfma_f32_16x16x32_bf16 v[78:81], v[134:137], v[240:243], v[78:81]
	v_mfma_f32_16x16x32_bf16 v[74:77], v[142:145], v[240:243], v[74:77]
	v_mfma_f32_16x16x32_bf16 v[118:121], v[146:149], v[176:179], 0
	v_mfma_f32_16x16x32_bf16 v[114:117], v[154:157], v[176:179], 0
	v_mfma_f32_16x16x32_bf16 v[102:105], v[146:149], v[184:187], 0
	v_mfma_f32_16x16x32_bf16 v[98:101], v[154:157], v[184:187], 0
	v_mfma_f32_16x16x32_bf16 v[86:89], v[146:149], v[214:217], 0
	v_mfma_f32_16x16x32_bf16 v[82:85], v[154:157], v[214:217], 0
	v_mfma_f32_16x16x32_bf16 v[70:73], v[146:149], v[222:225], 0
	v_mfma_f32_16x16x32_bf16 v[66:69], v[154:157], v[222:225], 0
	v_mfma_f32_16x16x32_bf16 v[118:121], v[150:153], v[180:183], v[118:121]
	v_mfma_f32_16x16x32_bf16 v[114:117], v[172:175], v[180:183], v[114:117]
	v_mfma_f32_16x16x32_bf16 v[102:105], v[150:153], v[188:191], v[102:105]
	v_mfma_f32_16x16x32_bf16 v[98:101], v[172:175], v[188:191], v[98:101]
	v_mfma_f32_16x16x32_bf16 v[86:89], v[150:153], v[218:221], v[86:89]
	v_mfma_f32_16x16x32_bf16 v[82:85], v[172:175], v[218:221], v[82:85]
	v_mfma_f32_16x16x32_bf16 v[70:73], v[150:153], v[240:243], v[70:73]
	v_mfma_f32_16x16x32_bf16 v[66:69], v[172:175], v[240:243], v[66:69]
	s_setprio 0
	s_barrier
	s_add_i32 s16, s30, s26
	v_lshl_add_u64 v[194:195], s[18:19], 0, v[0:1]
	s_mov_b32 m0, s16
	ds_read_b128 v[176:179], v212 offset:16384
	ds_read_b128 v[180:183], v212 offset:17408
	ds_read_b128 v[184:187], v212 offset:18432
	ds_read_b128 v[188:191], v212 offset:19456
	ds_read_b128 v[214:217], v212 offset:20480
	ds_read_b128 v[218:221], v212 offset:21504
	ds_read_b128 v[222:225], v212 offset:22528
	ds_read_b128 v[240:243], v212 offset:23552
	global_load_lds_dwordx4 v[194:195], off
	s_add_i32 m0, s16, 0x2000
	s_add_u32 s16, s18, 0x88000
	v_lshl_add_u64 v[196:197], s[18:19], 0, v[162:163]
	s_addc_u32 s17, s19, 0
	s_add_i32 s30, s33, s26
	global_load_lds_dwordx4 v[196:197], off
	v_lshl_add_u64 v[198:199], s[16:17], 0, v[0:1]
	s_mov_b32 m0, s30
	v_lshl_add_u64 v[200:201], s[20:21], 0, v[160:161]
	global_load_lds_dwordx4 v[198:199], off
	v_lshl_add_u64 v[198:199], s[16:17], 0, v[162:163]
	s_add_i32 m0, s30, 0x2000
	s_nop 0
	global_load_lds_dwordx4 v[198:199], off
	v_lshl_add_u64 v[198:199], s[20:21], 0, v[158:159]
	s_mov_b32 m0, s27
	s_nop 0
	global_load_lds_dwordx4 v[198:199], off
	s_mov_b32 m0, s28
	s_nop 0
	global_load_lds_dwordx4 v[200:201], off
	s_waitcnt vmcnt(8)
	s_waitcnt lgkmcnt(0)
	s_barrier
	s_setprio 1
	v_mfma_f32_16x16x32_bf16 v[62:65], v[130:133], v[176:179], 0
	v_mfma_f32_16x16x32_bf16 v[58:61], v[138:141], v[176:179], 0
	v_mfma_f32_16x16x32_bf16 v[46:49], v[130:133], v[184:187], 0
	v_mfma_f32_16x16x32_bf16 v[42:45], v[138:141], v[184:187], 0
	v_mfma_f32_16x16x32_bf16 v[30:33], v[130:133], v[214:217], 0
	v_mfma_f32_16x16x32_bf16 v[26:29], v[138:141], v[214:217], 0
	v_mfma_f32_16x16x32_bf16 v[14:17], v[130:133], v[222:225], 0
	v_mfma_f32_16x16x32_bf16 v[10:13], v[138:141], v[222:225], 0
	v_mfma_f32_16x16x32_bf16 v[62:65], v[134:137], v[180:183], v[62:65]
	v_mfma_f32_16x16x32_bf16 v[58:61], v[142:145], v[180:183], v[58:61]
	v_mfma_f32_16x16x32_bf16 v[46:49], v[134:137], v[188:191], v[46:49]
	v_mfma_f32_16x16x32_bf16 v[42:45], v[142:145], v[188:191], v[42:45]
	v_mfma_f32_16x16x32_bf16 v[30:33], v[134:137], v[218:221], v[30:33]
	v_mfma_f32_16x16x32_bf16 v[26:29], v[142:145], v[218:221], v[26:29]
	v_mfma_f32_16x16x32_bf16 v[14:17], v[134:137], v[240:243], v[14:17]
	v_mfma_f32_16x16x32_bf16 v[10:13], v[142:145], v[240:243], v[10:13]
	v_mfma_f32_16x16x32_bf16 v[54:57], v[146:149], v[176:179], 0
	v_mfma_f32_16x16x32_bf16 v[50:53], v[154:157], v[176:179], 0
	v_mfma_f32_16x16x32_bf16 v[38:41], v[146:149], v[184:187], 0
	v_mfma_f32_16x16x32_bf16 v[34:37], v[154:157], v[184:187], 0
	v_mfma_f32_16x16x32_bf16 v[22:25], v[146:149], v[214:217], 0
	v_mfma_f32_16x16x32_bf16 v[18:21], v[154:157], v[214:217], 0
	v_mfma_f32_16x16x32_bf16 v[6:9], v[146:149], v[222:225], 0
	v_mfma_f32_16x16x32_bf16 v[2:5], v[154:157], v[222:225], 0
	v_mfma_f32_16x16x32_bf16 v[54:57], v[150:153], v[180:183], v[54:57]
	v_mfma_f32_16x16x32_bf16 v[50:53], v[172:175], v[180:183], v[50:53]
	v_mfma_f32_16x16x32_bf16 v[38:41], v[150:153], v[188:191], v[38:41]
	v_mfma_f32_16x16x32_bf16 v[34:37], v[172:175], v[188:191], v[34:37]
	v_mfma_f32_16x16x32_bf16 v[22:25], v[150:153], v[218:221], v[22:25]
	v_mfma_f32_16x16x32_bf16 v[18:21], v[172:175], v[218:221], v[18:21]
	v_mfma_f32_16x16x32_bf16 v[6:9], v[150:153], v[240:243], v[6:9]
	v_mfma_f32_16x16x32_bf16 v[2:5], v[172:175], v[240:243], v[2:5]
	s_setprio 0
	s_barrier
	s_add_i32 s30, 0, 0x18000
	s_add_i32 s33, 0, 0x1c000
	v_add_u32_e32 v142, s30, v210
	v_add_u32_e32 v172, s33, v210
	ds_read_b128 v[130:133], v142
	ds_read_b128 v[134:137], v142 offset:1024
	ds_read_b128 v[138:141], v142 offset:2048
	ds_read_b128 v[142:145], v142 offset:3072
	ds_read_b128 v[146:149], v172
	ds_read_b128 v[150:153], v172 offset:1024
	ds_read_b128 v[154:157], v172 offset:2048
	ds_read_b128 v[172:175], v172 offset:3072
	s_add_u32 s16, s20, 0x88000
	s_addc_u32 s17, s21, 0
	s_mov_b32 m0, s29
	v_lshl_add_u64 v[202:203], s[16:17], 0, v[158:159]
	ds_read_b128 v[176:179], v212 offset:32768
	ds_read_b128 v[180:183], v212 offset:33792
	ds_read_b128 v[184:187], v212 offset:34816
	ds_read_b128 v[188:191], v212 offset:35840
	ds_read_b128 v[214:217], v212 offset:36864
	ds_read_b128 v[218:221], v212 offset:37888
	ds_read_b128 v[222:225], v212 offset:38912
	ds_read_b128 v[240:243], v212 offset:39936
	global_load_lds_dwordx4 v[202:203], off
	v_lshl_add_u64 v[202:203], s[16:17], 0, v[160:161]
	s_mov_b32 m0, s64
	s_nop 0
	global_load_lds_dwordx4 v[202:203], off
	s_waitcnt vmcnt(8)
	s_waitcnt lgkmcnt(0)
	s_barrier
	s_setprio 1
	v_mfma_f32_16x16x32_bf16 v[126:129], v[130:133], v[176:179], v[126:129]
	v_mfma_f32_16x16x32_bf16 v[122:125], v[138:141], v[176:179], v[122:125]
	v_mfma_f32_16x16x32_bf16 v[110:113], v[130:133], v[184:187], v[110:113]
	v_mfma_f32_16x16x32_bf16 v[106:109], v[138:141], v[184:187], v[106:109]
	v_mfma_f32_16x16x32_bf16 v[94:97], v[130:133], v[214:217], v[94:97]
	v_mfma_f32_16x16x32_bf16 v[90:93], v[138:141], v[214:217], v[90:93]
	v_mfma_f32_16x16x32_bf16 v[78:81], v[130:133], v[222:225], v[78:81]
	v_mfma_f32_16x16x32_bf16 v[74:77], v[138:141], v[222:225], v[74:77]
	v_mfma_f32_16x16x32_bf16 v[126:129], v[134:137], v[180:183], v[126:129]
	v_mfma_f32_16x16x32_bf16 v[122:125], v[142:145], v[180:183], v[122:125]
	v_mfma_f32_16x16x32_bf16 v[110:113], v[134:137], v[188:191], v[110:113]
	v_mfma_f32_16x16x32_bf16 v[106:109], v[142:145], v[188:191], v[106:109]
	v_mfma_f32_16x16x32_bf16 v[94:97], v[134:137], v[218:221], v[94:97]
	v_mfma_f32_16x16x32_bf16 v[90:93], v[142:145], v[218:221], v[90:93]
	v_mfma_f32_16x16x32_bf16 v[78:81], v[134:137], v[240:243], v[78:81]
	v_mfma_f32_16x16x32_bf16 v[74:77], v[142:145], v[240:243], v[74:77]
	v_mfma_f32_16x16x32_bf16 v[118:121], v[146:149], v[176:179], v[118:121]
	v_mfma_f32_16x16x32_bf16 v[114:117], v[154:157], v[176:179], v[114:117]
	v_mfma_f32_16x16x32_bf16 v[102:105], v[146:149], v[184:187], v[102:105]
	v_mfma_f32_16x16x32_bf16 v[98:101], v[154:157], v[184:187], v[98:101]
	v_mfma_f32_16x16x32_bf16 v[86:89], v[146:149], v[214:217], v[86:89]
	v_mfma_f32_16x16x32_bf16 v[82:85], v[154:157], v[214:217], v[82:85]
	v_mfma_f32_16x16x32_bf16 v[70:73], v[146:149], v[222:225], v[70:73]
	v_mfma_f32_16x16x32_bf16 v[66:69], v[154:157], v[222:225], v[66:69]
	v_mfma_f32_16x16x32_bf16 v[118:121], v[150:153], v[180:183], v[118:121]
	v_mfma_f32_16x16x32_bf16 v[114:117], v[172:175], v[180:183], v[114:117]
	v_mfma_f32_16x16x32_bf16 v[102:105], v[150:153], v[188:191], v[102:105]
	v_mfma_f32_16x16x32_bf16 v[98:101], v[172:175], v[188:191], v[98:101]
	v_mfma_f32_16x16x32_bf16 v[86:89], v[150:153], v[218:221], v[86:89]
	v_mfma_f32_16x16x32_bf16 v[82:85], v[172:175], v[218:221], v[82:85]
	v_mfma_f32_16x16x32_bf16 v[70:73], v[150:153], v[240:243], v[70:73]
	v_mfma_f32_16x16x32_bf16 v[66:69], v[172:175], v[240:243], v[66:69]
	s_setprio 0
	s_barrier
	s_add_i32 s16, s30, s26
	v_lshl_add_u64 v[194:195], v[194:195], 0, s[22:23]
	s_mov_b32 m0, s16
	ds_read_b128 v[176:179], v212 offset:49152
	ds_read_b128 v[180:183], v212 offset:50176
	ds_read_b128 v[184:187], v212 offset:51200
	ds_read_b128 v[188:191], v212 offset:52224
	ds_read_b128 v[214:217], v212 offset:53248
	ds_read_b128 v[218:221], v212 offset:54272
	ds_read_b128 v[222:225], v212 offset:55296
	ds_read_b128 v[240:243], v212 offset:56320
	global_load_lds_dwordx4 v[194:195], off
	s_add_i32 m0, s16, 0x2000
	s_add_u32 s16, s18, 0x88080
	v_lshl_add_u64 v[194:195], v[196:197], 0, s[22:23]
	s_addc_u32 s17, s19, 0
	s_add_i32 s18, s33, s26
	global_load_lds_dwordx4 v[194:195], off
	v_lshl_add_u64 v[194:195], s[16:17], 0, v[0:1]
	s_mov_b32 m0, s18
	s_nop 0
	global_load_lds_dwordx4 v[194:195], off
	v_lshl_add_u64 v[194:195], s[16:17], 0, v[162:163]
	s_add_i32 m0, s18, 0x2000
	s_nop 0
	global_load_lds_dwordx4 v[194:195], off
	v_lshl_add_u64 v[194:195], v[198:199], 0, s[22:23]
	s_mov_b32 m0, s73
	s_nop 0
	global_load_lds_dwordx4 v[194:195], off
	v_lshl_add_u64 v[194:195], v[200:201], 0, s[22:23]
	s_mov_b32 m0, s74
	s_nop 0
	global_load_lds_dwordx4 v[194:195], off
	s_waitcnt vmcnt(8)
	s_waitcnt lgkmcnt(0)
	s_barrier
	s_setprio 1
	v_mfma_f32_16x16x32_bf16 v[62:65], v[130:133], v[176:179], v[62:65]
	v_mfma_f32_16x16x32_bf16 v[58:61], v[138:141], v[176:179], v[58:61]
	v_mfma_f32_16x16x32_bf16 v[46:49], v[130:133], v[184:187], v[46:49]
	v_mfma_f32_16x16x32_bf16 v[42:45], v[138:141], v[184:187], v[42:45]
	v_mfma_f32_16x16x32_bf16 v[30:33], v[130:133], v[214:217], v[30:33]
	v_mfma_f32_16x16x32_bf16 v[26:29], v[138:141], v[214:217], v[26:29]
	v_mfma_f32_16x16x32_bf16 v[14:17], v[130:133], v[222:225], v[14:17]
	v_mfma_f32_16x16x32_bf16 v[10:13], v[138:141], v[222:225], v[10:13]
	v_mfma_f32_16x16x32_bf16 v[62:65], v[134:137], v[180:183], v[62:65]
	v_mfma_f32_16x16x32_bf16 v[58:61], v[142:145], v[180:183], v[58:61]
	v_mfma_f32_16x16x32_bf16 v[46:49], v[134:137], v[188:191], v[46:49]
	v_mfma_f32_16x16x32_bf16 v[42:45], v[142:145], v[188:191], v[42:45]
	v_mfma_f32_16x16x32_bf16 v[30:33], v[134:137], v[218:221], v[30:33]
	v_mfma_f32_16x16x32_bf16 v[26:29], v[142:145], v[218:221], v[26:29]
	v_mfma_f32_16x16x32_bf16 v[14:17], v[134:137], v[240:243], v[14:17]
	v_mfma_f32_16x16x32_bf16 v[10:13], v[142:145], v[240:243], v[10:13]
	v_mfma_f32_16x16x32_bf16 v[54:57], v[146:149], v[176:179], v[54:57]
	v_mfma_f32_16x16x32_bf16 v[50:53], v[154:157], v[176:179], v[50:53]
	v_mfma_f32_16x16x32_bf16 v[38:41], v[146:149], v[184:187], v[38:41]
	v_mfma_f32_16x16x32_bf16 v[34:37], v[154:157], v[184:187], v[34:37]
	v_mfma_f32_16x16x32_bf16 v[22:25], v[146:149], v[214:217], v[22:25]
	v_mfma_f32_16x16x32_bf16 v[18:21], v[154:157], v[214:217], v[18:21]
	v_mfma_f32_16x16x32_bf16 v[6:9], v[146:149], v[222:225], v[6:9]
	v_mfma_f32_16x16x32_bf16 v[2:5], v[154:157], v[222:225], v[2:5]
	v_mfma_f32_16x16x32_bf16 v[54:57], v[150:153], v[180:183], v[54:57]
	v_mfma_f32_16x16x32_bf16 v[50:53], v[172:175], v[180:183], v[50:53]
	v_mfma_f32_16x16x32_bf16 v[38:41], v[150:153], v[188:191], v[38:41]
	v_mfma_f32_16x16x32_bf16 v[34:37], v[172:175], v[188:191], v[34:37]
	v_mfma_f32_16x16x32_bf16 v[22:25], v[150:153], v[218:221], v[22:25]
	v_mfma_f32_16x16x32_bf16 v[18:21], v[172:175], v[218:221], v[18:21]
	v_mfma_f32_16x16x32_bf16 v[6:9], v[150:153], v[240:243], v[6:9]
	v_mfma_f32_16x16x32_bf16 v[2:5], v[172:175], v[240:243], v[2:5]
	s_setprio 0
	s_barrier
	s_add_i32 s25, s25, 2
	s_add_u32 s2, s2, 0x100
	s_addc_u32 s3, s3, 0
	s_cmp_gt_u32 s25, 29
	s_mov_b64 s[16:17], s[0:1]
.LBB0_137:
	s_add_u32 s0, s16, 0x100
	s_addc_u32 s1, s17, 0
	s_add_i32 s30, 0, 0x10000
	s_cmp_eq_u32 s25, 28
	s_cselect_b32 s21, s61, s1
	s_cselect_b32 s20, s60, s0
	s_cselect_b32 s19, s63, s3
	s_cselect_b32 s18, s62, s2
	s_add_i32 s33, 0, 0x14000
	v_add_u32_e32 v142, s30, v210
	v_add_u32_e32 v172, s33, v210
	ds_read_b128 v[130:133], v142
	ds_read_b128 v[134:137], v142 offset:1024
	ds_read_b128 v[138:141], v142 offset:2048
	ds_read_b128 v[142:145], v142 offset:3072
	ds_read_b128 v[146:149], v172
	ds_read_b128 v[150:153], v172 offset:1024
	ds_read_b128 v[154:157], v172 offset:2048
	ds_read_b128 v[172:175], v172 offset:3072
	v_lshl_add_u64 v[194:195], s[16:17], 0, v[168:169]
	s_add_i32 m0, s27, 0xc000
	ds_read_b128 v[176:179], v212
	ds_read_b128 v[180:183], v212 offset:1024
	ds_read_b128 v[184:187], v212 offset:2048
	ds_read_b128 v[188:191], v212 offset:3072
	ds_read_b128 v[214:217], v212 offset:4096
	ds_read_b128 v[218:221], v212 offset:5120
	ds_read_b128 v[222:225], v212 offset:6144
	ds_read_b128 v[240:243], v212 offset:7168
	global_load_lds_dwordx4 v[194:195], off
	v_lshl_add_u64 v[194:195], s[16:17], 0, v[170:171]
	s_add_i32 m0, s27, 0xe000
	s_nop 0
	global_load_lds_dwordx4 v[194:195], off
	s_waitcnt vmcnt(8)
	s_waitcnt lgkmcnt(0)
	s_barrier
	s_setprio 1
	v_mfma_f32_16x16x32_bf16 v[126:129], v[130:133], v[176:179], v[126:129]
	v_mfma_f32_16x16x32_bf16 v[122:125], v[138:141], v[176:179], v[122:125]
	v_mfma_f32_16x16x32_bf16 v[110:113], v[130:133], v[184:187], v[110:113]
	v_mfma_f32_16x16x32_bf16 v[106:109], v[138:141], v[184:187], v[106:109]
	v_mfma_f32_16x16x32_bf16 v[94:97], v[130:133], v[214:217], v[94:97]
	v_mfma_f32_16x16x32_bf16 v[90:93], v[138:141], v[214:217], v[90:93]
	v_mfma_f32_16x16x32_bf16 v[78:81], v[130:133], v[222:225], v[78:81]
	v_mfma_f32_16x16x32_bf16 v[74:77], v[138:141], v[222:225], v[74:77]
	v_mfma_f32_16x16x32_bf16 v[126:129], v[134:137], v[180:183], v[126:129]
	v_mfma_f32_16x16x32_bf16 v[122:125], v[142:145], v[180:183], v[122:125]
	v_mfma_f32_16x16x32_bf16 v[110:113], v[134:137], v[188:191], v[110:113]
	v_mfma_f32_16x16x32_bf16 v[106:109], v[142:145], v[188:191], v[106:109]
	v_mfma_f32_16x16x32_bf16 v[94:97], v[134:137], v[218:221], v[94:97]
	v_mfma_f32_16x16x32_bf16 v[90:93], v[142:145], v[218:221], v[90:93]
	v_mfma_f32_16x16x32_bf16 v[78:81], v[134:137], v[240:243], v[78:81]
	v_mfma_f32_16x16x32_bf16 v[74:77], v[142:145], v[240:243], v[74:77]
	v_mfma_f32_16x16x32_bf16 v[118:121], v[146:149], v[176:179], v[118:121]
	v_mfma_f32_16x16x32_bf16 v[114:117], v[154:157], v[176:179], v[114:117]
	v_mfma_f32_16x16x32_bf16 v[102:105], v[146:149], v[184:187], v[102:105]
	v_mfma_f32_16x16x32_bf16 v[98:101], v[154:157], v[184:187], v[98:101]
	v_mfma_f32_16x16x32_bf16 v[86:89], v[146:149], v[214:217], v[86:89]
	v_mfma_f32_16x16x32_bf16 v[82:85], v[154:157], v[214:217], v[82:85]
	v_mfma_f32_16x16x32_bf16 v[70:73], v[146:149], v[222:225], v[70:73]
	v_mfma_f32_16x16x32_bf16 v[66:69], v[154:157], v[222:225], v[66:69]
	v_mfma_f32_16x16x32_bf16 v[118:121], v[150:153], v[180:183], v[118:121]
	v_mfma_f32_16x16x32_bf16 v[114:117], v[172:175], v[180:183], v[114:117]
	v_mfma_f32_16x16x32_bf16 v[102:105], v[150:153], v[188:191], v[102:105]
	v_mfma_f32_16x16x32_bf16 v[98:101], v[172:175], v[188:191], v[98:101]
	v_mfma_f32_16x16x32_bf16 v[86:89], v[150:153], v[218:221], v[86:89]
	v_mfma_f32_16x16x32_bf16 v[82:85], v[172:175], v[218:221], v[82:85]
	v_mfma_f32_16x16x32_bf16 v[70:73], v[150:153], v[240:243], v[70:73]
	v_mfma_f32_16x16x32_bf16 v[66:69], v[172:175], v[240:243], v[66:69]
	s_setprio 0
	s_barrier
	s_add_i32 s16, s30, s26
	v_lshl_add_u64 v[194:195], s[18:19], 0, v[0:1]
	s_mov_b32 m0, s16
	ds_read_b128 v[176:179], v212 offset:16384
	ds_read_b128 v[180:183], v212 offset:17408
	ds_read_b128 v[184:187], v212 offset:18432
	ds_read_b128 v[188:191], v212 offset:19456
	ds_read_b128 v[214:217], v212 offset:20480
	ds_read_b128 v[218:221], v212 offset:21504
	ds_read_b128 v[222:225], v212 offset:22528
	ds_read_b128 v[240:243], v212 offset:23552
	global_load_lds_dwordx4 v[194:195], off
	s_add_i32 m0, s16, 0x2000
	s_add_u32 s16, s18, 0x88000
	v_lshl_add_u64 v[196:197], s[18:19], 0, v[162:163]
	s_addc_u32 s17, s19, 0
	s_add_i32 s30, s33, s26
	global_load_lds_dwordx4 v[196:197], off
	v_lshl_add_u64 v[198:199], s[16:17], 0, v[0:1]
	s_mov_b32 m0, s30
	v_lshl_add_u64 v[200:201], s[20:21], 0, v[160:161]
	global_load_lds_dwordx4 v[198:199], off
	v_lshl_add_u64 v[198:199], s[16:17], 0, v[162:163]
	s_add_i32 m0, s30, 0x2000
	s_nop 0
	global_load_lds_dwordx4 v[198:199], off
	v_lshl_add_u64 v[198:199], s[20:21], 0, v[158:159]
	s_mov_b32 m0, s27
	s_nop 0
	global_load_lds_dwordx4 v[198:199], off
	s_mov_b32 m0, s28
	s_nop 0
	global_load_lds_dwordx4 v[200:201], off
	s_waitcnt vmcnt(8)
	s_waitcnt lgkmcnt(0)
	s_barrier
	s_setprio 1
	v_mfma_f32_16x16x32_bf16 v[62:65], v[130:133], v[176:179], v[62:65]
	v_mfma_f32_16x16x32_bf16 v[58:61], v[138:141], v[176:179], v[58:61]
	v_mfma_f32_16x16x32_bf16 v[46:49], v[130:133], v[184:187], v[46:49]
	v_mfma_f32_16x16x32_bf16 v[42:45], v[138:141], v[184:187], v[42:45]
	v_mfma_f32_16x16x32_bf16 v[30:33], v[130:133], v[214:217], v[30:33]
	v_mfma_f32_16x16x32_bf16 v[26:29], v[138:141], v[214:217], v[26:29]
	v_mfma_f32_16x16x32_bf16 v[14:17], v[130:133], v[222:225], v[14:17]
	v_mfma_f32_16x16x32_bf16 v[10:13], v[138:141], v[222:225], v[10:13]
	v_mfma_f32_16x16x32_bf16 v[62:65], v[134:137], v[180:183], v[62:65]
	v_mfma_f32_16x16x32_bf16 v[58:61], v[142:145], v[180:183], v[58:61]
	v_mfma_f32_16x16x32_bf16 v[46:49], v[134:137], v[188:191], v[46:49]
	v_mfma_f32_16x16x32_bf16 v[42:45], v[142:145], v[188:191], v[42:45]
	v_mfma_f32_16x16x32_bf16 v[30:33], v[134:137], v[218:221], v[30:33]
	v_mfma_f32_16x16x32_bf16 v[26:29], v[142:145], v[218:221], v[26:29]
	v_mfma_f32_16x16x32_bf16 v[14:17], v[134:137], v[240:243], v[14:17]
	v_mfma_f32_16x16x32_bf16 v[10:13], v[142:145], v[240:243], v[10:13]
	v_mfma_f32_16x16x32_bf16 v[54:57], v[146:149], v[176:179], v[54:57]
	v_mfma_f32_16x16x32_bf16 v[50:53], v[154:157], v[176:179], v[50:53]
	v_mfma_f32_16x16x32_bf16 v[38:41], v[146:149], v[184:187], v[38:41]
	v_mfma_f32_16x16x32_bf16 v[34:37], v[154:157], v[184:187], v[34:37]
	v_mfma_f32_16x16x32_bf16 v[22:25], v[146:149], v[214:217], v[22:25]
	v_mfma_f32_16x16x32_bf16 v[18:21], v[154:157], v[214:217], v[18:21]
	v_mfma_f32_16x16x32_bf16 v[6:9], v[146:149], v[222:225], v[6:9]
	v_mfma_f32_16x16x32_bf16 v[2:5], v[154:157], v[222:225], v[2:5]
	v_mfma_f32_16x16x32_bf16 v[54:57], v[150:153], v[180:183], v[54:57]
	v_mfma_f32_16x16x32_bf16 v[50:53], v[172:175], v[180:183], v[50:53]
	v_mfma_f32_16x16x32_bf16 v[38:41], v[150:153], v[188:191], v[38:41]
	v_mfma_f32_16x16x32_bf16 v[34:37], v[172:175], v[188:191], v[34:37]
	v_mfma_f32_16x16x32_bf16 v[22:25], v[150:153], v[218:221], v[22:25]
	v_mfma_f32_16x16x32_bf16 v[18:21], v[172:175], v[218:221], v[18:21]
	v_mfma_f32_16x16x32_bf16 v[6:9], v[150:153], v[240:243], v[6:9]
	v_mfma_f32_16x16x32_bf16 v[2:5], v[172:175], v[240:243], v[2:5]
	s_setprio 0
	s_barrier
	s_add_i32 s30, 0, 0x18000
	s_add_i32 s33, 0, 0x1c000
	v_add_u32_e32 v142, s30, v210
	v_add_u32_e32 v172, s33, v210
	ds_read_b128 v[130:133], v142
	ds_read_b128 v[134:137], v142 offset:1024
	ds_read_b128 v[138:141], v142 offset:2048
	ds_read_b128 v[142:145], v142 offset:3072
	ds_read_b128 v[146:149], v172
	ds_read_b128 v[150:153], v172 offset:1024
	ds_read_b128 v[154:157], v172 offset:2048
	ds_read_b128 v[172:175], v172 offset:3072
	s_add_u32 s16, s20, 0x88000
	s_addc_u32 s17, s21, 0
	s_mov_b32 m0, s29
	v_lshl_add_u64 v[202:203], s[16:17], 0, v[158:159]
	ds_read_b128 v[176:179], v212 offset:32768
	ds_read_b128 v[180:183], v212 offset:33792
	ds_read_b128 v[184:187], v212 offset:34816
	ds_read_b128 v[188:191], v212 offset:35840
	ds_read_b128 v[214:217], v212 offset:36864
	ds_read_b128 v[218:221], v212 offset:37888
	ds_read_b128 v[222:225], v212 offset:38912
	ds_read_b128 v[240:243], v212 offset:39936
	global_load_lds_dwordx4 v[202:203], off
	v_lshl_add_u64 v[202:203], s[16:17], 0, v[160:161]
	s_mov_b32 m0, s64
	s_nop 0
	global_load_lds_dwordx4 v[202:203], off
	s_waitcnt vmcnt(8)
	s_waitcnt lgkmcnt(0)
	s_barrier
	s_setprio 1
	v_mfma_f32_16x16x32_bf16 v[126:129], v[130:133], v[176:179], v[126:129]
	v_mfma_f32_16x16x32_bf16 v[122:125], v[138:141], v[176:179], v[122:125]
	v_mfma_f32_16x16x32_bf16 v[110:113], v[130:133], v[184:187], v[110:113]
	v_mfma_f32_16x16x32_bf16 v[106:109], v[138:141], v[184:187], v[106:109]
	v_mfma_f32_16x16x32_bf16 v[94:97], v[130:133], v[214:217], v[94:97]
	v_mfma_f32_16x16x32_bf16 v[90:93], v[138:141], v[214:217], v[90:93]
	v_mfma_f32_16x16x32_bf16 v[78:81], v[130:133], v[222:225], v[78:81]
	v_mfma_f32_16x16x32_bf16 v[74:77], v[138:141], v[222:225], v[74:77]
	v_mfma_f32_16x16x32_bf16 v[126:129], v[134:137], v[180:183], v[126:129]
	v_mfma_f32_16x16x32_bf16 v[122:125], v[142:145], v[180:183], v[122:125]
	v_mfma_f32_16x16x32_bf16 v[110:113], v[134:137], v[188:191], v[110:113]
	v_mfma_f32_16x16x32_bf16 v[106:109], v[142:145], v[188:191], v[106:109]
	v_mfma_f32_16x16x32_bf16 v[94:97], v[134:137], v[218:221], v[94:97]
	v_mfma_f32_16x16x32_bf16 v[90:93], v[142:145], v[218:221], v[90:93]
	v_mfma_f32_16x16x32_bf16 v[78:81], v[134:137], v[240:243], v[78:81]
	v_mfma_f32_16x16x32_bf16 v[74:77], v[142:145], v[240:243], v[74:77]
	v_mfma_f32_16x16x32_bf16 v[118:121], v[146:149], v[176:179], v[118:121]
	v_mfma_f32_16x16x32_bf16 v[114:117], v[154:157], v[176:179], v[114:117]
	v_mfma_f32_16x16x32_bf16 v[102:105], v[146:149], v[184:187], v[102:105]
	v_mfma_f32_16x16x32_bf16 v[98:101], v[154:157], v[184:187], v[98:101]
	v_mfma_f32_16x16x32_bf16 v[86:89], v[146:149], v[214:217], v[86:89]
	v_mfma_f32_16x16x32_bf16 v[82:85], v[154:157], v[214:217], v[82:85]
	v_mfma_f32_16x16x32_bf16 v[70:73], v[146:149], v[222:225], v[70:73]
	v_mfma_f32_16x16x32_bf16 v[66:69], v[154:157], v[222:225], v[66:69]
	v_mfma_f32_16x16x32_bf16 v[118:121], v[150:153], v[180:183], v[118:121]
	v_mfma_f32_16x16x32_bf16 v[114:117], v[172:175], v[180:183], v[114:117]
	v_mfma_f32_16x16x32_bf16 v[102:105], v[150:153], v[188:191], v[102:105]
	v_mfma_f32_16x16x32_bf16 v[98:101], v[172:175], v[188:191], v[98:101]
	v_mfma_f32_16x16x32_bf16 v[86:89], v[150:153], v[218:221], v[86:89]
	v_mfma_f32_16x16x32_bf16 v[82:85], v[172:175], v[218:221], v[82:85]
	v_mfma_f32_16x16x32_bf16 v[70:73], v[150:153], v[240:243], v[70:73]
	v_mfma_f32_16x16x32_bf16 v[66:69], v[172:175], v[240:243], v[66:69]
	s_setprio 0
	s_barrier
	s_add_i32 s16, s30, s26
	v_lshl_add_u64 v[194:195], v[194:195], 0, s[22:23]
	s_mov_b32 m0, s16
	ds_read_b128 v[176:179], v212 offset:49152
	ds_read_b128 v[180:183], v212 offset:50176
	ds_read_b128 v[184:187], v212 offset:51200
	ds_read_b128 v[188:191], v212 offset:52224
	ds_read_b128 v[214:217], v212 offset:53248
	ds_read_b128 v[218:221], v212 offset:54272
	ds_read_b128 v[222:225], v212 offset:55296
	ds_read_b128 v[240:243], v212 offset:56320
	global_load_lds_dwordx4 v[194:195], off
	s_add_i32 m0, s16, 0x2000
	s_add_u32 s16, s18, 0x88080
	v_lshl_add_u64 v[194:195], v[196:197], 0, s[22:23]
	s_addc_u32 s17, s19, 0
	s_add_i32 s18, s33, s26
	global_load_lds_dwordx4 v[194:195], off
	v_lshl_add_u64 v[194:195], s[16:17], 0, v[0:1]
	s_mov_b32 m0, s18
	s_nop 0
	global_load_lds_dwordx4 v[194:195], off
	v_lshl_add_u64 v[194:195], s[16:17], 0, v[162:163]
	s_add_i32 m0, s18, 0x2000
	s_nop 0
	global_load_lds_dwordx4 v[194:195], off
	v_lshl_add_u64 v[194:195], v[198:199], 0, s[22:23]
	s_mov_b32 m0, s73
	s_nop 0
	global_load_lds_dwordx4 v[194:195], off
	v_lshl_add_u64 v[194:195], v[200:201], 0, s[22:23]
	s_mov_b32 m0, s74
	s_nop 0
	global_load_lds_dwordx4 v[194:195], off
	s_waitcnt vmcnt(8)
	s_waitcnt lgkmcnt(0)
	s_barrier
	s_setprio 1
	v_mfma_f32_16x16x32_bf16 v[62:65], v[130:133], v[176:179], v[62:65]
	v_mfma_f32_16x16x32_bf16 v[58:61], v[138:141], v[176:179], v[58:61]
	v_mfma_f32_16x16x32_bf16 v[46:49], v[130:133], v[184:187], v[46:49]
	v_mfma_f32_16x16x32_bf16 v[42:45], v[138:141], v[184:187], v[42:45]
	v_mfma_f32_16x16x32_bf16 v[30:33], v[130:133], v[214:217], v[30:33]
	v_mfma_f32_16x16x32_bf16 v[26:29], v[138:141], v[214:217], v[26:29]
	v_mfma_f32_16x16x32_bf16 v[14:17], v[130:133], v[222:225], v[14:17]
	v_mfma_f32_16x16x32_bf16 v[10:13], v[138:141], v[222:225], v[10:13]
	v_mfma_f32_16x16x32_bf16 v[62:65], v[134:137], v[180:183], v[62:65]
	v_mfma_f32_16x16x32_bf16 v[58:61], v[142:145], v[180:183], v[58:61]
	v_mfma_f32_16x16x32_bf16 v[46:49], v[134:137], v[188:191], v[46:49]
	v_mfma_f32_16x16x32_bf16 v[42:45], v[142:145], v[188:191], v[42:45]
	v_mfma_f32_16x16x32_bf16 v[30:33], v[134:137], v[218:221], v[30:33]
	v_mfma_f32_16x16x32_bf16 v[26:29], v[142:145], v[218:221], v[26:29]
	v_mfma_f32_16x16x32_bf16 v[14:17], v[134:137], v[240:243], v[14:17]
	v_mfma_f32_16x16x32_bf16 v[10:13], v[142:145], v[240:243], v[10:13]
	v_mfma_f32_16x16x32_bf16 v[54:57], v[146:149], v[176:179], v[54:57]
	v_mfma_f32_16x16x32_bf16 v[50:53], v[154:157], v[176:179], v[50:53]
	v_mfma_f32_16x16x32_bf16 v[38:41], v[146:149], v[184:187], v[38:41]
	v_mfma_f32_16x16x32_bf16 v[34:37], v[154:157], v[184:187], v[34:37]
	v_mfma_f32_16x16x32_bf16 v[22:25], v[146:149], v[214:217], v[22:25]
	v_mfma_f32_16x16x32_bf16 v[18:21], v[154:157], v[214:217], v[18:21]
	v_mfma_f32_16x16x32_bf16 v[6:9], v[146:149], v[222:225], v[6:9]
	v_mfma_f32_16x16x32_bf16 v[2:5], v[154:157], v[222:225], v[2:5]
	v_mfma_f32_16x16x32_bf16 v[54:57], v[150:153], v[180:183], v[54:57]
	v_mfma_f32_16x16x32_bf16 v[50:53], v[172:175], v[180:183], v[50:53]
	v_mfma_f32_16x16x32_bf16 v[38:41], v[150:153], v[188:191], v[38:41]
	v_mfma_f32_16x16x32_bf16 v[34:37], v[172:175], v[188:191], v[34:37]
	v_mfma_f32_16x16x32_bf16 v[22:25], v[150:153], v[218:221], v[22:25]
	v_mfma_f32_16x16x32_bf16 v[18:21], v[172:175], v[218:221], v[18:21]
	v_mfma_f32_16x16x32_bf16 v[6:9], v[150:153], v[240:243], v[6:9]
	v_mfma_f32_16x16x32_bf16 v[2:5], v[172:175], v[240:243], v[2:5]
	s_setprio 0
	s_barrier
	s_add_i32 s25, s25, 2
	s_add_u32 s2, s2, 0x100
	s_addc_u32 s3, s3, 0
	s_cmp_gt_u32 s25, 29
	s_mov_b64 s[16:17], s[0:1]
	s_cbranch_scc0 .LBB0_137
	s_and_b64 vcc, exec, s[52:53]
	s_cbranch_vccz .LBB0_140
	s_barrier

.LBB0_771:
	s_add_u32 s2, s10, 0x100
	s_addc_u32 s3, s11, 0
	s_mov_b32 s43, -2
	s_add_u32 s10, s8, 0x100
	s_addc_u32 s11, s9, 0
	s_add_i32 s44, 0, 0x10000
	s_cmp_eq_u32 s43, 4
	s_cselect_b32 s15, s1, s11
	s_cselect_b32 s14, s0, s10
	s_cselect_b32 s13, s7, s3
	s_cselect_b32 s12, s6, s2
	s_add_i32 s45, 0, 0x14000
	v_add_u32_e32 v156, s44, v145
	v_add_u32_e32 v172, s45, v145
	ds_read_b128 v[140:143], v156
	ds_read_b128 v[148:151], v156 offset:1024
	ds_read_b128 v[152:155], v156 offset:2048
	ds_read_b128 v[156:159], v156 offset:3072
	ds_read_b128 v[160:163], v172
	ds_read_b128 v[164:167], v172 offset:1024
	ds_read_b128 v[168:171], v172 offset:2048
	ds_read_b128 v[172:175], v172 offset:3072
	v_lshl_add_u64 v[192:193], s[8:9], 0, v[136:137]
	s_add_i32 m0, s24, 0xc000
	ds_read_b128 v[176:179], v147
	ds_read_b128 v[180:183], v147 offset:1024
	ds_read_b128 v[184:187], v147 offset:2048
	ds_read_b128 v[188:191], v147 offset:3072
	ds_read_b128 v[210:213], v147 offset:4096
	ds_read_b128 v[214:217], v147 offset:5120
	ds_read_b128 v[218:221], v147 offset:6144
	ds_read_b128 v[222:225], v147 offset:7168
	global_load_lds_dwordx4 v[192:193], off
	v_lshl_add_u64 v[192:193], s[8:9], 0, v[138:139]
	s_add_i32 m0, s24, 0xe000
	s_nop 0
	global_load_lds_dwordx4 v[192:193], off
	s_waitcnt vmcnt(8)
	s_waitcnt lgkmcnt(0)
	s_barrier
	s_setprio 1
	v_mfma_f32_16x16x32_bf16 v[126:129], v[140:143], v[176:179], 0
	v_mfma_f32_16x16x32_bf16 v[122:125], v[152:155], v[176:179], 0
	v_mfma_f32_16x16x32_bf16 v[118:121], v[140:143], v[184:187], 0
	v_mfma_f32_16x16x32_bf16 v[110:113], v[152:155], v[184:187], 0
	v_mfma_f32_16x16x32_bf16 v[102:105], v[140:143], v[210:213], 0
	v_mfma_f32_16x16x32_bf16 v[94:97], v[152:155], v[210:213], 0
	v_mfma_f32_16x16x32_bf16 v[86:89], v[140:143], v[218:221], 0
	v_mfma_f32_16x16x32_bf16 v[78:81], v[152:155], v[218:221], 0
	v_mfma_f32_16x16x32_bf16 v[126:129], v[148:151], v[180:183], v[126:129]
	v_mfma_f32_16x16x32_bf16 v[122:125], v[156:159], v[180:183], v[122:125]
	v_mfma_f32_16x16x32_bf16 v[118:121], v[148:151], v[188:191], v[118:121]
	v_mfma_f32_16x16x32_bf16 v[110:113], v[156:159], v[188:191], v[110:113]
	v_mfma_f32_16x16x32_bf16 v[102:105], v[148:151], v[214:217], v[102:105]
	v_mfma_f32_16x16x32_bf16 v[94:97], v[156:159], v[214:217], v[94:97]
	v_mfma_f32_16x16x32_bf16 v[86:89], v[148:151], v[222:225], v[86:89]
	v_mfma_f32_16x16x32_bf16 v[78:81], v[156:159], v[222:225], v[78:81]
	v_mfma_f32_16x16x32_bf16 v[114:117], v[160:163], v[176:179], 0
	v_mfma_f32_16x16x32_bf16 v[106:109], v[168:171], v[176:179], 0
	v_mfma_f32_16x16x32_bf16 v[98:101], v[160:163], v[184:187], 0
	v_mfma_f32_16x16x32_bf16 v[90:93], v[168:171], v[184:187], 0
	v_mfma_f32_16x16x32_bf16 v[82:85], v[160:163], v[210:213], 0
	v_mfma_f32_16x16x32_bf16 v[74:77], v[168:171], v[210:213], 0
	v_mfma_f32_16x16x32_bf16 v[70:73], v[160:163], v[218:221], 0
	v_mfma_f32_16x16x32_bf16 v[66:69], v[168:171], v[218:221], 0
	v_mfma_f32_16x16x32_bf16 v[114:117], v[164:167], v[180:183], v[114:117]
	v_mfma_f32_16x16x32_bf16 v[106:109], v[172:175], v[180:183], v[106:109]
	v_mfma_f32_16x16x32_bf16 v[98:101], v[164:167], v[188:191], v[98:101]
	v_mfma_f32_16x16x32_bf16 v[90:93], v[172:175], v[188:191], v[90:93]
	v_mfma_f32_16x16x32_bf16 v[82:85], v[164:167], v[214:217], v[82:85]
	v_mfma_f32_16x16x32_bf16 v[74:77], v[172:175], v[214:217], v[74:77]
	v_mfma_f32_16x16x32_bf16 v[70:73], v[164:167], v[222:225], v[70:73]
	v_mfma_f32_16x16x32_bf16 v[66:69], v[172:175], v[222:225], v[66:69]
	s_setprio 0
	s_barrier
	s_add_i32 s8, s44, s18
	v_lshl_add_u64 v[192:193], s[12:13], 0, v[0:1]
	s_mov_b32 m0, s8
	ds_read_b128 v[176:179], v147 offset:16384
	ds_read_b128 v[180:183], v147 offset:17408
	ds_read_b128 v[184:187], v147 offset:18432
	ds_read_b128 v[188:191], v147 offset:19456
	ds_read_b128 v[210:213], v147 offset:20480
	ds_read_b128 v[214:217], v147 offset:21504
	ds_read_b128 v[218:221], v147 offset:22528
	ds_read_b128 v[222:225], v147 offset:23552
	global_load_lds_dwordx4 v[192:193], off
	s_add_i32 m0, s8, 0x2000
	s_add_u32 s8, s12, 0x28000
	v_lshl_add_u64 v[194:195], s[12:13], 0, v[130:131]
	s_addc_u32 s9, s13, 0
	s_add_i32 s44, s45, s18
	global_load_lds_dwordx4 v[194:195], off
	v_lshl_add_u64 v[196:197], s[8:9], 0, v[0:1]
	s_mov_b32 m0, s44
	v_lshl_add_u64 v[198:199], s[14:15], 0, v[132:133]
	global_load_lds_dwordx4 v[196:197], off
	v_lshl_add_u64 v[196:197], s[8:9], 0, v[130:131]
	s_add_i32 m0, s44, 0x2000
	s_nop 0
	global_load_lds_dwordx4 v[196:197], off
	v_lshl_add_u64 v[196:197], s[14:15], 0, v[134:135]
	s_mov_b32 m0, s24
	s_nop 0
	global_load_lds_dwordx4 v[196:197], off
	s_mov_b32 m0, s26
	s_nop 0
	global_load_lds_dwordx4 v[198:199], off
	s_waitcnt vmcnt(8)
	s_waitcnt lgkmcnt(0)
	s_barrier
	s_setprio 1
	v_mfma_f32_16x16x32_bf16 v[62:65], v[140:143], v[176:179], 0
	v_mfma_f32_16x16x32_bf16 v[58:61], v[152:155], v[176:179], 0
	v_mfma_f32_16x16x32_bf16 v[54:57], v[140:143], v[184:187], 0
	v_mfma_f32_16x16x32_bf16 v[46:49], v[152:155], v[184:187], 0
	v_mfma_f32_16x16x32_bf16 v[38:41], v[140:143], v[210:213], 0
	v_mfma_f32_16x16x32_bf16 v[30:33], v[152:155], v[210:213], 0
	v_mfma_f32_16x16x32_bf16 v[22:25], v[140:143], v[218:221], 0
	v_mfma_f32_16x16x32_bf16 v[14:17], v[152:155], v[218:221], 0
	v_mfma_f32_16x16x32_bf16 v[62:65], v[148:151], v[180:183], v[62:65]
	v_mfma_f32_16x16x32_bf16 v[58:61], v[156:159], v[180:183], v[58:61]
	v_mfma_f32_16x16x32_bf16 v[54:57], v[148:151], v[188:191], v[54:57]
	v_mfma_f32_16x16x32_bf16 v[46:49], v[156:159], v[188:191], v[46:49]
	v_mfma_f32_16x16x32_bf16 v[38:41], v[148:151], v[214:217], v[38:41]
	v_mfma_f32_16x16x32_bf16 v[30:33], v[156:159], v[214:217], v[30:33]
	v_mfma_f32_16x16x32_bf16 v[22:25], v[148:151], v[222:225], v[22:25]
	v_mfma_f32_16x16x32_bf16 v[14:17], v[156:159], v[222:225], v[14:17]
	v_mfma_f32_16x16x32_bf16 v[50:53], v[160:163], v[176:179], 0
	v_mfma_f32_16x16x32_bf16 v[42:45], v[168:171], v[176:179], 0
	v_mfma_f32_16x16x32_bf16 v[34:37], v[160:163], v[184:187], 0
	v_mfma_f32_16x16x32_bf16 v[26:29], v[168:171], v[184:187], 0
	v_mfma_f32_16x16x32_bf16 v[18:21], v[160:163], v[210:213], 0
	v_mfma_f32_16x16x32_bf16 v[10:13], v[168:171], v[210:213], 0
	v_mfma_f32_16x16x32_bf16 v[6:9], v[160:163], v[218:221], 0
	v_mfma_f32_16x16x32_bf16 v[2:5], v[168:171], v[218:221], 0
	v_mfma_f32_16x16x32_bf16 v[50:53], v[164:167], v[180:183], v[50:53]
	v_mfma_f32_16x16x32_bf16 v[42:45], v[172:175], v[180:183], v[42:45]
	v_mfma_f32_16x16x32_bf16 v[34:37], v[164:167], v[188:191], v[34:37]
	v_mfma_f32_16x16x32_bf16 v[26:29], v[172:175], v[188:191], v[26:29]
	v_mfma_f32_16x16x32_bf16 v[18:21], v[164:167], v[214:217], v[18:21]
	v_mfma_f32_16x16x32_bf16 v[10:13], v[172:175], v[214:217], v[10:13]
	v_mfma_f32_16x16x32_bf16 v[6:9], v[164:167], v[222:225], v[6:9]
	v_mfma_f32_16x16x32_bf16 v[2:5], v[172:175], v[222:225], v[2:5]
	s_setprio 0
	s_barrier
	s_add_i32 s44, 0, 0x18000
	s_add_i32 s45, 0, 0x1c000
	v_add_u32_e32 v156, s44, v145
	v_add_u32_e32 v172, s45, v145
	ds_read_b128 v[140:143], v156
	ds_read_b128 v[148:151], v156 offset:1024
	ds_read_b128 v[152:155], v156 offset:2048
	ds_read_b128 v[156:159], v156 offset:3072
	ds_read_b128 v[160:163], v172
	ds_read_b128 v[164:167], v172 offset:1024
	ds_read_b128 v[168:171], v172 offset:2048
	ds_read_b128 v[172:175], v172 offset:3072
	s_add_u32 s8, s14, 0x28000
	s_addc_u32 s9, s15, 0
	s_mov_b32 m0, s27
	v_lshl_add_u64 v[200:201], s[8:9], 0, v[134:135]
	ds_read_b128 v[176:179], v147 offset:32768
	ds_read_b128 v[180:183], v147 offset:33792
	ds_read_b128 v[184:187], v147 offset:34816
	ds_read_b128 v[188:191], v147 offset:35840
	ds_read_b128 v[210:213], v147 offset:36864
	ds_read_b128 v[214:217], v147 offset:37888
	ds_read_b128 v[218:221], v147 offset:38912
	ds_read_b128 v[222:225], v147 offset:39936
	global_load_lds_dwordx4 v[200:201], off
	v_lshl_add_u64 v[200:201], s[8:9], 0, v[132:133]
	s_mov_b32 m0, s28
	s_nop 0
	global_load_lds_dwordx4 v[200:201], off
	s_waitcnt vmcnt(8)
	s_waitcnt lgkmcnt(0)
	s_barrier
	s_setprio 1
	v_mfma_f32_16x16x32_bf16 v[126:129], v[140:143], v[176:179], v[126:129]
	v_mfma_f32_16x16x32_bf16 v[122:125], v[152:155], v[176:179], v[122:125]
	v_mfma_f32_16x16x32_bf16 v[118:121], v[140:143], v[184:187], v[118:121]
	v_mfma_f32_16x16x32_bf16 v[110:113], v[152:155], v[184:187], v[110:113]
	v_mfma_f32_16x16x32_bf16 v[102:105], v[140:143], v[210:213], v[102:105]
	v_mfma_f32_16x16x32_bf16 v[94:97], v[152:155], v[210:213], v[94:97]
	v_mfma_f32_16x16x32_bf16 v[86:89], v[140:143], v[218:221], v[86:89]
	v_mfma_f32_16x16x32_bf16 v[78:81], v[152:155], v[218:221], v[78:81]
	v_mfma_f32_16x16x32_bf16 v[126:129], v[148:151], v[180:183], v[126:129]
	v_mfma_f32_16x16x32_bf16 v[122:125], v[156:159], v[180:183], v[122:125]
	v_mfma_f32_16x16x32_bf16 v[118:121], v[148:151], v[188:191], v[118:121]
	v_mfma_f32_16x16x32_bf16 v[110:113], v[156:159], v[188:191], v[110:113]
	v_mfma_f32_16x16x32_bf16 v[102:105], v[148:151], v[214:217], v[102:105]
	v_mfma_f32_16x16x32_bf16 v[94:97], v[156:159], v[214:217], v[94:97]
	v_mfma_f32_16x16x32_bf16 v[86:89], v[148:151], v[222:225], v[86:89]
	v_mfma_f32_16x16x32_bf16 v[78:81], v[156:159], v[222:225], v[78:81]
	v_mfma_f32_16x16x32_bf16 v[114:117], v[160:163], v[176:179], v[114:117]
	v_mfma_f32_16x16x32_bf16 v[106:109], v[168:171], v[176:179], v[106:109]
	v_mfma_f32_16x16x32_bf16 v[98:101], v[160:163], v[184:187], v[98:101]
	v_mfma_f32_16x16x32_bf16 v[90:93], v[168:171], v[184:187], v[90:93]
	v_mfma_f32_16x16x32_bf16 v[82:85], v[160:163], v[210:213], v[82:85]
	v_mfma_f32_16x16x32_bf16 v[74:77], v[168:171], v[210:213], v[74:77]
	v_mfma_f32_16x16x32_bf16 v[70:73], v[160:163], v[218:221], v[70:73]
	v_mfma_f32_16x16x32_bf16 v[66:69], v[168:171], v[218:221], v[66:69]
	v_mfma_f32_16x16x32_bf16 v[114:117], v[164:167], v[180:183], v[114:117]
	v_mfma_f32_16x16x32_bf16 v[106:109], v[172:175], v[180:183], v[106:109]
	v_mfma_f32_16x16x32_bf16 v[98:101], v[164:167], v[188:191], v[98:101]
	v_mfma_f32_16x16x32_bf16 v[90:93], v[172:175], v[188:191], v[90:93]
	v_mfma_f32_16x16x32_bf16 v[82:85], v[164:167], v[214:217], v[82:85]
	v_mfma_f32_16x16x32_bf16 v[74:77], v[172:175], v[214:217], v[74:77]
	v_mfma_f32_16x16x32_bf16 v[70:73], v[164:167], v[222:225], v[70:73]
	v_mfma_f32_16x16x32_bf16 v[66:69], v[172:175], v[222:225], v[66:69]
	s_setprio 0
	s_barrier
	s_add_i32 s8, s44, s18
	v_lshl_add_u64 v[192:193], v[192:193], 0, s[22:23]
	s_mov_b32 m0, s8
	ds_read_b128 v[176:179], v147 offset:49152
	ds_read_b128 v[180:183], v147 offset:50176
	ds_read_b128 v[184:187], v147 offset:51200
	ds_read_b128 v[188:191], v147 offset:52224
	ds_read_b128 v[210:213], v147 offset:53248
	ds_read_b128 v[214:217], v147 offset:54272
	ds_read_b128 v[218:221], v147 offset:55296
	ds_read_b128 v[222:225], v147 offset:56320
	global_load_lds_dwordx4 v[192:193], off
	s_add_i32 m0, s8, 0x2000
	s_add_u32 s8, s12, 0x28080
	v_lshl_add_u64 v[192:193], v[194:195], 0, s[22:23]
	s_addc_u32 s9, s13, 0
	s_add_i32 s12, s45, s18
	global_load_lds_dwordx4 v[192:193], off
	v_lshl_add_u64 v[192:193], s[8:9], 0, v[0:1]
	s_mov_b32 m0, s12
	s_nop 0
	global_load_lds_dwordx4 v[192:193], off
	v_lshl_add_u64 v[192:193], s[8:9], 0, v[130:131]
	s_add_i32 m0, s12, 0x2000
	s_nop 0
	global_load_lds_dwordx4 v[192:193], off
	v_lshl_add_u64 v[192:193], v[196:197], 0, s[22:23]
	s_mov_b32 m0, s29
	s_nop 0
	global_load_lds_dwordx4 v[192:193], off
	v_lshl_add_u64 v[192:193], v[198:199], 0, s[22:23]
	s_mov_b32 m0, s33
	s_nop 0
	global_load_lds_dwordx4 v[192:193], off
	s_waitcnt vmcnt(8)
	s_waitcnt lgkmcnt(0)
	s_barrier
	s_setprio 1
	v_mfma_f32_16x16x32_bf16 v[62:65], v[140:143], v[176:179], v[62:65]
	v_mfma_f32_16x16x32_bf16 v[58:61], v[152:155], v[176:179], v[58:61]
	v_mfma_f32_16x16x32_bf16 v[54:57], v[140:143], v[184:187], v[54:57]
	v_mfma_f32_16x16x32_bf16 v[46:49], v[152:155], v[184:187], v[46:49]
	v_mfma_f32_16x16x32_bf16 v[38:41], v[140:143], v[210:213], v[38:41]
	v_mfma_f32_16x16x32_bf16 v[30:33], v[152:155], v[210:213], v[30:33]
	v_mfma_f32_16x16x32_bf16 v[22:25], v[140:143], v[218:221], v[22:25]
	v_mfma_f32_16x16x32_bf16 v[14:17], v[152:155], v[218:221], v[14:17]
	v_mfma_f32_16x16x32_bf16 v[62:65], v[148:151], v[180:183], v[62:65]
	v_mfma_f32_16x16x32_bf16 v[58:61], v[156:159], v[180:183], v[58:61]
	v_mfma_f32_16x16x32_bf16 v[54:57], v[148:151], v[188:191], v[54:57]
	v_mfma_f32_16x16x32_bf16 v[46:49], v[156:159], v[188:191], v[46:49]
	v_mfma_f32_16x16x32_bf16 v[38:41], v[148:151], v[214:217], v[38:41]
	v_mfma_f32_16x16x32_bf16 v[30:33], v[156:159], v[214:217], v[30:33]
	v_mfma_f32_16x16x32_bf16 v[22:25], v[148:151], v[222:225], v[22:25]
	v_mfma_f32_16x16x32_bf16 v[14:17], v[156:159], v[222:225], v[14:17]
	v_mfma_f32_16x16x32_bf16 v[50:53], v[160:163], v[176:179], v[50:53]
	v_mfma_f32_16x16x32_bf16 v[42:45], v[168:171], v[176:179], v[42:45]
	v_mfma_f32_16x16x32_bf16 v[34:37], v[160:163], v[184:187], v[34:37]
	v_mfma_f32_16x16x32_bf16 v[26:29], v[168:171], v[184:187], v[26:29]
	v_mfma_f32_16x16x32_bf16 v[18:21], v[160:163], v[210:213], v[18:21]
	v_mfma_f32_16x16x32_bf16 v[10:13], v[168:171], v[210:213], v[10:13]
	v_mfma_f32_16x16x32_bf16 v[6:9], v[160:163], v[218:221], v[6:9]
	v_mfma_f32_16x16x32_bf16 v[2:5], v[168:171], v[218:221], v[2:5]
	v_mfma_f32_16x16x32_bf16 v[50:53], v[164:167], v[180:183], v[50:53]
	v_mfma_f32_16x16x32_bf16 v[42:45], v[172:175], v[180:183], v[42:45]
	v_mfma_f32_16x16x32_bf16 v[34:37], v[164:167], v[188:191], v[34:37]
	v_mfma_f32_16x16x32_bf16 v[26:29], v[172:175], v[188:191], v[26:29]
	v_mfma_f32_16x16x32_bf16 v[18:21], v[164:167], v[214:217], v[18:21]
	v_mfma_f32_16x16x32_bf16 v[10:13], v[172:175], v[214:217], v[10:13]
	v_mfma_f32_16x16x32_bf16 v[6:9], v[164:167], v[222:225], v[6:9]
	v_mfma_f32_16x16x32_bf16 v[2:5], v[172:175], v[222:225], v[2:5]
	s_setprio 0
	s_barrier
	s_add_i32 s43, s43, 2
	s_add_u32 s2, s2, 0x100
	s_addc_u32 s3, s3, 0
	s_cmp_gt_u32 s43, 5
	s_mov_b64 s[8:9], s[10:11]
.LBB0_772:
	s_add_u32 s10, s8, 0x100
	s_addc_u32 s11, s9, 0
	s_add_i32 s44, 0, 0x10000
	s_cmp_eq_u32 s43, 4
	s_cselect_b32 s15, s1, s11
	s_cselect_b32 s14, s0, s10
	s_cselect_b32 s13, s7, s3
	s_cselect_b32 s12, s6, s2
	s_add_i32 s45, 0, 0x14000
	v_add_u32_e32 v156, s44, v145
	v_add_u32_e32 v172, s45, v145
	ds_read_b128 v[140:143], v156
	ds_read_b128 v[148:151], v156 offset:1024
	ds_read_b128 v[152:155], v156 offset:2048
	ds_read_b128 v[156:159], v156 offset:3072
	ds_read_b128 v[160:163], v172
	ds_read_b128 v[164:167], v172 offset:1024
	ds_read_b128 v[168:171], v172 offset:2048
	ds_read_b128 v[172:175], v172 offset:3072
	v_lshl_add_u64 v[192:193], s[8:9], 0, v[136:137]
	s_add_i32 m0, s24, 0xc000
	ds_read_b128 v[176:179], v147
	ds_read_b128 v[180:183], v147 offset:1024
	ds_read_b128 v[184:187], v147 offset:2048
	ds_read_b128 v[188:191], v147 offset:3072
	ds_read_b128 v[210:213], v147 offset:4096
	ds_read_b128 v[214:217], v147 offset:5120
	ds_read_b128 v[218:221], v147 offset:6144
	ds_read_b128 v[222:225], v147 offset:7168
	global_load_lds_dwordx4 v[192:193], off
	v_lshl_add_u64 v[192:193], s[8:9], 0, v[138:139]
	s_add_i32 m0, s24, 0xe000
	s_nop 0
	global_load_lds_dwordx4 v[192:193], off
	s_waitcnt vmcnt(8)
	s_waitcnt lgkmcnt(0)
	s_barrier
	s_setprio 1
	v_mfma_f32_16x16x32_bf16 v[126:129], v[140:143], v[176:179], v[126:129]
	v_mfma_f32_16x16x32_bf16 v[122:125], v[152:155], v[176:179], v[122:125]
	v_mfma_f32_16x16x32_bf16 v[118:121], v[140:143], v[184:187], v[118:121]
	v_mfma_f32_16x16x32_bf16 v[110:113], v[152:155], v[184:187], v[110:113]
	v_mfma_f32_16x16x32_bf16 v[102:105], v[140:143], v[210:213], v[102:105]
	v_mfma_f32_16x16x32_bf16 v[94:97], v[152:155], v[210:213], v[94:97]
	v_mfma_f32_16x16x32_bf16 v[86:89], v[140:143], v[218:221], v[86:89]
	v_mfma_f32_16x16x32_bf16 v[78:81], v[152:155], v[218:221], v[78:81]
	v_mfma_f32_16x16x32_bf16 v[126:129], v[148:151], v[180:183], v[126:129]
	v_mfma_f32_16x16x32_bf16 v[122:125], v[156:159], v[180:183], v[122:125]
	v_mfma_f32_16x16x32_bf16 v[118:121], v[148:151], v[188:191], v[118:121]
	v_mfma_f32_16x16x32_bf16 v[110:113], v[156:159], v[188:191], v[110:113]
	v_mfma_f32_16x16x32_bf16 v[102:105], v[148:151], v[214:217], v[102:105]
	v_mfma_f32_16x16x32_bf16 v[94:97], v[156:159], v[214:217], v[94:97]
	v_mfma_f32_16x16x32_bf16 v[86:89], v[148:151], v[222:225], v[86:89]
	v_mfma_f32_16x16x32_bf16 v[78:81], v[156:159], v[222:225], v[78:81]
	v_mfma_f32_16x16x32_bf16 v[114:117], v[160:163], v[176:179], v[114:117]
	v_mfma_f32_16x16x32_bf16 v[106:109], v[168:171], v[176:179], v[106:109]
	v_mfma_f32_16x16x32_bf16 v[98:101], v[160:163], v[184:187], v[98:101]
	v_mfma_f32_16x16x32_bf16 v[90:93], v[168:171], v[184:187], v[90:93]
	v_mfma_f32_16x16x32_bf16 v[82:85], v[160:163], v[210:213], v[82:85]
	v_mfma_f32_16x16x32_bf16 v[74:77], v[168:171], v[210:213], v[74:77]
	v_mfma_f32_16x16x32_bf16 v[70:73], v[160:163], v[218:221], v[70:73]
	v_mfma_f32_16x16x32_bf16 v[66:69], v[168:171], v[218:221], v[66:69]
	v_mfma_f32_16x16x32_bf16 v[114:117], v[164:167], v[180:183], v[114:117]
	v_mfma_f32_16x16x32_bf16 v[106:109], v[172:175], v[180:183], v[106:109]
	v_mfma_f32_16x16x32_bf16 v[98:101], v[164:167], v[188:191], v[98:101]
	v_mfma_f32_16x16x32_bf16 v[90:93], v[172:175], v[188:191], v[90:93]
	v_mfma_f32_16x16x32_bf16 v[82:85], v[164:167], v[214:217], v[82:85]
	v_mfma_f32_16x16x32_bf16 v[74:77], v[172:175], v[214:217], v[74:77]
	v_mfma_f32_16x16x32_bf16 v[70:73], v[164:167], v[222:225], v[70:73]
	v_mfma_f32_16x16x32_bf16 v[66:69], v[172:175], v[222:225], v[66:69]
	s_setprio 0
	s_barrier
	s_add_i32 s8, s44, s18
	v_lshl_add_u64 v[192:193], s[12:13], 0, v[0:1]
	s_mov_b32 m0, s8
	ds_read_b128 v[176:179], v147 offset:16384
	ds_read_b128 v[180:183], v147 offset:17408
	ds_read_b128 v[184:187], v147 offset:18432
	ds_read_b128 v[188:191], v147 offset:19456
	ds_read_b128 v[210:213], v147 offset:20480
	ds_read_b128 v[214:217], v147 offset:21504
	ds_read_b128 v[218:221], v147 offset:22528
	ds_read_b128 v[222:225], v147 offset:23552
	global_load_lds_dwordx4 v[192:193], off
	s_add_i32 m0, s8, 0x2000
	s_add_u32 s8, s12, 0x28000
	v_lshl_add_u64 v[194:195], s[12:13], 0, v[130:131]
	s_addc_u32 s9, s13, 0
	s_add_i32 s44, s45, s18
	global_load_lds_dwordx4 v[194:195], off
	v_lshl_add_u64 v[196:197], s[8:9], 0, v[0:1]
	s_mov_b32 m0, s44
	v_lshl_add_u64 v[198:199], s[14:15], 0, v[132:133]
	global_load_lds_dwordx4 v[196:197], off
	v_lshl_add_u64 v[196:197], s[8:9], 0, v[130:131]
	s_add_i32 m0, s44, 0x2000
	s_nop 0
	global_load_lds_dwordx4 v[196:197], off
	v_lshl_add_u64 v[196:197], s[14:15], 0, v[134:135]
	s_mov_b32 m0, s24
	s_nop 0
	global_load_lds_dwordx4 v[196:197], off
	s_mov_b32 m0, s26
	s_nop 0
	global_load_lds_dwordx4 v[198:199], off
	s_waitcnt vmcnt(8)
	s_waitcnt lgkmcnt(0)
	s_barrier
	s_setprio 1
	v_mfma_f32_16x16x32_bf16 v[62:65], v[140:143], v[176:179], v[62:65]
	v_mfma_f32_16x16x32_bf16 v[58:61], v[152:155], v[176:179], v[58:61]
	v_mfma_f32_16x16x32_bf16 v[54:57], v[140:143], v[184:187], v[54:57]
	v_mfma_f32_16x16x32_bf16 v[46:49], v[152:155], v[184:187], v[46:49]
	v_mfma_f32_16x16x32_bf16 v[38:41], v[140:143], v[210:213], v[38:41]
	v_mfma_f32_16x16x32_bf16 v[30:33], v[152:155], v[210:213], v[30:33]
	v_mfma_f32_16x16x32_bf16 v[22:25], v[140:143], v[218:221], v[22:25]
	v_mfma_f32_16x16x32_bf16 v[14:17], v[152:155], v[218:221], v[14:17]
	v_mfma_f32_16x16x32_bf16 v[62:65], v[148:151], v[180:183], v[62:65]
	v_mfma_f32_16x16x32_bf16 v[58:61], v[156:159], v[180:183], v[58:61]
	v_mfma_f32_16x16x32_bf16 v[54:57], v[148:151], v[188:191], v[54:57]
	v_mfma_f32_16x16x32_bf16 v[46:49], v[156:159], v[188:191], v[46:49]
	v_mfma_f32_16x16x32_bf16 v[38:41], v[148:151], v[214:217], v[38:41]
	v_mfma_f32_16x16x32_bf16 v[30:33], v[156:159], v[214:217], v[30:33]
	v_mfma_f32_16x16x32_bf16 v[22:25], v[148:151], v[222:225], v[22:25]
	v_mfma_f32_16x16x32_bf16 v[14:17], v[156:159], v[222:225], v[14:17]
	v_mfma_f32_16x16x32_bf16 v[50:53], v[160:163], v[176:179], v[50:53]
	v_mfma_f32_16x16x32_bf16 v[42:45], v[168:171], v[176:179], v[42:45]
	v_mfma_f32_16x16x32_bf16 v[34:37], v[160:163], v[184:187], v[34:37]
	v_mfma_f32_16x16x32_bf16 v[26:29], v[168:171], v[184:187], v[26:29]
	v_mfma_f32_16x16x32_bf16 v[18:21], v[160:163], v[210:213], v[18:21]
	v_mfma_f32_16x16x32_bf16 v[10:13], v[168:171], v[210:213], v[10:13]
	v_mfma_f32_16x16x32_bf16 v[6:9], v[160:163], v[218:221], v[6:9]
	v_mfma_f32_16x16x32_bf16 v[2:5], v[168:171], v[218:221], v[2:5]
	v_mfma_f32_16x16x32_bf16 v[50:53], v[164:167], v[180:183], v[50:53]
	v_mfma_f32_16x16x32_bf16 v[42:45], v[172:175], v[180:183], v[42:45]
	v_mfma_f32_16x16x32_bf16 v[34:37], v[164:167], v[188:191], v[34:37]
	v_mfma_f32_16x16x32_bf16 v[26:29], v[172:175], v[188:191], v[26:29]
	v_mfma_f32_16x16x32_bf16 v[18:21], v[164:167], v[214:217], v[18:21]
	v_mfma_f32_16x16x32_bf16 v[10:13], v[172:175], v[214:217], v[10:13]
	v_mfma_f32_16x16x32_bf16 v[6:9], v[164:167], v[222:225], v[6:9]
	v_mfma_f32_16x16x32_bf16 v[2:5], v[172:175], v[222:225], v[2:5]
	s_setprio 0
	s_barrier
	s_add_i32 s44, 0, 0x18000
	s_add_i32 s45, 0, 0x1c000
	v_add_u32_e32 v156, s44, v145
	v_add_u32_e32 v172, s45, v145
	ds_read_b128 v[140:143], v156
	ds_read_b128 v[148:151], v156 offset:1024
	ds_read_b128 v[152:155], v156 offset:2048
	ds_read_b128 v[156:159], v156 offset:3072
	ds_read_b128 v[160:163], v172
	ds_read_b128 v[164:167], v172 offset:1024
	ds_read_b128 v[168:171], v172 offset:2048
	ds_read_b128 v[172:175], v172 offset:3072
	s_add_u32 s8, s14, 0x28000
	s_addc_u32 s9, s15, 0
	s_mov_b32 m0, s27
	v_lshl_add_u64 v[200:201], s[8:9], 0, v[134:135]
	ds_read_b128 v[176:179], v147 offset:32768
	ds_read_b128 v[180:183], v147 offset:33792
	ds_read_b128 v[184:187], v147 offset:34816
	ds_read_b128 v[188:191], v147 offset:35840
	ds_read_b128 v[210:213], v147 offset:36864
	ds_read_b128 v[214:217], v147 offset:37888
	ds_read_b128 v[218:221], v147 offset:38912
	ds_read_b128 v[222:225], v147 offset:39936
	global_load_lds_dwordx4 v[200:201], off
	v_lshl_add_u64 v[200:201], s[8:9], 0, v[132:133]
	s_mov_b32 m0, s28
	s_nop 0
	global_load_lds_dwordx4 v[200:201], off
	s_waitcnt vmcnt(8)
	s_waitcnt lgkmcnt(0)
	s_barrier
	s_setprio 1
	v_mfma_f32_16x16x32_bf16 v[126:129], v[140:143], v[176:179], v[126:129]
	v_mfma_f32_16x16x32_bf16 v[122:125], v[152:155], v[176:179], v[122:125]
	v_mfma_f32_16x16x32_bf16 v[118:121], v[140:143], v[184:187], v[118:121]
	v_mfma_f32_16x16x32_bf16 v[110:113], v[152:155], v[184:187], v[110:113]
	v_mfma_f32_16x16x32_bf16 v[102:105], v[140:143], v[210:213], v[102:105]
	v_mfma_f32_16x16x32_bf16 v[94:97], v[152:155], v[210:213], v[94:97]
	v_mfma_f32_16x16x32_bf16 v[86:89], v[140:143], v[218:221], v[86:89]
	v_mfma_f32_16x16x32_bf16 v[78:81], v[152:155], v[218:221], v[78:81]
	v_mfma_f32_16x16x32_bf16 v[126:129], v[148:151], v[180:183], v[126:129]
	v_mfma_f32_16x16x32_bf16 v[122:125], v[156:159], v[180:183], v[122:125]
	v_mfma_f32_16x16x32_bf16 v[118:121], v[148:151], v[188:191], v[118:121]
	v_mfma_f32_16x16x32_bf16 v[110:113], v[156:159], v[188:191], v[110:113]
	v_mfma_f32_16x16x32_bf16 v[102:105], v[148:151], v[214:217], v[102:105]
	v_mfma_f32_16x16x32_bf16 v[94:97], v[156:159], v[214:217], v[94:97]
	v_mfma_f32_16x16x32_bf16 v[86:89], v[148:151], v[222:225], v[86:89]
	v_mfma_f32_16x16x32_bf16 v[78:81], v[156:159], v[222:225], v[78:81]
	v_mfma_f32_16x16x32_bf16 v[114:117], v[160:163], v[176:179], v[114:117]
	v_mfma_f32_16x16x32_bf16 v[106:109], v[168:171], v[176:179], v[106:109]
	v_mfma_f32_16x16x32_bf16 v[98:101], v[160:163], v[184:187], v[98:101]
	v_mfma_f32_16x16x32_bf16 v[90:93], v[168:171], v[184:187], v[90:93]
	v_mfma_f32_16x16x32_bf16 v[82:85], v[160:163], v[210:213], v[82:85]
	v_mfma_f32_16x16x32_bf16 v[74:77], v[168:171], v[210:213], v[74:77]
	v_mfma_f32_16x16x32_bf16 v[70:73], v[160:163], v[218:221], v[70:73]
	v_mfma_f32_16x16x32_bf16 v[66:69], v[168:171], v[218:221], v[66:69]
	v_mfma_f32_16x16x32_bf16 v[114:117], v[164:167], v[180:183], v[114:117]
	v_mfma_f32_16x16x32_bf16 v[106:109], v[172:175], v[180:183], v[106:109]
	v_mfma_f32_16x16x32_bf16 v[98:101], v[164:167], v[188:191], v[98:101]
	v_mfma_f32_16x16x32_bf16 v[90:93], v[172:175], v[188:191], v[90:93]
	v_mfma_f32_16x16x32_bf16 v[82:85], v[164:167], v[214:217], v[82:85]
	v_mfma_f32_16x16x32_bf16 v[74:77], v[172:175], v[214:217], v[74:77]
	v_mfma_f32_16x16x32_bf16 v[70:73], v[164:167], v[222:225], v[70:73]
	v_mfma_f32_16x16x32_bf16 v[66:69], v[172:175], v[222:225], v[66:69]
	s_setprio 0
	s_barrier
	s_add_i32 s8, s44, s18
	v_lshl_add_u64 v[192:193], v[192:193], 0, s[22:23]
	s_mov_b32 m0, s8
	ds_read_b128 v[176:179], v147 offset:49152
	ds_read_b128 v[180:183], v147 offset:50176
	ds_read_b128 v[184:187], v147 offset:51200
	ds_read_b128 v[188:191], v147 offset:52224
	ds_read_b128 v[210:213], v147 offset:53248
	ds_read_b128 v[214:217], v147 offset:54272
	ds_read_b128 v[218:221], v147 offset:55296
	ds_read_b128 v[222:225], v147 offset:56320
	global_load_lds_dwordx4 v[192:193], off
	s_add_i32 m0, s8, 0x2000
	s_add_u32 s8, s12, 0x28080
	v_lshl_add_u64 v[192:193], v[194:195], 0, s[22:23]
	s_addc_u32 s9, s13, 0
	s_add_i32 s12, s45, s18
	global_load_lds_dwordx4 v[192:193], off
	v_lshl_add_u64 v[192:193], s[8:9], 0, v[0:1]
	s_mov_b32 m0, s12
	s_nop 0
	global_load_lds_dwordx4 v[192:193], off
	v_lshl_add_u64 v[192:193], s[8:9], 0, v[130:131]
	s_add_i32 m0, s12, 0x2000
	s_nop 0
	global_load_lds_dwordx4 v[192:193], off
	v_lshl_add_u64 v[192:193], v[196:197], 0, s[22:23]
	s_mov_b32 m0, s29
	s_nop 0
	global_load_lds_dwordx4 v[192:193], off
	v_lshl_add_u64 v[192:193], v[198:199], 0, s[22:23]
	s_mov_b32 m0, s33
	s_nop 0
	global_load_lds_dwordx4 v[192:193], off
	s_waitcnt vmcnt(8)
	s_waitcnt lgkmcnt(0)
	s_barrier
	s_setprio 1
	v_mfma_f32_16x16x32_bf16 v[62:65], v[140:143], v[176:179], v[62:65]
	v_mfma_f32_16x16x32_bf16 v[58:61], v[152:155], v[176:179], v[58:61]
	v_mfma_f32_16x16x32_bf16 v[54:57], v[140:143], v[184:187], v[54:57]
	v_mfma_f32_16x16x32_bf16 v[46:49], v[152:155], v[184:187], v[46:49]
	v_mfma_f32_16x16x32_bf16 v[38:41], v[140:143], v[210:213], v[38:41]
	v_mfma_f32_16x16x32_bf16 v[30:33], v[152:155], v[210:213], v[30:33]
	v_mfma_f32_16x16x32_bf16 v[22:25], v[140:143], v[218:221], v[22:25]
	v_mfma_f32_16x16x32_bf16 v[14:17], v[152:155], v[218:221], v[14:17]
	v_mfma_f32_16x16x32_bf16 v[62:65], v[148:151], v[180:183], v[62:65]
	v_mfma_f32_16x16x32_bf16 v[58:61], v[156:159], v[180:183], v[58:61]
	v_mfma_f32_16x16x32_bf16 v[54:57], v[148:151], v[188:191], v[54:57]
	v_mfma_f32_16x16x32_bf16 v[46:49], v[156:159], v[188:191], v[46:49]
	v_mfma_f32_16x16x32_bf16 v[38:41], v[148:151], v[214:217], v[38:41]
	v_mfma_f32_16x16x32_bf16 v[30:33], v[156:159], v[214:217], v[30:33]
	v_mfma_f32_16x16x32_bf16 v[22:25], v[148:151], v[222:225], v[22:25]
	v_mfma_f32_16x16x32_bf16 v[14:17], v[156:159], v[222:225], v[14:17]
	v_mfma_f32_16x16x32_bf16 v[50:53], v[160:163], v[176:179], v[50:53]
	v_mfma_f32_16x16x32_bf16 v[42:45], v[168:171], v[176:179], v[42:45]
	v_mfma_f32_16x16x32_bf16 v[34:37], v[160:163], v[184:187], v[34:37]
	v_mfma_f32_16x16x32_bf16 v[26:29], v[168:171], v[184:187], v[26:29]
	v_mfma_f32_16x16x32_bf16 v[18:21], v[160:163], v[210:213], v[18:21]
	v_mfma_f32_16x16x32_bf16 v[10:13], v[168:171], v[210:213], v[10:13]
	v_mfma_f32_16x16x32_bf16 v[6:9], v[160:163], v[218:221], v[6:9]
	v_mfma_f32_16x16x32_bf16 v[2:5], v[168:171], v[218:221], v[2:5]
	v_mfma_f32_16x16x32_bf16 v[50:53], v[164:167], v[180:183], v[50:53]
	v_mfma_f32_16x16x32_bf16 v[42:45], v[172:175], v[180:183], v[42:45]
	v_mfma_f32_16x16x32_bf16 v[34:37], v[164:167], v[188:191], v[34:37]
	v_mfma_f32_16x16x32_bf16 v[26:29], v[172:175], v[188:191], v[26:29]
	v_mfma_f32_16x16x32_bf16 v[18:21], v[164:167], v[214:217], v[18:21]
	v_mfma_f32_16x16x32_bf16 v[10:13], v[172:175], v[214:217], v[10:13]
	v_mfma_f32_16x16x32_bf16 v[6:9], v[164:167], v[222:225], v[6:9]
	v_mfma_f32_16x16x32_bf16 v[2:5], v[172:175], v[222:225], v[2:5]
	s_setprio 0
	s_barrier
	s_add_i32 s43, s43, 2
	s_add_u32 s2, s2, 0x100
	s_addc_u32 s3, s3, 0
	s_cmp_gt_u32 s43, 5
	s_mov_b64 s[8:9], s[10:11]
	s_cbranch_scc0 .LBB0_772
	s_and_b64 vcc, exec, s[4:5]
	s_cbranch_vccz .LBB0_775
	s_barrier

.LBB0_797:
	s_add_i32 s44, 0, 0x10000
	s_add_i32 s2, 0, 0x14000
	v_add_u32_e32 v204, s44, v188
	v_add_u32_e32 v205, s2, v188
	ds_read_b128 v[2:5], v204
	ds_read_b128 v[6:9], v204 offset:1024
	ds_read_b128 v[10:13], v204 offset:2048
	ds_read_b128 v[14:17], v204 offset:3072
	ds_read_b128 v[18:21], v205
	ds_read_b128 v[22:25], v205 offset:1024
	ds_read_b128 v[26:29], v205 offset:2048
	ds_read_b128 v[30:33], v205 offset:3072
	s_add_u32 s0, s14, 0x18080
	s_addc_u32 s1, s15, 0
	s_add_i32 s46, s24, 0xc000
	v_lshl_add_u64 v[66:67], s[0:1], 0, v[150:151]
	s_mov_b32 m0, s46
	ds_read_b128 v[34:37], v189
	ds_read_b128 v[38:41], v189 offset:1024
	ds_read_b128 v[42:45], v189 offset:2048
	ds_read_b128 v[46:49], v189 offset:3072
	ds_read_b128 v[50:53], v189 offset:4096
	ds_read_b128 v[54:57], v189 offset:5120
	ds_read_b128 v[58:61], v189 offset:6144
	ds_read_b128 v[62:65], v189 offset:7168
	global_load_lds_dwordx4 v[66:67], off
	v_lshl_add_u64 v[66:67], s[0:1], 0, v[152:153]
	s_add_i32 s0, s24, 0xe000
	s_mov_b32 m0, s0
	s_nop 0
	global_load_lds_dwordx4 v[66:67], off
	s_waitcnt vmcnt(8)
	s_waitcnt lgkmcnt(0)
	s_barrier
	s_setprio 1
	v_mfma_f32_16x16x32_bf16 v[66:69], v[2:5], v[34:37], 0
	v_mfma_f32_16x16x32_bf16 v[70:73], v[10:13], v[34:37], 0
	v_mfma_f32_16x16x32_bf16 v[74:77], v[2:5], v[42:45], 0
	v_mfma_f32_16x16x32_bf16 v[78:81], v[10:13], v[42:45], 0
	v_mfma_f32_16x16x32_bf16 v[82:85], v[2:5], v[50:53], 0
	v_mfma_f32_16x16x32_bf16 v[86:89], v[10:13], v[50:53], 0
	v_mfma_f32_16x16x32_bf16 v[90:93], v[2:5], v[58:61], 0
	v_mfma_f32_16x16x32_bf16 v[94:97], v[10:13], v[58:61], 0
	v_mfma_f32_16x16x32_bf16 v[66:69], v[6:9], v[38:41], v[66:69]
	v_mfma_f32_16x16x32_bf16 v[70:73], v[14:17], v[38:41], v[70:73]
	v_mfma_f32_16x16x32_bf16 v[74:77], v[6:9], v[46:49], v[74:77]
	v_mfma_f32_16x16x32_bf16 v[78:81], v[14:17], v[46:49], v[78:81]
	v_mfma_f32_16x16x32_bf16 v[82:85], v[6:9], v[54:57], v[82:85]
	v_mfma_f32_16x16x32_bf16 v[86:89], v[14:17], v[54:57], v[86:89]
	v_mfma_f32_16x16x32_bf16 v[90:93], v[6:9], v[62:65], v[90:93]
	v_mfma_f32_16x16x32_bf16 v[94:97], v[14:17], v[62:65], v[94:97]
	v_mfma_f32_16x16x32_bf16 v[98:101], v[18:21], v[34:37], 0
	v_mfma_f32_16x16x32_bf16 v[34:37], v[26:29], v[34:37], 0
	v_mfma_f32_16x16x32_bf16 v[98:101], v[22:25], v[38:41], v[98:101]
	v_mfma_f32_16x16x32_bf16 v[34:37], v[30:33], v[38:41], v[34:37]
	v_mfma_f32_16x16x32_bf16 v[38:41], v[18:21], v[42:45], 0
	v_mfma_f32_16x16x32_bf16 v[42:45], v[26:29], v[42:45], 0
	v_mfma_f32_16x16x32_bf16 v[38:41], v[22:25], v[46:49], v[38:41]
	v_mfma_f32_16x16x32_bf16 v[42:45], v[30:33], v[46:49], v[42:45]
	v_mfma_f32_16x16x32_bf16 v[46:49], v[18:21], v[50:53], 0
	v_mfma_f32_16x16x32_bf16 v[50:53], v[26:29], v[50:53], 0
	v_mfma_f32_16x16x32_bf16 v[46:49], v[22:25], v[54:57], v[46:49]
	v_mfma_f32_16x16x32_bf16 v[50:53], v[30:33], v[54:57], v[50:53]
	v_mfma_f32_16x16x32_bf16 v[54:57], v[18:21], v[58:61], 0
	v_mfma_f32_16x16x32_bf16 v[58:61], v[26:29], v[58:61], 0
	v_mfma_f32_16x16x32_bf16 v[58:61], v[30:33], v[62:65], v[58:61]
	v_mfma_f32_16x16x32_bf16 v[54:57], v[22:25], v[62:65], v[54:57]
	s_setprio 0
	s_barrier
	s_add_i32 s44, s44, s18
	v_lshl_add_u64 v[194:195], s[16:17], 0, v[0:1]
	s_mov_b64 s[50:51], 0x100
	s_add_i32 s1, s44, 0x2000
	v_lshl_add_u64 v[130:131], v[194:195], 0, s[50:51]
	s_mov_b32 m0, s44
	v_lshl_add_u64 v[196:197], s[16:17], 0, v[154:155]
	s_add_u32 s48, s16, 0x18100
	ds_read_b128 v[62:65], v189 offset:16384
	ds_read_b128 v[102:105], v189 offset:17408
	ds_read_b128 v[106:109], v189 offset:18432
	ds_read_b128 v[110:113], v189 offset:19456
	ds_read_b128 v[114:117], v189 offset:20480
	ds_read_b128 v[118:121], v189 offset:21504
	ds_read_b128 v[122:125], v189 offset:22528
	ds_read_b128 v[126:129], v189 offset:23552
	global_load_lds_dwordx4 v[130:131], off
	v_lshl_add_u64 v[130:131], v[196:197], 0, s[50:51]
	s_mov_b32 m0, s1
	s_addc_u32 s49, s17, 0
	s_add_i32 s2, s2, s18
	global_load_lds_dwordx4 v[130:131], off
	v_lshl_add_u64 v[130:131], s[48:49], 0, v[0:1]
	s_mov_b32 m0, s2
	s_add_i32 s3, s2, 0x2000
	global_load_lds_dwordx4 v[130:131], off
	v_lshl_add_u64 v[130:131], s[48:49], 0, v[154:155]
	s_mov_b32 m0, s3
	v_lshl_add_u64 v[198:199], s[14:15], 0, v[150:151]
	global_load_lds_dwordx4 v[130:131], off
	v_lshl_add_u64 v[130:131], v[198:199], 0, s[50:51]
	s_mov_b32 m0, s24
	v_lshl_add_u64 v[200:201], s[14:15], 0, v[152:153]
	global_load_lds_dwordx4 v[130:131], off
	v_lshl_add_u64 v[130:131], v[200:201], 0, s[50:51]
	s_mov_b32 m0, s26
	s_nop 0
	global_load_lds_dwordx4 v[130:131], off
	s_waitcnt vmcnt(8)
	s_waitcnt lgkmcnt(0)
	s_barrier
	s_setprio 1
	v_mfma_f32_16x16x32_bf16 v[130:133], v[2:5], v[62:65], 0
	v_mfma_f32_16x16x32_bf16 v[138:141], v[2:5], v[106:109], 0
	v_mfma_f32_16x16x32_bf16 v[146:149], v[2:5], v[114:117], 0
	v_mfma_f32_16x16x32_bf16 v[2:5], v[2:5], v[122:125], 0
	v_mfma_f32_16x16x32_bf16 v[130:133], v[6:9], v[102:105], v[130:133]
	v_mfma_f32_16x16x32_bf16 v[134:137], v[10:13], v[62:65], 0
	v_mfma_f32_16x16x32_bf16 v[138:141], v[6:9], v[110:113], v[138:141]
	v_mfma_f32_16x16x32_bf16 v[146:149], v[6:9], v[118:121], v[146:149]
	v_mfma_f32_16x16x32_bf16 v[2:5], v[6:9], v[126:129], v[2:5]
	v_mfma_f32_16x16x32_bf16 v[6:9], v[10:13], v[122:125], 0
	v_mfma_f32_16x16x32_bf16 v[134:137], v[14:17], v[102:105], v[134:137]
	v_mfma_f32_16x16x32_bf16 v[142:145], v[10:13], v[106:109], 0
	v_mfma_f32_16x16x32_bf16 v[156:159], v[10:13], v[114:117], 0
	v_mfma_f32_16x16x32_bf16 v[6:9], v[14:17], v[126:129], v[6:9]
	v_mfma_f32_16x16x32_bf16 v[142:145], v[14:17], v[110:113], v[142:145]
	v_mfma_f32_16x16x32_bf16 v[156:159], v[14:17], v[118:121], v[156:159]
	v_mfma_f32_16x16x32_bf16 v[10:13], v[18:21], v[62:65], 0
	v_mfma_f32_16x16x32_bf16 v[14:17], v[26:29], v[62:65], 0
	v_mfma_f32_16x16x32_bf16 v[10:13], v[22:25], v[102:105], v[10:13]
	v_mfma_f32_16x16x32_bf16 v[14:17], v[30:33], v[102:105], v[14:17]
	v_mfma_f32_16x16x32_bf16 v[62:65], v[18:21], v[106:109], 0
	v_mfma_f32_16x16x32_bf16 v[102:105], v[26:29], v[106:109], 0
	v_mfma_f32_16x16x32_bf16 v[106:109], v[18:21], v[114:117], 0
	v_mfma_f32_16x16x32_bf16 v[18:21], v[18:21], v[122:125], 0
	v_mfma_f32_16x16x32_bf16 v[62:65], v[22:25], v[110:113], v[62:65]
	v_mfma_f32_16x16x32_bf16 v[102:105], v[30:33], v[110:113], v[102:105]
	v_mfma_f32_16x16x32_bf16 v[106:109], v[22:25], v[118:121], v[106:109]
	v_mfma_f32_16x16x32_bf16 v[110:113], v[26:29], v[114:117], 0
	v_mfma_f32_16x16x32_bf16 v[18:21], v[22:25], v[126:129], v[18:21]
	v_mfma_f32_16x16x32_bf16 v[22:25], v[26:29], v[122:125], 0
	v_mfma_f32_16x16x32_bf16 v[110:113], v[30:33], v[118:121], v[110:113]
	v_mfma_f32_16x16x32_bf16 v[22:25], v[30:33], v[126:129], v[22:25]
	s_setprio 0
	s_barrier
	s_add_i32 s47, 0, 0x18000
	s_add_i32 s50, 0, 0x1c000
	v_add_u32_e32 v206, s47, v188
	v_add_u32_e32 v207, s50, v188
	ds_read_b128 v[26:29], v206
	ds_read_b128 v[30:33], v206 offset:1024
	ds_read_b128 v[114:117], v206 offset:2048
	ds_read_b128 v[118:121], v206 offset:3072
	ds_read_b128 v[122:125], v207
	ds_read_b128 v[126:129], v207 offset:1024
	ds_read_b128 v[160:163], v207 offset:2048
	ds_read_b128 v[164:167], v207 offset:3072
	s_add_u32 s48, s14, 0x18100
	s_addc_u32 s49, s15, 0
	s_mov_b32 m0, s27
	v_lshl_add_u64 v[202:203], s[48:49], 0, v[150:151]
	ds_read_b128 v[168:171], v189 offset:32768
	ds_read_b128 v[172:175], v189 offset:33792
	ds_read_b128 v[176:179], v189 offset:34816
	ds_read_b128 v[180:183], v189 offset:35840
	ds_read_b128 v[184:187], v189 offset:36864
	ds_read_b128 v[190:193], v189 offset:37888
	ds_read_b128 v[210:213], v189 offset:38912
	ds_read_b128 v[214:217], v189 offset:39936
	global_load_lds_dwordx4 v[202:203], off
	v_lshl_add_u64 v[202:203], s[48:49], 0, v[152:153]
	s_mov_b32 m0, s28
	s_nop 0
	global_load_lds_dwordx4 v[202:203], off
	s_waitcnt vmcnt(8)
	s_waitcnt lgkmcnt(0)
	s_barrier
	s_setprio 1
	v_mfma_f32_16x16x32_bf16 v[66:69], v[26:29], v[168:171], v[66:69]
	v_mfma_f32_16x16x32_bf16 v[70:73], v[114:117], v[168:171], v[70:73]
	v_mfma_f32_16x16x32_bf16 v[74:77], v[26:29], v[176:179], v[74:77]
	v_mfma_f32_16x16x32_bf16 v[78:81], v[114:117], v[176:179], v[78:81]
	v_mfma_f32_16x16x32_bf16 v[82:85], v[26:29], v[184:187], v[82:85]
	v_mfma_f32_16x16x32_bf16 v[86:89], v[114:117], v[184:187], v[86:89]
	v_mfma_f32_16x16x32_bf16 v[90:93], v[26:29], v[210:213], v[90:93]
	v_mfma_f32_16x16x32_bf16 v[94:97], v[114:117], v[210:213], v[94:97]
	v_mfma_f32_16x16x32_bf16 v[66:69], v[30:33], v[172:175], v[66:69]
	v_mfma_f32_16x16x32_bf16 v[70:73], v[118:121], v[172:175], v[70:73]
	v_mfma_f32_16x16x32_bf16 v[74:77], v[30:33], v[180:183], v[74:77]
	v_mfma_f32_16x16x32_bf16 v[78:81], v[118:121], v[180:183], v[78:81]
	v_mfma_f32_16x16x32_bf16 v[82:85], v[30:33], v[190:193], v[82:85]
	v_mfma_f32_16x16x32_bf16 v[86:89], v[118:121], v[190:193], v[86:89]
	v_mfma_f32_16x16x32_bf16 v[90:93], v[30:33], v[214:217], v[90:93]
	v_mfma_f32_16x16x32_bf16 v[94:97], v[118:121], v[214:217], v[94:97]
	v_mfma_f32_16x16x32_bf16 v[98:101], v[122:125], v[168:171], v[98:101]
	v_mfma_f32_16x16x32_bf16 v[34:37], v[160:163], v[168:171], v[34:37]
	v_mfma_f32_16x16x32_bf16 v[38:41], v[122:125], v[176:179], v[38:41]
	v_mfma_f32_16x16x32_bf16 v[42:45], v[160:163], v[176:179], v[42:45]
	v_mfma_f32_16x16x32_bf16 v[46:49], v[122:125], v[184:187], v[46:49]
	v_mfma_f32_16x16x32_bf16 v[58:61], v[160:163], v[210:213], v[58:61]
	v_mfma_f32_16x16x32_bf16 v[98:101], v[126:129], v[172:175], v[98:101]
	v_mfma_f32_16x16x32_bf16 v[34:37], v[164:167], v[172:175], v[34:37]
	v_mfma_f32_16x16x32_bf16 v[38:41], v[126:129], v[180:183], v[38:41]
	v_mfma_f32_16x16x32_bf16 v[42:45], v[164:167], v[180:183], v[42:45]
	v_mfma_f32_16x16x32_bf16 v[46:49], v[126:129], v[190:193], v[46:49]
	v_mfma_f32_16x16x32_bf16 v[50:53], v[160:163], v[184:187], v[50:53]
	v_mfma_f32_16x16x32_bf16 v[54:57], v[122:125], v[210:213], v[54:57]
	v_mfma_f32_16x16x32_bf16 v[58:61], v[164:167], v[214:217], v[58:61]
	v_mfma_f32_16x16x32_bf16 v[50:53], v[164:167], v[190:193], v[50:53]
	v_mfma_f32_16x16x32_bf16 v[54:57], v[126:129], v[214:217], v[54:57]
	s_setprio 0
	s_barrier
	s_add_i32 s47, s47, s18
	s_mov_b64 s[52:53], 0x180
	s_add_i32 s45, s47, 0x2000
	v_lshl_add_u64 v[194:195], v[194:195], 0, s[52:53]
	s_mov_b32 m0, s47
	s_add_u32 s48, s16, 0x18180
	ds_read_b128 v[168:171], v189 offset:49152
	ds_read_b128 v[172:175], v189 offset:50176
	ds_read_b128 v[176:179], v189 offset:51200
	ds_read_b128 v[180:183], v189 offset:52224
	ds_read_b128 v[184:187], v189 offset:53248
	ds_read_b128 v[190:193], v189 offset:54272
	ds_read_b128 v[210:213], v189 offset:55296
	ds_read_b128 v[214:217], v189 offset:56320
	global_load_lds_dwordx4 v[194:195], off
	v_lshl_add_u64 v[194:195], v[196:197], 0, s[52:53]
	s_mov_b32 m0, s45
	s_addc_u32 s49, s17, 0
	s_add_i32 s16, s50, s18
	global_load_lds_dwordx4 v[194:195], off
	v_lshl_add_u64 v[194:195], s[48:49], 0, v[0:1]
	s_mov_b32 m0, s16
	s_add_i32 s17, s16, 0x2000
	global_load_lds_dwordx4 v[194:195], off
	v_lshl_add_u64 v[194:195], s[48:49], 0, v[154:155]
	s_mov_b32 m0, s17
	s_nop 0
	global_load_lds_dwordx4 v[194:195], off
	v_lshl_add_u64 v[194:195], v[198:199], 0, s[52:53]
	s_mov_b32 m0, s39
	s_nop 0
	global_load_lds_dwordx4 v[194:195], off
	v_lshl_add_u64 v[194:195], v[200:201], 0, s[52:53]
	s_mov_b32 m0, s40
	s_nop 0
	global_load_lds_dwordx4 v[194:195], off
	s_waitcnt vmcnt(8)
	s_waitcnt lgkmcnt(0)
	s_barrier
	s_setprio 1
	v_mfma_f32_16x16x32_bf16 v[130:133], v[26:29], v[168:171], v[130:133]
	v_mfma_f32_16x16x32_bf16 v[134:137], v[114:117], v[168:171], v[134:137]
	v_mfma_f32_16x16x32_bf16 v[2:5], v[26:29], v[210:213], v[2:5]
	v_mfma_f32_16x16x32_bf16 v[6:9], v[114:117], v[210:213], v[6:9]
	v_mfma_f32_16x16x32_bf16 v[130:133], v[30:33], v[172:175], v[130:133]
	v_mfma_f32_16x16x32_bf16 v[134:137], v[118:121], v[172:175], v[134:137]
	v_mfma_f32_16x16x32_bf16 v[138:141], v[26:29], v[176:179], v[138:141]
	v_mfma_f32_16x16x32_bf16 v[142:145], v[114:117], v[176:179], v[142:145]
	v_mfma_f32_16x16x32_bf16 v[146:149], v[26:29], v[184:187], v[146:149]
	v_mfma_f32_16x16x32_bf16 v[156:159], v[114:117], v[184:187], v[156:159]
	v_mfma_f32_16x16x32_bf16 v[2:5], v[30:33], v[214:217], v[2:5]
	v_mfma_f32_16x16x32_bf16 v[6:9], v[118:121], v[214:217], v[6:9]
	v_mfma_f32_16x16x32_bf16 v[138:141], v[30:33], v[180:183], v[138:141]
	v_mfma_f32_16x16x32_bf16 v[142:145], v[118:121], v[180:183], v[142:145]
	v_mfma_f32_16x16x32_bf16 v[146:149], v[30:33], v[190:193], v[146:149]
	v_mfma_f32_16x16x32_bf16 v[156:159], v[118:121], v[190:193], v[156:159]
	v_mfma_f32_16x16x32_bf16 v[10:13], v[122:125], v[168:171], v[10:13]
	v_mfma_f32_16x16x32_bf16 v[14:17], v[160:163], v[168:171], v[14:17]
	v_mfma_f32_16x16x32_bf16 v[26:29], v[122:125], v[176:179], v[62:65]
	v_mfma_f32_16x16x32_bf16 v[30:33], v[160:163], v[176:179], v[102:105]
	v_mfma_f32_16x16x32_bf16 v[62:65], v[122:125], v[184:187], v[106:109]
	v_mfma_f32_16x16x32_bf16 v[102:105], v[160:163], v[184:187], v[110:113]
	v_mfma_f32_16x16x32_bf16 v[18:21], v[122:125], v[210:213], v[18:21]
	v_mfma_f32_16x16x32_bf16 v[22:25], v[160:163], v[210:213], v[22:25]
	v_mfma_f32_16x16x32_bf16 v[10:13], v[126:129], v[172:175], v[10:13]
	v_mfma_f32_16x16x32_bf16 v[14:17], v[164:167], v[172:175], v[14:17]
	v_mfma_f32_16x16x32_bf16 v[26:29], v[126:129], v[180:183], v[26:29]
	v_mfma_f32_16x16x32_bf16 v[30:33], v[164:167], v[180:183], v[30:33]
	v_mfma_f32_16x16x32_bf16 v[62:65], v[126:129], v[190:193], v[62:65]
	v_mfma_f32_16x16x32_bf16 v[102:105], v[164:167], v[190:193], v[102:105]
	v_mfma_f32_16x16x32_bf16 v[18:21], v[126:129], v[214:217], v[18:21]
	v_mfma_f32_16x16x32_bf16 v[22:25], v[164:167], v[214:217], v[22:25]
	s_setprio 0
	s_barrier
	ds_read_b128 v[106:109], v204
	ds_read_b128 v[110:113], v204 offset:1024
	ds_read_b128 v[114:117], v204 offset:2048
	ds_read_b128 v[118:121], v204 offset:3072
	ds_read_b128 v[122:125], v205
	ds_read_b128 v[126:129], v205 offset:1024
	ds_read_b128 v[160:163], v205 offset:2048
	ds_read_b128 v[164:167], v205 offset:3072
	s_add_u32 s14, s14, 0x18180
	s_addc_u32 s15, s15, 0
	s_mov_b32 m0, s46
	v_lshl_add_u64 v[194:195], s[14:15], 0, v[150:151]
	ds_read_b128 v[168:171], v189
	ds_read_b128 v[172:175], v189 offset:1024
	ds_read_b128 v[176:179], v189 offset:2048
	ds_read_b128 v[180:183], v189 offset:3072
	ds_read_b128 v[184:187], v189 offset:4096
	ds_read_b128 v[190:193], v189 offset:5120
	ds_read_b128 v[210:213], v189 offset:6144
	ds_read_b128 v[214:217], v189 offset:7168
	global_load_lds_dwordx4 v[194:195], off
	v_lshl_add_u64 v[194:195], s[14:15], 0, v[152:153]
	s_mov_b32 m0, s0
	s_nop 0
	global_load_lds_dwordx4 v[194:195], off
	s_waitcnt vmcnt(8)
	s_waitcnt lgkmcnt(0)
	s_barrier
	s_setprio 1
	v_mfma_f32_16x16x32_bf16 v[66:69], v[106:109], v[168:171], v[66:69]
	v_mfma_f32_16x16x32_bf16 v[70:73], v[114:117], v[168:171], v[70:73]
	v_mfma_f32_16x16x32_bf16 v[74:77], v[106:109], v[176:179], v[74:77]
	v_mfma_f32_16x16x32_bf16 v[78:81], v[114:117], v[176:179], v[78:81]
	v_mfma_f32_16x16x32_bf16 v[82:85], v[106:109], v[184:187], v[82:85]
	v_mfma_f32_16x16x32_bf16 v[86:89], v[114:117], v[184:187], v[86:89]
	v_mfma_f32_16x16x32_bf16 v[90:93], v[106:109], v[210:213], v[90:93]
	v_mfma_f32_16x16x32_bf16 v[94:97], v[114:117], v[210:213], v[94:97]
	v_mfma_f32_16x16x32_bf16 v[66:69], v[110:113], v[172:175], v[66:69]
	v_mfma_f32_16x16x32_bf16 v[70:73], v[118:121], v[172:175], v[70:73]
	v_mfma_f32_16x16x32_bf16 v[74:77], v[110:113], v[180:183], v[74:77]
	v_mfma_f32_16x16x32_bf16 v[78:81], v[118:121], v[180:183], v[78:81]
	v_mfma_f32_16x16x32_bf16 v[82:85], v[110:113], v[190:193], v[82:85]
	v_mfma_f32_16x16x32_bf16 v[86:89], v[118:121], v[190:193], v[86:89]
	v_mfma_f32_16x16x32_bf16 v[90:93], v[110:113], v[214:217], v[90:93]
	v_mfma_f32_16x16x32_bf16 v[94:97], v[118:121], v[214:217], v[94:97]
	v_mfma_f32_16x16x32_bf16 v[34:37], v[160:163], v[168:171], v[34:37]
	v_mfma_f32_16x16x32_bf16 v[38:41], v[122:125], v[176:179], v[38:41]
	v_mfma_f32_16x16x32_bf16 v[42:45], v[160:163], v[176:179], v[42:45]
	v_mfma_f32_16x16x32_bf16 v[46:49], v[122:125], v[184:187], v[46:49]
	v_mfma_f32_16x16x32_bf16 v[58:61], v[160:163], v[210:213], v[58:61]
	v_mfma_f32_16x16x32_bf16 v[98:101], v[122:125], v[168:171], v[98:101]
	v_mfma_f32_16x16x32_bf16 v[34:37], v[164:167], v[172:175], v[34:37]
	v_mfma_f32_16x16x32_bf16 v[38:41], v[126:129], v[180:183], v[38:41]
	v_mfma_f32_16x16x32_bf16 v[42:45], v[164:167], v[180:183], v[42:45]
	v_mfma_f32_16x16x32_bf16 v[46:49], v[126:129], v[190:193], v[46:49]
	v_mfma_f32_16x16x32_bf16 v[50:53], v[160:163], v[184:187], v[50:53]
	v_mfma_f32_16x16x32_bf16 v[54:57], v[122:125], v[210:213], v[54:57]
	v_mfma_f32_16x16x32_bf16 v[58:61], v[164:167], v[214:217], v[58:61]
	v_mfma_f32_16x16x32_bf16 v[218:221], v[126:129], v[172:175], v[98:101]
	v_mfma_f32_16x16x32_bf16 v[50:53], v[164:167], v[190:193], v[50:53]
	v_mfma_f32_16x16x32_bf16 v[54:57], v[126:129], v[214:217], v[54:57]
	s_setprio 0
	s_barrier
	s_mov_b32 m0, s44
	v_lshl_add_u64 v[234:235], s[12:13], 0, v[0:1]
	s_add_u32 s0, s12, 0x18000
	ds_read_b128 v[98:101], v189 offset:16384
	ds_read_b128 v[168:171], v189 offset:17408
	ds_read_b128 v[172:175], v189 offset:18432
	ds_read_b128 v[176:179], v189 offset:19456
	ds_read_b128 v[180:183], v189 offset:20480
	ds_read_b128 v[184:187], v189 offset:21504
	ds_read_b128 v[190:193], v189 offset:22528
	ds_read_b128 v[210:213], v189 offset:23552
	global_load_lds_dwordx4 v[234:235], off
	v_lshl_add_u64 v[248:249], s[12:13], 0, v[154:155]
	s_mov_b32 m0, s1
	s_addc_u32 s1, s13, 0
	global_load_lds_dwordx4 v[248:249], off
	v_lshl_add_u64 v[194:195], s[0:1], 0, v[0:1]
	s_mov_b32 m0, s2
	v_lshl_add_u64 v[230:231], s[10:11], 0, v[150:151]
	global_load_lds_dwordx4 v[194:195], off
	v_lshl_add_u64 v[194:195], s[0:1], 0, v[154:155]
	s_mov_b32 m0, s3
	v_lshl_add_u64 v[226:227], s[10:11], 0, v[152:153]
	global_load_lds_dwordx4 v[194:195], off
	s_mov_b32 m0, s24
	s_nop 0
	global_load_lds_dwordx4 v[230:231], off
	s_mov_b32 m0, s26
	s_nop 0
	global_load_lds_dwordx4 v[226:227], off
	s_waitcnt vmcnt(8)
	s_waitcnt lgkmcnt(0)
	s_barrier
	s_setprio 1
	v_mfma_f32_16x16x32_bf16 v[130:133], v[106:109], v[98:101], v[130:133]
	v_mfma_f32_16x16x32_bf16 v[214:217], v[110:113], v[168:171], v[130:133]
	v_mfma_f32_16x16x32_bf16 v[130:133], v[114:117], v[98:101], v[134:137]
	v_mfma_f32_16x16x32_bf16 v[222:225], v[118:121], v[168:171], v[130:133]
	v_mfma_f32_16x16x32_bf16 v[130:133], v[106:109], v[172:175], v[138:141]
	v_mfma_f32_16x16x32_bf16 v[138:141], v[110:113], v[176:179], v[130:133]
	v_mfma_f32_16x16x32_bf16 v[130:133], v[114:117], v[172:175], v[142:145]
	v_mfma_f32_16x16x32_bf16 v[142:145], v[118:121], v[176:179], v[130:133]
	v_mfma_f32_16x16x32_bf16 v[130:133], v[106:109], v[180:183], v[146:149]
	v_mfma_f32_16x16x32_bf16 v[2:5], v[106:109], v[190:193], v[2:5]
	v_mfma_f32_16x16x32_bf16 v[6:9], v[114:117], v[190:193], v[6:9]
	v_mfma_f32_16x16x32_bf16 v[146:149], v[110:113], v[184:187], v[130:133]
	v_mfma_f32_16x16x32_bf16 v[130:133], v[114:117], v[180:183], v[156:159]
	v_mfma_f32_16x16x32_bf16 v[2:5], v[110:113], v[210:213], v[2:5]
	v_mfma_f32_16x16x32_bf16 v[6:9], v[118:121], v[210:213], v[6:9]
	v_mfma_f32_16x16x32_bf16 v[156:159], v[118:121], v[184:187], v[130:133]
	v_mfma_f32_16x16x32_bf16 v[10:13], v[122:125], v[98:101], v[10:13]
	v_mfma_f32_16x16x32_bf16 v[240:243], v[126:129], v[168:171], v[10:13]
	v_mfma_f32_16x16x32_bf16 v[10:13], v[160:163], v[98:101], v[14:17]
	v_mfma_f32_16x16x32_bf16 v[168:171], v[164:167], v[168:171], v[10:13]
	v_mfma_f32_16x16x32_bf16 v[10:13], v[122:125], v[172:175], v[26:29]
	v_mfma_f32_16x16x32_bf16 v[244:247], v[126:129], v[176:179], v[10:13]
	v_mfma_f32_16x16x32_bf16 v[10:13], v[160:163], v[172:175], v[30:33]
	v_mfma_f32_16x16x32_bf16 v[172:175], v[164:167], v[176:179], v[10:13]
	v_mfma_f32_16x16x32_bf16 v[10:13], v[122:125], v[180:183], v[62:65]
	v_mfma_f32_16x16x32_bf16 v[176:179], v[126:129], v[184:187], v[10:13]
	v_mfma_f32_16x16x32_bf16 v[10:13], v[160:163], v[180:183], v[102:105]
	v_mfma_f32_16x16x32_bf16 v[180:183], v[164:167], v[184:187], v[10:13]
	v_mfma_f32_16x16x32_bf16 v[10:13], v[122:125], v[190:193], v[18:21]
	v_mfma_f32_16x16x32_bf16 v[184:187], v[126:129], v[210:213], v[10:13]
	v_mfma_f32_16x16x32_bf16 v[10:13], v[160:163], v[190:193], v[22:25]
	v_mfma_f32_16x16x32_bf16 v[160:163], v[164:167], v[210:213], v[10:13]
	s_setprio 0
	s_barrier
	s_nop 4
	ds_read_b128 v[10:13], v206
	ds_read_b128 v[14:17], v206 offset:1024
	ds_read_b128 v[18:21], v206 offset:2048
	ds_read_b128 v[22:25], v206 offset:3072
	ds_read_b128 v[164:167], v207
	ds_read_b128 v[190:193], v207 offset:1024
	ds_read_b128 v[210:213], v207 offset:2048
	ds_read_b128 v[194:197], v207 offset:3072
	s_add_u32 s0, s10, 0x18000
	s_addc_u32 s1, s11, 0
	s_mov_b32 m0, s27
	v_lshl_add_u64 v[98:99], s[0:1], 0, v[150:151]
	ds_read_b128 v[26:29], v189 offset:32768
	ds_read_b128 v[30:33], v189 offset:33792
	ds_read_b128 v[62:65], v189 offset:34816
	ds_read_b128 v[106:109], v189 offset:35840
	ds_read_b128 v[198:201], v189 offset:36864
	ds_read_b128 v[206:209], v189 offset:37888
	ds_read_b128 v[236:239], v189 offset:38912
	ds_read_b128 v[202:205], v189 offset:39936
	global_load_lds_dwordx4 v[98:99], off
	v_lshl_add_u64 v[98:99], s[0:1], 0, v[152:153]
	s_mov_b32 m0, s28
	s_nop 0
	global_load_lds_dwordx4 v[98:99], off
	s_waitcnt vmcnt(8)
	s_waitcnt lgkmcnt(0)
	s_barrier
	s_setprio 1
	v_mfma_f32_16x16x32_bf16 v[66:69], v[10:13], v[26:29], v[66:69]
	v_mfma_f32_16x16x32_bf16 v[134:137], v[14:17], v[30:33], v[66:69]
	v_mfma_f32_16x16x32_bf16 v[66:69], v[18:21], v[26:29], v[70:73]
	v_mfma_f32_16x16x32_bf16 v[130:133], v[22:25], v[30:33], v[66:69]
	v_mfma_f32_16x16x32_bf16 v[66:69], v[10:13], v[62:65], v[74:77]
	v_mfma_f32_16x16x32_bf16 v[118:121], v[14:17], v[106:109], v[66:69]
	v_mfma_f32_16x16x32_bf16 v[66:69], v[18:21], v[62:65], v[78:81]
	v_mfma_f32_16x16x32_bf16 v[114:117], v[22:25], v[106:109], v[66:69]
	v_mfma_f32_16x16x32_bf16 v[66:69], v[10:13], v[198:201], v[82:85]
	v_mfma_f32_16x16x32_bf16 v[102:105], v[14:17], v[206:209], v[66:69]
	v_mfma_f32_16x16x32_bf16 v[66:69], v[18:21], v[198:201], v[86:89]
	v_mfma_f32_16x16x32_bf16 v[98:101], v[22:25], v[206:209], v[66:69]
	v_mfma_f32_16x16x32_bf16 v[66:69], v[10:13], v[236:239], v[90:93]
	v_mfma_f32_16x16x32_bf16 v[86:89], v[14:17], v[202:205], v[66:69]
	v_mfma_f32_16x16x32_bf16 v[66:69], v[18:21], v[236:239], v[94:97]
	v_mfma_f32_16x16x32_bf16 v[82:85], v[22:25], v[202:205], v[66:69]
	v_mfma_f32_16x16x32_bf16 v[66:69], v[164:167], v[26:29], v[218:221]
	v_mfma_f32_16x16x32_bf16 v[26:29], v[210:213], v[26:29], v[34:37]
	v_mfma_f32_16x16x32_bf16 v[122:125], v[194:197], v[30:33], v[26:29]
	v_mfma_f32_16x16x32_bf16 v[26:29], v[164:167], v[62:65], v[38:41]
	v_mfma_f32_16x16x32_bf16 v[110:113], v[190:193], v[106:109], v[26:29]
	v_mfma_f32_16x16x32_bf16 v[26:29], v[210:213], v[62:65], v[42:45]
	v_mfma_f32_16x16x32_bf16 v[106:109], v[194:197], v[106:109], v[26:29]
	v_mfma_f32_16x16x32_bf16 v[26:29], v[164:167], v[198:201], v[46:49]
	v_mfma_f32_16x16x32_bf16 v[94:97], v[190:193], v[206:209], v[26:29]
	v_mfma_f32_16x16x32_bf16 v[26:29], v[210:213], v[198:201], v[50:53]
	v_mfma_f32_16x16x32_bf16 v[90:93], v[194:197], v[206:209], v[26:29]
	v_mfma_f32_16x16x32_bf16 v[26:29], v[164:167], v[236:239], v[54:57]
	v_mfma_f32_16x16x32_bf16 v[78:81], v[190:193], v[202:205], v[26:29]
	v_mfma_f32_16x16x32_bf16 v[26:29], v[210:213], v[236:239], v[58:61]
	v_mfma_f32_16x16x32_bf16 v[126:129], v[190:193], v[30:33], v[66:69]
	v_mfma_f32_16x16x32_bf16 v[74:77], v[194:197], v[202:205], v[26:29]
	s_setprio 0
	s_barrier
	s_mov_b32 m0, s47
	s_nop 2
	v_lshl_add_u64 v[26:27], v[234:235], 0, s[22:23]
	s_add_u32 s0, s12, 0x18080
	ds_read_b128 v[34:37], v189 offset:49152
	ds_read_b128 v[38:41], v189 offset:50176
	ds_read_b128 v[50:53], v189 offset:51200
	ds_read_b128 v[54:57], v189 offset:52224
	ds_read_b128 v[198:201], v189 offset:53248
	ds_read_b128 v[202:205], v189 offset:54272
	ds_read_b128 v[206:209], v189 offset:55296
	ds_read_b128 v[218:221], v189 offset:56320
	global_load_lds_dwordx4 v[26:27], off
	v_lshl_add_u64 v[26:27], v[248:249], 0, s[22:23]
	s_mov_b32 m0, s45
	s_addc_u32 s1, s13, 0
	global_load_lds_dwordx4 v[26:27], off
	v_lshl_add_u64 v[26:27], s[0:1], 0, v[0:1]
	s_mov_b32 m0, s16
	s_nop 0
	global_load_lds_dwordx4 v[26:27], off
	v_lshl_add_u64 v[26:27], s[0:1], 0, v[154:155]
	s_mov_b32 m0, s17
	s_nop 0
	global_load_lds_dwordx4 v[26:27], off
	v_lshl_add_u64 v[26:27], v[230:231], 0, s[22:23]
	s_mov_b32 m0, s39
	s_nop 0
	global_load_lds_dwordx4 v[26:27], off
	v_lshl_add_u64 v[26:27], v[226:227], 0, s[22:23]
	s_mov_b32 m0, s40
	s_nop 0
	global_load_lds_dwordx4 v[26:27], off
	s_waitcnt vmcnt(8)
	s_waitcnt lgkmcnt(0)
	s_barrier
	s_setprio 1
	v_mfma_f32_16x16x32_bf16 v[26:29], v[10:13], v[34:37], v[214:217]
	v_mfma_f32_16x16x32_bf16 v[70:73], v[14:17], v[38:41], v[26:29]
	v_mfma_f32_16x16x32_bf16 v[26:29], v[18:21], v[34:37], v[222:225]
	v_mfma_f32_16x16x32_bf16 v[66:69], v[22:25], v[38:41], v[26:29]
	v_mfma_f32_16x16x32_bf16 v[26:29], v[10:13], v[50:53], v[138:141]
	v_mfma_f32_16x16x32_bf16 v[46:49], v[14:17], v[54:57], v[26:29]
	v_mfma_f32_16x16x32_bf16 v[26:29], v[18:21], v[50:53], v[142:145]
	v_mfma_f32_16x16x32_bf16 v[42:45], v[22:25], v[54:57], v[26:29]
	v_mfma_f32_16x16x32_bf16 v[26:29], v[10:13], v[198:201], v[146:149]
	v_mfma_f32_16x16x32_bf16 v[2:5], v[10:13], v[206:209], v[2:5]
	v_mfma_f32_16x16x32_bf16 v[30:33], v[14:17], v[202:205], v[26:29]
	v_mfma_f32_16x16x32_bf16 v[26:29], v[18:21], v[198:201], v[156:159]
	v_mfma_f32_16x16x32_bf16 v[14:17], v[14:17], v[218:221], v[2:5]
	v_mfma_f32_16x16x32_bf16 v[2:5], v[18:21], v[206:209], v[6:9]
	v_mfma_f32_16x16x32_bf16 v[26:29], v[22:25], v[202:205], v[26:29]
	v_mfma_f32_16x16x32_bf16 v[10:13], v[22:25], v[218:221], v[2:5]
	v_mfma_f32_16x16x32_bf16 v[2:5], v[164:167], v[34:37], v[240:243]
	v_mfma_f32_16x16x32_bf16 v[62:65], v[190:193], v[38:41], v[2:5]
	v_mfma_f32_16x16x32_bf16 v[2:5], v[210:213], v[34:37], v[168:171]
	v_mfma_f32_16x16x32_bf16 v[58:61], v[194:197], v[38:41], v[2:5]
	v_mfma_f32_16x16x32_bf16 v[2:5], v[164:167], v[50:53], v[244:247]
	v_mfma_f32_16x16x32_bf16 v[38:41], v[190:193], v[54:57], v[2:5]
	v_mfma_f32_16x16x32_bf16 v[2:5], v[210:213], v[50:53], v[172:175]
	v_mfma_f32_16x16x32_bf16 v[34:37], v[194:197], v[54:57], v[2:5]
	v_mfma_f32_16x16x32_bf16 v[2:5], v[164:167], v[198:201], v[176:179]
	v_mfma_f32_16x16x32_bf16 v[22:25], v[190:193], v[202:205], v[2:5]
	v_mfma_f32_16x16x32_bf16 v[2:5], v[210:213], v[198:201], v[180:183]
	v_mfma_f32_16x16x32_bf16 v[18:21], v[194:197], v[202:205], v[2:5]
	v_mfma_f32_16x16x32_bf16 v[2:5], v[164:167], v[206:209], v[184:187]
	v_mfma_f32_16x16x32_bf16 v[6:9], v[190:193], v[218:221], v[2:5]
	v_mfma_f32_16x16x32_bf16 v[2:5], v[210:213], v[206:209], v[160:163]
	v_mfma_f32_16x16x32_bf16 v[2:5], v[194:197], v[218:221], v[2:5]
	s_setprio 0
	s_barrier
	s_andn2_b64 vcc, exec, s[4:5]
	s_cbranch_vccnz .LBB0_799
	s_barrier

.LBB0_1611:
	s_add_u32 s2, s20, 0x100
	s_addc_u32 s3, s21, 0
	s_mov_b32 s30, -2
	s_add_u32 s20, s18, 0x100
	s_addc_u32 s21, s19, 0
	s_add_i32 s50, 0, 0x10000
	s_cmp_eq_u32 s30, 20
	s_cselect_b32 s37, s1, s21
	s_cselect_b32 s36, s0, s20
	s_cselect_b32 s27, s29, s3
	s_cselect_b32 s26, s28, s2
	s_add_i32 s51, 0, 0x14000
	v_add_u32_e32 v142, s50, v171
	v_add_u32_e32 v168, s51, v171
	s_waitcnt lgkmcnt(0)
	ds_read_b128 v[130:133], v142
	ds_read_b128 v[134:137], v142 offset:1024
	ds_read_b128 v[138:141], v142 offset:2048
	ds_read_b128 v[142:145], v142 offset:3072
	ds_read_b128 v[146:149], v168
	ds_read_b128 v[150:153], v168 offset:1024
	ds_read_b128 v[164:167], v168 offset:2048
	ds_read_b128 v[180:183], v168 offset:3072
	v_lshl_add_u64 v[168:169], s[18:19], 0, v[160:161]
	s_add_i32 m0, s40, 0xc000
	ds_read_b128 v[184:187], v179
	ds_read_b128 v[188:191], v179 offset:1024
	ds_read_b128 v[192:195], v179 offset:2048
	ds_read_b128 v[196:199], v179 offset:3072
	ds_read_b128 v[200:203], v179 offset:4096
	ds_read_b128 v[204:207], v179 offset:5120
	ds_read_b128 v[208:211], v179 offset:6144
	ds_read_b128 v[212:215], v179 offset:7168
	global_load_lds_dwordx4 v[168:169], off
	v_lshl_add_u64 v[168:169], s[18:19], 0, v[162:163]
	s_add_i32 m0, s40, 0xe000
	s_nop 0
	global_load_lds_dwordx4 v[168:169], off
	s_waitcnt vmcnt(8)
	s_waitcnt lgkmcnt(0)
	s_barrier
	s_setprio 1
	v_mfma_f32_16x16x32_bf16 v[126:129], v[130:133], v[184:187], 0
	v_mfma_f32_16x16x32_bf16 v[122:125], v[138:141], v[184:187], 0
	v_mfma_f32_16x16x32_bf16 v[110:113], v[130:133], v[192:195], 0
	v_mfma_f32_16x16x32_bf16 v[106:109], v[138:141], v[192:195], 0
	v_mfma_f32_16x16x32_bf16 v[94:97], v[130:133], v[200:203], 0
	v_mfma_f32_16x16x32_bf16 v[90:93], v[138:141], v[200:203], 0
	v_mfma_f32_16x16x32_bf16 v[78:81], v[130:133], v[208:211], 0
	v_mfma_f32_16x16x32_bf16 v[74:77], v[138:141], v[208:211], 0
	v_mfma_f32_16x16x32_bf16 v[126:129], v[134:137], v[188:191], v[126:129]
	v_mfma_f32_16x16x32_bf16 v[122:125], v[142:145], v[188:191], v[122:125]
	v_mfma_f32_16x16x32_bf16 v[110:113], v[134:137], v[196:199], v[110:113]
	v_mfma_f32_16x16x32_bf16 v[106:109], v[142:145], v[196:199], v[106:109]
	v_mfma_f32_16x16x32_bf16 v[94:97], v[134:137], v[204:207], v[94:97]
	v_mfma_f32_16x16x32_bf16 v[90:93], v[142:145], v[204:207], v[90:93]
	v_mfma_f32_16x16x32_bf16 v[78:81], v[134:137], v[212:215], v[78:81]
	v_mfma_f32_16x16x32_bf16 v[74:77], v[142:145], v[212:215], v[74:77]
	v_mfma_f32_16x16x32_bf16 v[118:121], v[146:149], v[184:187], 0
	v_mfma_f32_16x16x32_bf16 v[114:117], v[164:167], v[184:187], 0
	v_mfma_f32_16x16x32_bf16 v[102:105], v[146:149], v[192:195], 0
	v_mfma_f32_16x16x32_bf16 v[98:101], v[164:167], v[192:195], 0
	v_mfma_f32_16x16x32_bf16 v[86:89], v[146:149], v[200:203], 0
	v_mfma_f32_16x16x32_bf16 v[82:85], v[164:167], v[200:203], 0
	v_mfma_f32_16x16x32_bf16 v[70:73], v[146:149], v[208:211], 0
	v_mfma_f32_16x16x32_bf16 v[66:69], v[164:167], v[208:211], 0
	v_mfma_f32_16x16x32_bf16 v[118:121], v[150:153], v[188:191], v[118:121]
	v_mfma_f32_16x16x32_bf16 v[114:117], v[180:183], v[188:191], v[114:117]
	v_mfma_f32_16x16x32_bf16 v[102:105], v[150:153], v[196:199], v[102:105]
	v_mfma_f32_16x16x32_bf16 v[98:101], v[180:183], v[196:199], v[98:101]
	v_mfma_f32_16x16x32_bf16 v[86:89], v[150:153], v[204:207], v[86:89]
	v_mfma_f32_16x16x32_bf16 v[82:85], v[180:183], v[204:207], v[82:85]
	v_mfma_f32_16x16x32_bf16 v[70:73], v[150:153], v[212:215], v[70:73]
	v_mfma_f32_16x16x32_bf16 v[66:69], v[180:183], v[212:215], v[66:69]
	s_setprio 0
	s_barrier
	s_add_i32 s18, s50, s38
	v_lshl_add_u64 v[168:169], s[26:27], 0, v[0:1]
	s_mov_b32 m0, s18
	ds_read_b128 v[184:187], v179 offset:16384
	ds_read_b128 v[188:191], v179 offset:17408
	ds_read_b128 v[192:195], v179 offset:18432
	ds_read_b128 v[196:199], v179 offset:19456
	ds_read_b128 v[200:203], v179 offset:20480
	ds_read_b128 v[204:207], v179 offset:21504
	ds_read_b128 v[208:211], v179 offset:22528
	ds_read_b128 v[212:215], v179 offset:23552
	global_load_lds_dwordx4 v[168:169], off
	s_add_i32 m0, s18, 0x2000
	s_add_u32 s18, s26, 0x1a000
	v_lshl_add_u64 v[216:217], s[26:27], 0, v[158:159]
	s_addc_u32 s19, s27, 0
	s_add_i32 s50, s51, s38
	global_load_lds_dwordx4 v[216:217], off
	v_lshl_add_u64 v[218:219], s[18:19], 0, v[0:1]
	s_mov_b32 m0, s50
	v_lshl_add_u64 v[220:221], s[36:37], 0, v[156:157]
	global_load_lds_dwordx4 v[218:219], off
	v_lshl_add_u64 v[218:219], s[18:19], 0, v[158:159]
	s_add_i32 m0, s50, 0x2000
	s_nop 0
	global_load_lds_dwordx4 v[218:219], off
	v_lshl_add_u64 v[218:219], s[36:37], 0, v[154:155]
	s_mov_b32 m0, s40
	s_nop 0
	global_load_lds_dwordx4 v[218:219], off
	s_mov_b32 m0, s41
	s_nop 0
	global_load_lds_dwordx4 v[220:221], off
	s_waitcnt vmcnt(8)
	s_waitcnt lgkmcnt(0)
	s_barrier
	s_setprio 1
	v_mfma_f32_16x16x32_bf16 v[62:65], v[130:133], v[184:187], 0
	v_mfma_f32_16x16x32_bf16 v[58:61], v[138:141], v[184:187], 0
	v_mfma_f32_16x16x32_bf16 v[46:49], v[130:133], v[192:195], 0
	v_mfma_f32_16x16x32_bf16 v[42:45], v[138:141], v[192:195], 0
	v_mfma_f32_16x16x32_bf16 v[30:33], v[130:133], v[200:203], 0
	v_mfma_f32_16x16x32_bf16 v[26:29], v[138:141], v[200:203], 0
	v_mfma_f32_16x16x32_bf16 v[14:17], v[130:133], v[208:211], 0
	v_mfma_f32_16x16x32_bf16 v[10:13], v[138:141], v[208:211], 0
	v_mfma_f32_16x16x32_bf16 v[62:65], v[134:137], v[188:191], v[62:65]
	v_mfma_f32_16x16x32_bf16 v[58:61], v[142:145], v[188:191], v[58:61]
	v_mfma_f32_16x16x32_bf16 v[46:49], v[134:137], v[196:199], v[46:49]
	v_mfma_f32_16x16x32_bf16 v[42:45], v[142:145], v[196:199], v[42:45]
	v_mfma_f32_16x16x32_bf16 v[30:33], v[134:137], v[204:207], v[30:33]
	v_mfma_f32_16x16x32_bf16 v[26:29], v[142:145], v[204:207], v[26:29]
	v_mfma_f32_16x16x32_bf16 v[14:17], v[134:137], v[212:215], v[14:17]
	v_mfma_f32_16x16x32_bf16 v[10:13], v[142:145], v[212:215], v[10:13]
	v_mfma_f32_16x16x32_bf16 v[54:57], v[146:149], v[184:187], 0
	v_mfma_f32_16x16x32_bf16 v[50:53], v[164:167], v[184:187], 0
	v_mfma_f32_16x16x32_bf16 v[38:41], v[146:149], v[192:195], 0
	v_mfma_f32_16x16x32_bf16 v[34:37], v[164:167], v[192:195], 0
	v_mfma_f32_16x16x32_bf16 v[22:25], v[146:149], v[200:203], 0
	v_mfma_f32_16x16x32_bf16 v[18:21], v[164:167], v[200:203], 0
	v_mfma_f32_16x16x32_bf16 v[6:9], v[146:149], v[208:211], 0
	v_mfma_f32_16x16x32_bf16 v[2:5], v[164:167], v[208:211], 0
	v_mfma_f32_16x16x32_bf16 v[54:57], v[150:153], v[188:191], v[54:57]
	v_mfma_f32_16x16x32_bf16 v[50:53], v[180:183], v[188:191], v[50:53]
	v_mfma_f32_16x16x32_bf16 v[38:41], v[150:153], v[196:199], v[38:41]
	v_mfma_f32_16x16x32_bf16 v[34:37], v[180:183], v[196:199], v[34:37]
	v_mfma_f32_16x16x32_bf16 v[22:25], v[150:153], v[204:207], v[22:25]
	v_mfma_f32_16x16x32_bf16 v[18:21], v[180:183], v[204:207], v[18:21]
	v_mfma_f32_16x16x32_bf16 v[6:9], v[150:153], v[212:215], v[6:9]
	v_mfma_f32_16x16x32_bf16 v[2:5], v[180:183], v[212:215], v[2:5]
	s_setprio 0
	s_barrier
	s_add_i32 s50, 0, 0x18000
	s_add_i32 s51, 0, 0x1c000
	v_add_u32_e32 v142, s50, v171
	v_add_u32_e32 v180, s51, v171
	ds_read_b128 v[130:133], v142
	ds_read_b128 v[134:137], v142 offset:1024
	ds_read_b128 v[138:141], v142 offset:2048
	ds_read_b128 v[142:145], v142 offset:3072
	ds_read_b128 v[146:149], v180
	ds_read_b128 v[150:153], v180 offset:1024
	ds_read_b128 v[164:167], v180 offset:2048
	ds_read_b128 v[180:183], v180 offset:3072
	s_add_u32 s18, s36, 0x68000
	s_addc_u32 s19, s37, 0
	s_mov_b32 m0, s42
	v_lshl_add_u64 v[222:223], s[18:19], 0, v[154:155]
	ds_read_b128 v[184:187], v179 offset:32768
	ds_read_b128 v[188:191], v179 offset:33792
	ds_read_b128 v[192:195], v179 offset:34816
	ds_read_b128 v[196:199], v179 offset:35840
	ds_read_b128 v[200:203], v179 offset:36864
	ds_read_b128 v[204:207], v179 offset:37888
	ds_read_b128 v[208:211], v179 offset:38912
	ds_read_b128 v[212:215], v179 offset:39936
	global_load_lds_dwordx4 v[222:223], off
	v_lshl_add_u64 v[222:223], s[18:19], 0, v[156:157]
	s_mov_b32 m0, s43
	s_nop 0
	global_load_lds_dwordx4 v[222:223], off
	s_waitcnt vmcnt(8)
	s_waitcnt lgkmcnt(0)
	s_barrier
	s_setprio 1
	v_mfma_f32_16x16x32_bf16 v[126:129], v[130:133], v[184:187], v[126:129]
	v_mfma_f32_16x16x32_bf16 v[122:125], v[138:141], v[184:187], v[122:125]
	v_mfma_f32_16x16x32_bf16 v[110:113], v[130:133], v[192:195], v[110:113]
	v_mfma_f32_16x16x32_bf16 v[106:109], v[138:141], v[192:195], v[106:109]
	v_mfma_f32_16x16x32_bf16 v[94:97], v[130:133], v[200:203], v[94:97]
	v_mfma_f32_16x16x32_bf16 v[90:93], v[138:141], v[200:203], v[90:93]
	v_mfma_f32_16x16x32_bf16 v[78:81], v[130:133], v[208:211], v[78:81]
	v_mfma_f32_16x16x32_bf16 v[74:77], v[138:141], v[208:211], v[74:77]
	v_mfma_f32_16x16x32_bf16 v[126:129], v[134:137], v[188:191], v[126:129]
	v_mfma_f32_16x16x32_bf16 v[122:125], v[142:145], v[188:191], v[122:125]
	v_mfma_f32_16x16x32_bf16 v[110:113], v[134:137], v[196:199], v[110:113]
	v_mfma_f32_16x16x32_bf16 v[106:109], v[142:145], v[196:199], v[106:109]
	v_mfma_f32_16x16x32_bf16 v[94:97], v[134:137], v[204:207], v[94:97]
	v_mfma_f32_16x16x32_bf16 v[90:93], v[142:145], v[204:207], v[90:93]
	v_mfma_f32_16x16x32_bf16 v[78:81], v[134:137], v[212:215], v[78:81]
	v_mfma_f32_16x16x32_bf16 v[74:77], v[142:145], v[212:215], v[74:77]
	v_mfma_f32_16x16x32_bf16 v[118:121], v[146:149], v[184:187], v[118:121]
	v_mfma_f32_16x16x32_bf16 v[114:117], v[164:167], v[184:187], v[114:117]
	v_mfma_f32_16x16x32_bf16 v[102:105], v[146:149], v[192:195], v[102:105]
	v_mfma_f32_16x16x32_bf16 v[98:101], v[164:167], v[192:195], v[98:101]
	v_mfma_f32_16x16x32_bf16 v[86:89], v[146:149], v[200:203], v[86:89]
	v_mfma_f32_16x16x32_bf16 v[82:85], v[164:167], v[200:203], v[82:85]
	v_mfma_f32_16x16x32_bf16 v[70:73], v[146:149], v[208:211], v[70:73]
	v_mfma_f32_16x16x32_bf16 v[66:69], v[164:167], v[208:211], v[66:69]
	v_mfma_f32_16x16x32_bf16 v[118:121], v[150:153], v[188:191], v[118:121]
	v_mfma_f32_16x16x32_bf16 v[114:117], v[180:183], v[188:191], v[114:117]
	v_mfma_f32_16x16x32_bf16 v[102:105], v[150:153], v[196:199], v[102:105]
	v_mfma_f32_16x16x32_bf16 v[98:101], v[180:183], v[196:199], v[98:101]
	v_mfma_f32_16x16x32_bf16 v[86:89], v[150:153], v[204:207], v[86:89]
	v_mfma_f32_16x16x32_bf16 v[82:85], v[180:183], v[204:207], v[82:85]
	v_mfma_f32_16x16x32_bf16 v[70:73], v[150:153], v[212:215], v[70:73]
	v_mfma_f32_16x16x32_bf16 v[66:69], v[180:183], v[212:215], v[66:69]
	s_setprio 0
	s_barrier
	s_add_i32 s18, s50, s38
	v_lshl_add_u64 v[168:169], v[168:169], 0, s[22:23]
	s_mov_b32 m0, s18
	ds_read_b128 v[184:187], v179 offset:49152
	ds_read_b128 v[188:191], v179 offset:50176
	ds_read_b128 v[192:195], v179 offset:51200
	ds_read_b128 v[196:199], v179 offset:52224
	ds_read_b128 v[200:203], v179 offset:53248
	ds_read_b128 v[204:207], v179 offset:54272
	ds_read_b128 v[208:211], v179 offset:55296
	ds_read_b128 v[212:215], v179 offset:56320
	global_load_lds_dwordx4 v[168:169], off
	s_add_i32 m0, s18, 0x2000
	s_add_u32 s18, s26, 0x1a080
	v_lshl_add_u64 v[168:169], v[216:217], 0, s[22:23]
	s_addc_u32 s19, s27, 0
	s_add_i32 s26, s51, s38
	global_load_lds_dwordx4 v[168:169], off
	v_lshl_add_u64 v[168:169], s[18:19], 0, v[0:1]
	s_mov_b32 m0, s26
	s_nop 0
	global_load_lds_dwordx4 v[168:169], off
	v_lshl_add_u64 v[168:169], s[18:19], 0, v[158:159]
	s_add_i32 m0, s26, 0x2000
	s_nop 0
	global_load_lds_dwordx4 v[168:169], off
	v_lshl_add_u64 v[168:169], v[218:219], 0, s[22:23]
	s_mov_b32 m0, s44
	s_nop 0
	global_load_lds_dwordx4 v[168:169], off
	v_lshl_add_u64 v[168:169], v[220:221], 0, s[22:23]
	s_mov_b32 m0, s45
	s_nop 0
	global_load_lds_dwordx4 v[168:169], off
	s_waitcnt vmcnt(8)
	s_waitcnt lgkmcnt(0)
	s_barrier
	s_setprio 1
	v_mfma_f32_16x16x32_bf16 v[62:65], v[130:133], v[184:187], v[62:65]
	v_mfma_f32_16x16x32_bf16 v[58:61], v[138:141], v[184:187], v[58:61]
	v_mfma_f32_16x16x32_bf16 v[46:49], v[130:133], v[192:195], v[46:49]
	v_mfma_f32_16x16x32_bf16 v[42:45], v[138:141], v[192:195], v[42:45]
	v_mfma_f32_16x16x32_bf16 v[30:33], v[130:133], v[200:203], v[30:33]
	v_mfma_f32_16x16x32_bf16 v[26:29], v[138:141], v[200:203], v[26:29]
	v_mfma_f32_16x16x32_bf16 v[14:17], v[130:133], v[208:211], v[14:17]
	v_mfma_f32_16x16x32_bf16 v[10:13], v[138:141], v[208:211], v[10:13]
	v_mfma_f32_16x16x32_bf16 v[62:65], v[134:137], v[188:191], v[62:65]
	v_mfma_f32_16x16x32_bf16 v[58:61], v[142:145], v[188:191], v[58:61]
	v_mfma_f32_16x16x32_bf16 v[46:49], v[134:137], v[196:199], v[46:49]
	v_mfma_f32_16x16x32_bf16 v[42:45], v[142:145], v[196:199], v[42:45]
	v_mfma_f32_16x16x32_bf16 v[30:33], v[134:137], v[204:207], v[30:33]
	v_mfma_f32_16x16x32_bf16 v[26:29], v[142:145], v[204:207], v[26:29]
	v_mfma_f32_16x16x32_bf16 v[14:17], v[134:137], v[212:215], v[14:17]
	v_mfma_f32_16x16x32_bf16 v[10:13], v[142:145], v[212:215], v[10:13]
	v_mfma_f32_16x16x32_bf16 v[54:57], v[146:149], v[184:187], v[54:57]
	v_mfma_f32_16x16x32_bf16 v[50:53], v[164:167], v[184:187], v[50:53]
	v_mfma_f32_16x16x32_bf16 v[38:41], v[146:149], v[192:195], v[38:41]
	v_mfma_f32_16x16x32_bf16 v[34:37], v[164:167], v[192:195], v[34:37]
	v_mfma_f32_16x16x32_bf16 v[22:25], v[146:149], v[200:203], v[22:25]
	v_mfma_f32_16x16x32_bf16 v[18:21], v[164:167], v[200:203], v[18:21]
	v_mfma_f32_16x16x32_bf16 v[6:9], v[146:149], v[208:211], v[6:9]
	v_mfma_f32_16x16x32_bf16 v[2:5], v[164:167], v[208:211], v[2:5]
	v_mfma_f32_16x16x32_bf16 v[54:57], v[150:153], v[188:191], v[54:57]
	v_mfma_f32_16x16x32_bf16 v[50:53], v[180:183], v[188:191], v[50:53]
	v_mfma_f32_16x16x32_bf16 v[38:41], v[150:153], v[196:199], v[38:41]
	v_mfma_f32_16x16x32_bf16 v[34:37], v[180:183], v[196:199], v[34:37]
	v_mfma_f32_16x16x32_bf16 v[22:25], v[150:153], v[204:207], v[22:25]
	v_mfma_f32_16x16x32_bf16 v[18:21], v[180:183], v[204:207], v[18:21]
	v_mfma_f32_16x16x32_bf16 v[6:9], v[150:153], v[212:215], v[6:9]
	v_mfma_f32_16x16x32_bf16 v[2:5], v[180:183], v[212:215], v[2:5]
	s_setprio 0
	s_barrier
	s_add_i32 s30, s30, 2
	s_add_u32 s2, s2, 0x100
	s_addc_u32 s3, s3, 0
	s_cmp_gt_u32 s30, 21
	s_mov_b64 s[18:19], s[20:21]
.LBB0_1612:
	s_add_u32 s20, s18, 0x100
	s_addc_u32 s21, s19, 0
	s_add_i32 s50, 0, 0x10000
	s_cmp_eq_u32 s30, 20
	s_cselect_b32 s37, s1, s21
	s_cselect_b32 s36, s0, s20
	s_cselect_b32 s27, s29, s3
	s_cselect_b32 s26, s28, s2
	s_add_i32 s51, 0, 0x14000
	v_add_u32_e32 v142, s50, v171
	v_add_u32_e32 v168, s51, v171
	s_waitcnt lgkmcnt(0)
	ds_read_b128 v[130:133], v142
	ds_read_b128 v[134:137], v142 offset:1024
	ds_read_b128 v[138:141], v142 offset:2048
	ds_read_b128 v[142:145], v142 offset:3072
	ds_read_b128 v[146:149], v168
	ds_read_b128 v[150:153], v168 offset:1024
	ds_read_b128 v[164:167], v168 offset:2048
	ds_read_b128 v[180:183], v168 offset:3072
	v_lshl_add_u64 v[168:169], s[18:19], 0, v[160:161]
	s_add_i32 m0, s40, 0xc000
	ds_read_b128 v[184:187], v179
	ds_read_b128 v[188:191], v179 offset:1024
	ds_read_b128 v[192:195], v179 offset:2048
	ds_read_b128 v[196:199], v179 offset:3072
	ds_read_b128 v[200:203], v179 offset:4096
	ds_read_b128 v[204:207], v179 offset:5120
	ds_read_b128 v[208:211], v179 offset:6144
	ds_read_b128 v[212:215], v179 offset:7168
	global_load_lds_dwordx4 v[168:169], off
	v_lshl_add_u64 v[168:169], s[18:19], 0, v[162:163]
	s_add_i32 m0, s40, 0xe000
	s_nop 0
	global_load_lds_dwordx4 v[168:169], off
	s_waitcnt vmcnt(8)
	s_waitcnt lgkmcnt(0)
	s_barrier
	s_setprio 1
	v_mfma_f32_16x16x32_bf16 v[126:129], v[130:133], v[184:187], v[126:129]
	v_mfma_f32_16x16x32_bf16 v[122:125], v[138:141], v[184:187], v[122:125]
	v_mfma_f32_16x16x32_bf16 v[110:113], v[130:133], v[192:195], v[110:113]
	v_mfma_f32_16x16x32_bf16 v[106:109], v[138:141], v[192:195], v[106:109]
	v_mfma_f32_16x16x32_bf16 v[94:97], v[130:133], v[200:203], v[94:97]
	v_mfma_f32_16x16x32_bf16 v[90:93], v[138:141], v[200:203], v[90:93]
	v_mfma_f32_16x16x32_bf16 v[78:81], v[130:133], v[208:211], v[78:81]
	v_mfma_f32_16x16x32_bf16 v[74:77], v[138:141], v[208:211], v[74:77]
	v_mfma_f32_16x16x32_bf16 v[126:129], v[134:137], v[188:191], v[126:129]
	v_mfma_f32_16x16x32_bf16 v[122:125], v[142:145], v[188:191], v[122:125]
	v_mfma_f32_16x16x32_bf16 v[110:113], v[134:137], v[196:199], v[110:113]
	v_mfma_f32_16x16x32_bf16 v[106:109], v[142:145], v[196:199], v[106:109]
	v_mfma_f32_16x16x32_bf16 v[94:97], v[134:137], v[204:207], v[94:97]
	v_mfma_f32_16x16x32_bf16 v[90:93], v[142:145], v[204:207], v[90:93]
	v_mfma_f32_16x16x32_bf16 v[78:81], v[134:137], v[212:215], v[78:81]
	v_mfma_f32_16x16x32_bf16 v[74:77], v[142:145], v[212:215], v[74:77]
	v_mfma_f32_16x16x32_bf16 v[118:121], v[146:149], v[184:187], v[118:121]
	v_mfma_f32_16x16x32_bf16 v[114:117], v[164:167], v[184:187], v[114:117]
	v_mfma_f32_16x16x32_bf16 v[102:105], v[146:149], v[192:195], v[102:105]
	v_mfma_f32_16x16x32_bf16 v[98:101], v[164:167], v[192:195], v[98:101]
	v_mfma_f32_16x16x32_bf16 v[86:89], v[146:149], v[200:203], v[86:89]
	v_mfma_f32_16x16x32_bf16 v[82:85], v[164:167], v[200:203], v[82:85]
	v_mfma_f32_16x16x32_bf16 v[70:73], v[146:149], v[208:211], v[70:73]
	v_mfma_f32_16x16x32_bf16 v[66:69], v[164:167], v[208:211], v[66:69]
	v_mfma_f32_16x16x32_bf16 v[118:121], v[150:153], v[188:191], v[118:121]
	v_mfma_f32_16x16x32_bf16 v[114:117], v[180:183], v[188:191], v[114:117]
	v_mfma_f32_16x16x32_bf16 v[102:105], v[150:153], v[196:199], v[102:105]
	v_mfma_f32_16x16x32_bf16 v[98:101], v[180:183], v[196:199], v[98:101]
	v_mfma_f32_16x16x32_bf16 v[86:89], v[150:153], v[204:207], v[86:89]
	v_mfma_f32_16x16x32_bf16 v[82:85], v[180:183], v[204:207], v[82:85]
	v_mfma_f32_16x16x32_bf16 v[70:73], v[150:153], v[212:215], v[70:73]
	v_mfma_f32_16x16x32_bf16 v[66:69], v[180:183], v[212:215], v[66:69]
	s_setprio 0
	s_barrier
	s_add_i32 s18, s50, s38
	v_lshl_add_u64 v[168:169], s[26:27], 0, v[0:1]
	s_mov_b32 m0, s18
	ds_read_b128 v[184:187], v179 offset:16384
	ds_read_b128 v[188:191], v179 offset:17408
	ds_read_b128 v[192:195], v179 offset:18432
	ds_read_b128 v[196:199], v179 offset:19456
	ds_read_b128 v[200:203], v179 offset:20480
	ds_read_b128 v[204:207], v179 offset:21504
	ds_read_b128 v[208:211], v179 offset:22528
	ds_read_b128 v[212:215], v179 offset:23552
	global_load_lds_dwordx4 v[168:169], off
	s_add_i32 m0, s18, 0x2000
	s_add_u32 s18, s26, 0x1a000
	v_lshl_add_u64 v[216:217], s[26:27], 0, v[158:159]
	s_addc_u32 s19, s27, 0
	s_add_i32 s50, s51, s38
	global_load_lds_dwordx4 v[216:217], off
	v_lshl_add_u64 v[218:219], s[18:19], 0, v[0:1]
	s_mov_b32 m0, s50
	v_lshl_add_u64 v[220:221], s[36:37], 0, v[156:157]
	global_load_lds_dwordx4 v[218:219], off
	v_lshl_add_u64 v[218:219], s[18:19], 0, v[158:159]
	s_add_i32 m0, s50, 0x2000
	s_nop 0
	global_load_lds_dwordx4 v[218:219], off
	v_lshl_add_u64 v[218:219], s[36:37], 0, v[154:155]
	s_mov_b32 m0, s40
	s_nop 0
	global_load_lds_dwordx4 v[218:219], off
	s_mov_b32 m0, s41
	s_nop 0
	global_load_lds_dwordx4 v[220:221], off
	s_waitcnt vmcnt(8)
	s_waitcnt lgkmcnt(0)
	s_barrier
	s_setprio 1
	v_mfma_f32_16x16x32_bf16 v[62:65], v[130:133], v[184:187], v[62:65]
	v_mfma_f32_16x16x32_bf16 v[58:61], v[138:141], v[184:187], v[58:61]
	v_mfma_f32_16x16x32_bf16 v[46:49], v[130:133], v[192:195], v[46:49]
	v_mfma_f32_16x16x32_bf16 v[42:45], v[138:141], v[192:195], v[42:45]
	v_mfma_f32_16x16x32_bf16 v[30:33], v[130:133], v[200:203], v[30:33]
	v_mfma_f32_16x16x32_bf16 v[26:29], v[138:141], v[200:203], v[26:29]
	v_mfma_f32_16x16x32_bf16 v[14:17], v[130:133], v[208:211], v[14:17]
	v_mfma_f32_16x16x32_bf16 v[10:13], v[138:141], v[208:211], v[10:13]
	v_mfma_f32_16x16x32_bf16 v[62:65], v[134:137], v[188:191], v[62:65]
	v_mfma_f32_16x16x32_bf16 v[58:61], v[142:145], v[188:191], v[58:61]
	v_mfma_f32_16x16x32_bf16 v[46:49], v[134:137], v[196:199], v[46:49]
	v_mfma_f32_16x16x32_bf16 v[42:45], v[142:145], v[196:199], v[42:45]
	v_mfma_f32_16x16x32_bf16 v[30:33], v[134:137], v[204:207], v[30:33]
	v_mfma_f32_16x16x32_bf16 v[26:29], v[142:145], v[204:207], v[26:29]
	v_mfma_f32_16x16x32_bf16 v[14:17], v[134:137], v[212:215], v[14:17]
	v_mfma_f32_16x16x32_bf16 v[10:13], v[142:145], v[212:215], v[10:13]
	v_mfma_f32_16x16x32_bf16 v[54:57], v[146:149], v[184:187], v[54:57]
	v_mfma_f32_16x16x32_bf16 v[50:53], v[164:167], v[184:187], v[50:53]
	v_mfma_f32_16x16x32_bf16 v[38:41], v[146:149], v[192:195], v[38:41]
	v_mfma_f32_16x16x32_bf16 v[34:37], v[164:167], v[192:195], v[34:37]
	v_mfma_f32_16x16x32_bf16 v[22:25], v[146:149], v[200:203], v[22:25]
	v_mfma_f32_16x16x32_bf16 v[18:21], v[164:167], v[200:203], v[18:21]
	v_mfma_f32_16x16x32_bf16 v[6:9], v[146:149], v[208:211], v[6:9]
	v_mfma_f32_16x16x32_bf16 v[2:5], v[164:167], v[208:211], v[2:5]
	v_mfma_f32_16x16x32_bf16 v[54:57], v[150:153], v[188:191], v[54:57]
	v_mfma_f32_16x16x32_bf16 v[50:53], v[180:183], v[188:191], v[50:53]
	v_mfma_f32_16x16x32_bf16 v[38:41], v[150:153], v[196:199], v[38:41]
	v_mfma_f32_16x16x32_bf16 v[34:37], v[180:183], v[196:199], v[34:37]
	v_mfma_f32_16x16x32_bf16 v[22:25], v[150:153], v[204:207], v[22:25]
	v_mfma_f32_16x16x32_bf16 v[18:21], v[180:183], v[204:207], v[18:21]
	v_mfma_f32_16x16x32_bf16 v[6:9], v[150:153], v[212:215], v[6:9]
	v_mfma_f32_16x16x32_bf16 v[2:5], v[180:183], v[212:215], v[2:5]
	s_setprio 0
	s_barrier
	s_add_i32 s50, 0, 0x18000
	s_add_i32 s51, 0, 0x1c000
	v_add_u32_e32 v142, s50, v171
	v_add_u32_e32 v180, s51, v171
	ds_read_b128 v[130:133], v142
	ds_read_b128 v[134:137], v142 offset:1024
	ds_read_b128 v[138:141], v142 offset:2048
	ds_read_b128 v[142:145], v142 offset:3072
	ds_read_b128 v[146:149], v180
	ds_read_b128 v[150:153], v180 offset:1024
	ds_read_b128 v[164:167], v180 offset:2048
	ds_read_b128 v[180:183], v180 offset:3072
	s_add_u32 s18, s36, 0x68000
	s_addc_u32 s19, s37, 0
	s_mov_b32 m0, s42
	v_lshl_add_u64 v[222:223], s[18:19], 0, v[154:155]
	ds_read_b128 v[184:187], v179 offset:32768
	ds_read_b128 v[188:191], v179 offset:33792
	ds_read_b128 v[192:195], v179 offset:34816
	ds_read_b128 v[196:199], v179 offset:35840
	ds_read_b128 v[200:203], v179 offset:36864
	ds_read_b128 v[204:207], v179 offset:37888
	ds_read_b128 v[208:211], v179 offset:38912
	ds_read_b128 v[212:215], v179 offset:39936
	global_load_lds_dwordx4 v[222:223], off
	v_lshl_add_u64 v[222:223], s[18:19], 0, v[156:157]
	s_mov_b32 m0, s43
	s_nop 0
	global_load_lds_dwordx4 v[222:223], off
	s_waitcnt vmcnt(8)
	s_waitcnt lgkmcnt(0)
	s_barrier
	s_setprio 1
	v_mfma_f32_16x16x32_bf16 v[126:129], v[130:133], v[184:187], v[126:129]
	v_mfma_f32_16x16x32_bf16 v[122:125], v[138:141], v[184:187], v[122:125]
	v_mfma_f32_16x16x32_bf16 v[110:113], v[130:133], v[192:195], v[110:113]
	v_mfma_f32_16x16x32_bf16 v[106:109], v[138:141], v[192:195], v[106:109]
	v_mfma_f32_16x16x32_bf16 v[94:97], v[130:133], v[200:203], v[94:97]
	v_mfma_f32_16x16x32_bf16 v[90:93], v[138:141], v[200:203], v[90:93]
	v_mfma_f32_16x16x32_bf16 v[78:81], v[130:133], v[208:211], v[78:81]
	v_mfma_f32_16x16x32_bf16 v[74:77], v[138:141], v[208:211], v[74:77]
	v_mfma_f32_16x16x32_bf16 v[126:129], v[134:137], v[188:191], v[126:129]
	v_mfma_f32_16x16x32_bf16 v[122:125], v[142:145], v[188:191], v[122:125]
	v_mfma_f32_16x16x32_bf16 v[110:113], v[134:137], v[196:199], v[110:113]
	v_mfma_f32_16x16x32_bf16 v[106:109], v[142:145], v[196:199], v[106:109]
	v_mfma_f32_16x16x32_bf16 v[94:97], v[134:137], v[204:207], v[94:97]
	v_mfma_f32_16x16x32_bf16 v[90:93], v[142:145], v[204:207], v[90:93]
	v_mfma_f32_16x16x32_bf16 v[78:81], v[134:137], v[212:215], v[78:81]
	v_mfma_f32_16x16x32_bf16 v[74:77], v[142:145], v[212:215], v[74:77]
	v_mfma_f32_16x16x32_bf16 v[118:121], v[146:149], v[184:187], v[118:121]
	v_mfma_f32_16x16x32_bf16 v[114:117], v[164:167], v[184:187], v[114:117]
	v_mfma_f32_16x16x32_bf16 v[102:105], v[146:149], v[192:195], v[102:105]
	v_mfma_f32_16x16x32_bf16 v[98:101], v[164:167], v[192:195], v[98:101]
	v_mfma_f32_16x16x32_bf16 v[86:89], v[146:149], v[200:203], v[86:89]
	v_mfma_f32_16x16x32_bf16 v[82:85], v[164:167], v[200:203], v[82:85]
	v_mfma_f32_16x16x32_bf16 v[70:73], v[146:149], v[208:211], v[70:73]
	v_mfma_f32_16x16x32_bf16 v[66:69], v[164:167], v[208:211], v[66:69]
	v_mfma_f32_16x16x32_bf16 v[118:121], v[150:153], v[188:191], v[118:121]
	v_mfma_f32_16x16x32_bf16 v[114:117], v[180:183], v[188:191], v[114:117]
	v_mfma_f32_16x16x32_bf16 v[102:105], v[150:153], v[196:199], v[102:105]
	v_mfma_f32_16x16x32_bf16 v[98:101], v[180:183], v[196:199], v[98:101]
	v_mfma_f32_16x16x32_bf16 v[86:89], v[150:153], v[204:207], v[86:89]
	v_mfma_f32_16x16x32_bf16 v[82:85], v[180:183], v[204:207], v[82:85]
	v_mfma_f32_16x16x32_bf16 v[70:73], v[150:153], v[212:215], v[70:73]
	v_mfma_f32_16x16x32_bf16 v[66:69], v[180:183], v[212:215], v[66:69]
	s_setprio 0
	s_barrier
	s_add_i32 s18, s50, s38
	v_lshl_add_u64 v[168:169], v[168:169], 0, s[22:23]
	s_mov_b32 m0, s18
	ds_read_b128 v[184:187], v179 offset:49152
	ds_read_b128 v[188:191], v179 offset:50176
	ds_read_b128 v[192:195], v179 offset:51200
	ds_read_b128 v[196:199], v179 offset:52224
	ds_read_b128 v[200:203], v179 offset:53248
	ds_read_b128 v[204:207], v179 offset:54272
	ds_read_b128 v[208:211], v179 offset:55296
	ds_read_b128 v[212:215], v179 offset:56320
	global_load_lds_dwordx4 v[168:169], off
	s_add_i32 m0, s18, 0x2000
	s_add_u32 s18, s26, 0x1a080
	v_lshl_add_u64 v[168:169], v[216:217], 0, s[22:23]
	s_addc_u32 s19, s27, 0
	s_add_i32 s26, s51, s38
	global_load_lds_dwordx4 v[168:169], off
	v_lshl_add_u64 v[168:169], s[18:19], 0, v[0:1]
	s_mov_b32 m0, s26
	s_nop 0
	global_load_lds_dwordx4 v[168:169], off
	v_lshl_add_u64 v[168:169], s[18:19], 0, v[158:159]
	s_add_i32 m0, s26, 0x2000
	s_nop 0
	global_load_lds_dwordx4 v[168:169], off
	v_lshl_add_u64 v[168:169], v[218:219], 0, s[22:23]
	s_mov_b32 m0, s44
	s_nop 0
	global_load_lds_dwordx4 v[168:169], off
	v_lshl_add_u64 v[168:169], v[220:221], 0, s[22:23]
	s_mov_b32 m0, s45
	s_nop 0
	global_load_lds_dwordx4 v[168:169], off
	s_waitcnt vmcnt(8)
	s_waitcnt lgkmcnt(0)
	s_barrier
	s_setprio 1
	v_mfma_f32_16x16x32_bf16 v[62:65], v[130:133], v[184:187], v[62:65]
	v_mfma_f32_16x16x32_bf16 v[58:61], v[138:141], v[184:187], v[58:61]
	v_mfma_f32_16x16x32_bf16 v[46:49], v[130:133], v[192:195], v[46:49]
	v_mfma_f32_16x16x32_bf16 v[42:45], v[138:141], v[192:195], v[42:45]
	v_mfma_f32_16x16x32_bf16 v[30:33], v[130:133], v[200:203], v[30:33]
	v_mfma_f32_16x16x32_bf16 v[26:29], v[138:141], v[200:203], v[26:29]
	v_mfma_f32_16x16x32_bf16 v[14:17], v[130:133], v[208:211], v[14:17]
	v_mfma_f32_16x16x32_bf16 v[10:13], v[138:141], v[208:211], v[10:13]
	v_mfma_f32_16x16x32_bf16 v[62:65], v[134:137], v[188:191], v[62:65]
	v_mfma_f32_16x16x32_bf16 v[58:61], v[142:145], v[188:191], v[58:61]
	v_mfma_f32_16x16x32_bf16 v[46:49], v[134:137], v[196:199], v[46:49]
	v_mfma_f32_16x16x32_bf16 v[42:45], v[142:145], v[196:199], v[42:45]
	v_mfma_f32_16x16x32_bf16 v[30:33], v[134:137], v[204:207], v[30:33]
	v_mfma_f32_16x16x32_bf16 v[26:29], v[142:145], v[204:207], v[26:29]
	v_mfma_f32_16x16x32_bf16 v[14:17], v[134:137], v[212:215], v[14:17]
	v_mfma_f32_16x16x32_bf16 v[10:13], v[142:145], v[212:215], v[10:13]
	v_mfma_f32_16x16x32_bf16 v[54:57], v[146:149], v[184:187], v[54:57]
	v_mfma_f32_16x16x32_bf16 v[50:53], v[164:167], v[184:187], v[50:53]
	v_mfma_f32_16x16x32_bf16 v[38:41], v[146:149], v[192:195], v[38:41]
	v_mfma_f32_16x16x32_bf16 v[34:37], v[164:167], v[192:195], v[34:37]
	v_mfma_f32_16x16x32_bf16 v[22:25], v[146:149], v[200:203], v[22:25]
	v_mfma_f32_16x16x32_bf16 v[18:21], v[164:167], v[200:203], v[18:21]
	v_mfma_f32_16x16x32_bf16 v[6:9], v[146:149], v[208:211], v[6:9]
	v_mfma_f32_16x16x32_bf16 v[2:5], v[164:167], v[208:211], v[2:5]
	v_mfma_f32_16x16x32_bf16 v[54:57], v[150:153], v[188:191], v[54:57]
	v_mfma_f32_16x16x32_bf16 v[50:53], v[180:183], v[188:191], v[50:53]
	v_mfma_f32_16x16x32_bf16 v[38:41], v[150:153], v[196:199], v[38:41]
	v_mfma_f32_16x16x32_bf16 v[34:37], v[180:183], v[196:199], v[34:37]
	v_mfma_f32_16x16x32_bf16 v[22:25], v[150:153], v[204:207], v[22:25]
	v_mfma_f32_16x16x32_bf16 v[18:21], v[180:183], v[204:207], v[18:21]
	v_mfma_f32_16x16x32_bf16 v[6:9], v[150:153], v[212:215], v[6:9]
	v_mfma_f32_16x16x32_bf16 v[2:5], v[180:183], v[212:215], v[2:5]
	s_setprio 0
	s_barrier
	s_add_i32 s30, s30, 2
	s_add_u32 s2, s2, 0x100
	s_addc_u32 s3, s3, 0
	s_cmp_gt_u32 s30, 21
	s_mov_b64 s[18:19], s[20:21]
	s_cbranch_scc0 .LBB0_1612
	s_and_b64 vcc, exec, s[12:13]
	s_cbranch_vccz .LBB0_1615
	s_barrier

.LBB0_1737:
	s_add_u32 s2, s16, 0x100
	s_addc_u32 s3, s17, 0
	s_mov_b32 s41, -2
	s_add_u32 s0, s14, 0x100
	s_addc_u32 s1, s15, 0
	s_add_i32 s42, 0, 0x10000
	s_cmp_eq_u32 s41, 28
	s_cselect_b32 s19, s11, s1
	s_cselect_b32 s18, s10, s0
	s_cselect_b32 s17, s13, s3
	s_cselect_b32 s16, s12, s2
	s_add_i32 s43, 0, 0x14000
	v_add_u32_e32 v154, s42, v171
	v_add_u32_e32 v175, s43, v171
	ds_read_b128 v[130:133], v154
	ds_read_b128 v[134:137], v154 offset:1024
	ds_read_b128 v[150:153], v154 offset:2048
	ds_read_b128 v[154:157], v154 offset:3072
	ds_read_b128 v[158:161], v175
	ds_read_b128 v[162:165], v175 offset:1024
	ds_read_b128 v[166:169], v175 offset:2048
	ds_read_b128 v[176:179], v175 offset:3072
	v_lshl_add_u64 v[212:213], s[14:15], 0, v[146:147]
	s_add_i32 m0, s24, 0xc000
	ds_read_b128 v[180:183], v174
	ds_read_b128 v[184:187], v174 offset:1024
	ds_read_b128 v[188:191], v174 offset:2048
	ds_read_b128 v[192:195], v174 offset:3072
	ds_read_b128 v[196:199], v174 offset:4096
	ds_read_b128 v[200:203], v174 offset:5120
	ds_read_b128 v[204:207], v174 offset:6144
	ds_read_b128 v[208:211], v174 offset:7168
	global_load_lds_dwordx4 v[212:213], off
	v_lshl_add_u64 v[212:213], s[14:15], 0, v[148:149]
	s_add_i32 m0, s24, 0xe000
	s_nop 0
	global_load_lds_dwordx4 v[212:213], off
	s_waitcnt vmcnt(8)
	s_waitcnt lgkmcnt(0)
	s_barrier
	s_setprio 1
	v_mfma_f32_16x16x32_bf16 v[126:129], v[130:133], v[180:183], 0
	v_mfma_f32_16x16x32_bf16 v[118:121], v[150:153], v[180:183], 0
	v_mfma_f32_16x16x32_bf16 v[110:113], v[130:133], v[188:191], 0
	v_mfma_f32_16x16x32_bf16 v[102:105], v[150:153], v[188:191], 0
	v_mfma_f32_16x16x32_bf16 v[94:97], v[130:133], v[196:199], 0
	v_mfma_f32_16x16x32_bf16 v[86:89], v[150:153], v[196:199], 0
	v_mfma_f32_16x16x32_bf16 v[78:81], v[130:133], v[204:207], 0
	v_mfma_f32_16x16x32_bf16 v[70:73], v[150:153], v[204:207], 0
	v_mfma_f32_16x16x32_bf16 v[126:129], v[134:137], v[184:187], v[126:129]
	v_mfma_f32_16x16x32_bf16 v[118:121], v[154:157], v[184:187], v[118:121]
	v_mfma_f32_16x16x32_bf16 v[110:113], v[134:137], v[192:195], v[110:113]
	v_mfma_f32_16x16x32_bf16 v[102:105], v[154:157], v[192:195], v[102:105]
	v_mfma_f32_16x16x32_bf16 v[94:97], v[134:137], v[200:203], v[94:97]
	v_mfma_f32_16x16x32_bf16 v[86:89], v[154:157], v[200:203], v[86:89]
	v_mfma_f32_16x16x32_bf16 v[78:81], v[134:137], v[208:211], v[78:81]
	v_mfma_f32_16x16x32_bf16 v[70:73], v[154:157], v[208:211], v[70:73]
	v_mfma_f32_16x16x32_bf16 v[122:125], v[158:161], v[180:183], 0
	v_mfma_f32_16x16x32_bf16 v[114:117], v[166:169], v[180:183], 0
	v_mfma_f32_16x16x32_bf16 v[106:109], v[158:161], v[188:191], 0
	v_mfma_f32_16x16x32_bf16 v[98:101], v[166:169], v[188:191], 0
	v_mfma_f32_16x16x32_bf16 v[90:93], v[158:161], v[196:199], 0
	v_mfma_f32_16x16x32_bf16 v[82:85], v[166:169], v[196:199], 0
	v_mfma_f32_16x16x32_bf16 v[74:77], v[158:161], v[204:207], 0
	v_mfma_f32_16x16x32_bf16 v[66:69], v[166:169], v[204:207], 0
	v_mfma_f32_16x16x32_bf16 v[122:125], v[162:165], v[184:187], v[122:125]
	v_mfma_f32_16x16x32_bf16 v[114:117], v[176:179], v[184:187], v[114:117]
	v_mfma_f32_16x16x32_bf16 v[106:109], v[162:165], v[192:195], v[106:109]
	v_mfma_f32_16x16x32_bf16 v[98:101], v[176:179], v[192:195], v[98:101]
	v_mfma_f32_16x16x32_bf16 v[90:93], v[162:165], v[200:203], v[90:93]
	v_mfma_f32_16x16x32_bf16 v[82:85], v[176:179], v[200:203], v[82:85]
	v_mfma_f32_16x16x32_bf16 v[74:77], v[162:165], v[208:211], v[74:77]
	v_mfma_f32_16x16x32_bf16 v[66:69], v[176:179], v[208:211], v[66:69]
	s_setprio 0
	s_barrier
	s_add_i32 s14, s42, s20
	v_lshl_add_u64 v[212:213], s[16:17], 0, v[0:1]
	s_mov_b32 m0, s14
	ds_read_b128 v[180:183], v174 offset:16384
	ds_read_b128 v[184:187], v174 offset:17408
	ds_read_b128 v[188:191], v174 offset:18432
	ds_read_b128 v[192:195], v174 offset:19456
	ds_read_b128 v[196:199], v174 offset:20480
	ds_read_b128 v[200:203], v174 offset:21504
	ds_read_b128 v[204:207], v174 offset:22528
	ds_read_b128 v[208:211], v174 offset:23552
	global_load_lds_dwordx4 v[212:213], off
	s_add_i32 m0, s14, 0x2000
	s_add_u32 s14, s16, 0x88000
	v_lshl_add_u64 v[214:215], s[16:17], 0, v[138:139]
	s_addc_u32 s15, s17, 0
	s_add_i32 s42, s43, s20
	global_load_lds_dwordx4 v[214:215], off
	v_lshl_add_u64 v[216:217], s[14:15], 0, v[0:1]
	s_mov_b32 m0, s42
	v_lshl_add_u64 v[218:219], s[18:19], 0, v[140:141]
	global_load_lds_dwordx4 v[216:217], off
	v_lshl_add_u64 v[216:217], s[14:15], 0, v[138:139]
	s_add_i32 m0, s42, 0x2000
	s_nop 0
	global_load_lds_dwordx4 v[216:217], off
	v_lshl_add_u64 v[216:217], s[18:19], 0, v[142:143]
	s_mov_b32 m0, s24
	s_nop 0
	global_load_lds_dwordx4 v[216:217], off
	s_mov_b32 m0, s26
	s_nop 0
	global_load_lds_dwordx4 v[218:219], off
	s_waitcnt vmcnt(8)
	s_waitcnt lgkmcnt(0)
	s_barrier
	s_setprio 1
	v_mfma_f32_16x16x32_bf16 v[62:65], v[130:133], v[180:183], 0
	v_mfma_f32_16x16x32_bf16 v[54:57], v[150:153], v[180:183], 0
	v_mfma_f32_16x16x32_bf16 v[46:49], v[130:133], v[188:191], 0
	v_mfma_f32_16x16x32_bf16 v[38:41], v[150:153], v[188:191], 0
	v_mfma_f32_16x16x32_bf16 v[30:33], v[130:133], v[196:199], 0
	v_mfma_f32_16x16x32_bf16 v[22:25], v[150:153], v[196:199], 0
	v_mfma_f32_16x16x32_bf16 v[14:17], v[130:133], v[204:207], 0
	v_mfma_f32_16x16x32_bf16 v[6:9], v[150:153], v[204:207], 0
	v_mfma_f32_16x16x32_bf16 v[62:65], v[134:137], v[184:187], v[62:65]
	v_mfma_f32_16x16x32_bf16 v[54:57], v[154:157], v[184:187], v[54:57]
	v_mfma_f32_16x16x32_bf16 v[46:49], v[134:137], v[192:195], v[46:49]
	v_mfma_f32_16x16x32_bf16 v[38:41], v[154:157], v[192:195], v[38:41]
	v_mfma_f32_16x16x32_bf16 v[30:33], v[134:137], v[200:203], v[30:33]
	v_mfma_f32_16x16x32_bf16 v[22:25], v[154:157], v[200:203], v[22:25]
	v_mfma_f32_16x16x32_bf16 v[14:17], v[134:137], v[208:211], v[14:17]
	v_mfma_f32_16x16x32_bf16 v[6:9], v[154:157], v[208:211], v[6:9]
	v_mfma_f32_16x16x32_bf16 v[58:61], v[158:161], v[180:183], 0
	v_mfma_f32_16x16x32_bf16 v[50:53], v[166:169], v[180:183], 0
	v_mfma_f32_16x16x32_bf16 v[42:45], v[158:161], v[188:191], 0
	v_mfma_f32_16x16x32_bf16 v[34:37], v[166:169], v[188:191], 0
	v_mfma_f32_16x16x32_bf16 v[26:29], v[158:161], v[196:199], 0
	v_mfma_f32_16x16x32_bf16 v[18:21], v[166:169], v[196:199], 0
	v_mfma_f32_16x16x32_bf16 v[10:13], v[158:161], v[204:207], 0
	v_mfma_f32_16x16x32_bf16 v[2:5], v[166:169], v[204:207], 0
	v_mfma_f32_16x16x32_bf16 v[58:61], v[162:165], v[184:187], v[58:61]
	v_mfma_f32_16x16x32_bf16 v[50:53], v[176:179], v[184:187], v[50:53]
	v_mfma_f32_16x16x32_bf16 v[42:45], v[162:165], v[192:195], v[42:45]
	v_mfma_f32_16x16x32_bf16 v[34:37], v[176:179], v[192:195], v[34:37]
	v_mfma_f32_16x16x32_bf16 v[26:29], v[162:165], v[200:203], v[26:29]
	v_mfma_f32_16x16x32_bf16 v[18:21], v[176:179], v[200:203], v[18:21]
	v_mfma_f32_16x16x32_bf16 v[10:13], v[162:165], v[208:211], v[10:13]
	v_mfma_f32_16x16x32_bf16 v[2:5], v[176:179], v[208:211], v[2:5]
	s_setprio 0
	s_barrier
	s_add_i32 s42, 0, 0x18000
	s_add_i32 s43, 0, 0x1c000
	v_add_u32_e32 v154, s42, v171
	v_add_u32_e32 v175, s43, v171
	ds_read_b128 v[130:133], v154
	ds_read_b128 v[134:137], v154 offset:1024
	ds_read_b128 v[150:153], v154 offset:2048
	ds_read_b128 v[154:157], v154 offset:3072
	ds_read_b128 v[158:161], v175
	ds_read_b128 v[162:165], v175 offset:1024
	ds_read_b128 v[166:169], v175 offset:2048
	ds_read_b128 v[176:179], v175 offset:3072
	s_add_u32 s14, s18, 0x88000
	s_addc_u32 s15, s19, 0
	s_mov_b32 m0, s27
	v_lshl_add_u64 v[220:221], s[14:15], 0, v[142:143]
	ds_read_b128 v[180:183], v174 offset:32768
	ds_read_b128 v[184:187], v174 offset:33792
	ds_read_b128 v[188:191], v174 offset:34816
	ds_read_b128 v[192:195], v174 offset:35840
	ds_read_b128 v[196:199], v174 offset:36864
	ds_read_b128 v[200:203], v174 offset:37888
	ds_read_b128 v[204:207], v174 offset:38912
	ds_read_b128 v[208:211], v174 offset:39936
	global_load_lds_dwordx4 v[220:221], off
	v_lshl_add_u64 v[220:221], s[14:15], 0, v[140:141]
	s_mov_b32 m0, s28
	s_nop 0
	global_load_lds_dwordx4 v[220:221], off
	s_waitcnt vmcnt(8)
	s_waitcnt lgkmcnt(0)
	s_barrier
	s_setprio 1
	v_mfma_f32_16x16x32_bf16 v[126:129], v[130:133], v[180:183], v[126:129]
	v_mfma_f32_16x16x32_bf16 v[118:121], v[150:153], v[180:183], v[118:121]
	v_mfma_f32_16x16x32_bf16 v[110:113], v[130:133], v[188:191], v[110:113]
	v_mfma_f32_16x16x32_bf16 v[102:105], v[150:153], v[188:191], v[102:105]
	v_mfma_f32_16x16x32_bf16 v[94:97], v[130:133], v[196:199], v[94:97]
	v_mfma_f32_16x16x32_bf16 v[86:89], v[150:153], v[196:199], v[86:89]
	v_mfma_f32_16x16x32_bf16 v[78:81], v[130:133], v[204:207], v[78:81]
	v_mfma_f32_16x16x32_bf16 v[70:73], v[150:153], v[204:207], v[70:73]
	v_mfma_f32_16x16x32_bf16 v[126:129], v[134:137], v[184:187], v[126:129]
	v_mfma_f32_16x16x32_bf16 v[118:121], v[154:157], v[184:187], v[118:121]
	v_mfma_f32_16x16x32_bf16 v[110:113], v[134:137], v[192:195], v[110:113]
	v_mfma_f32_16x16x32_bf16 v[102:105], v[154:157], v[192:195], v[102:105]
	v_mfma_f32_16x16x32_bf16 v[94:97], v[134:137], v[200:203], v[94:97]
	v_mfma_f32_16x16x32_bf16 v[86:89], v[154:157], v[200:203], v[86:89]
	v_mfma_f32_16x16x32_bf16 v[78:81], v[134:137], v[208:211], v[78:81]
	v_mfma_f32_16x16x32_bf16 v[70:73], v[154:157], v[208:211], v[70:73]
	v_mfma_f32_16x16x32_bf16 v[122:125], v[158:161], v[180:183], v[122:125]
	v_mfma_f32_16x16x32_bf16 v[114:117], v[166:169], v[180:183], v[114:117]
	v_mfma_f32_16x16x32_bf16 v[106:109], v[158:161], v[188:191], v[106:109]
	v_mfma_f32_16x16x32_bf16 v[98:101], v[166:169], v[188:191], v[98:101]
	v_mfma_f32_16x16x32_bf16 v[90:93], v[158:161], v[196:199], v[90:93]
	v_mfma_f32_16x16x32_bf16 v[82:85], v[166:169], v[196:199], v[82:85]
	v_mfma_f32_16x16x32_bf16 v[74:77], v[158:161], v[204:207], v[74:77]
	v_mfma_f32_16x16x32_bf16 v[66:69], v[166:169], v[204:207], v[66:69]
	v_mfma_f32_16x16x32_bf16 v[122:125], v[162:165], v[184:187], v[122:125]
	v_mfma_f32_16x16x32_bf16 v[114:117], v[176:179], v[184:187], v[114:117]
	v_mfma_f32_16x16x32_bf16 v[106:109], v[162:165], v[192:195], v[106:109]
	v_mfma_f32_16x16x32_bf16 v[98:101], v[176:179], v[192:195], v[98:101]
	v_mfma_f32_16x16x32_bf16 v[90:93], v[162:165], v[200:203], v[90:93]
	v_mfma_f32_16x16x32_bf16 v[82:85], v[176:179], v[200:203], v[82:85]
	v_mfma_f32_16x16x32_bf16 v[74:77], v[162:165], v[208:211], v[74:77]
	v_mfma_f32_16x16x32_bf16 v[66:69], v[176:179], v[208:211], v[66:69]
	s_setprio 0
	s_barrier
	s_add_i32 s14, s42, s20
	v_lshl_add_u64 v[212:213], v[212:213], 0, s[22:23]
	s_mov_b32 m0, s14
	ds_read_b128 v[180:183], v174 offset:49152
	ds_read_b128 v[184:187], v174 offset:50176
	ds_read_b128 v[188:191], v174 offset:51200
	ds_read_b128 v[192:195], v174 offset:52224
	ds_read_b128 v[196:199], v174 offset:53248
	ds_read_b128 v[200:203], v174 offset:54272
	ds_read_b128 v[204:207], v174 offset:55296
	ds_read_b128 v[208:211], v174 offset:56320
	global_load_lds_dwordx4 v[212:213], off
	s_add_i32 m0, s14, 0x2000
	s_add_u32 s14, s16, 0x88080
	v_lshl_add_u64 v[212:213], v[214:215], 0, s[22:23]
	s_addc_u32 s15, s17, 0
	s_add_i32 s16, s43, s20
	global_load_lds_dwordx4 v[212:213], off
	v_lshl_add_u64 v[212:213], s[14:15], 0, v[0:1]
	s_mov_b32 m0, s16
	s_nop 0
	global_load_lds_dwordx4 v[212:213], off
	v_lshl_add_u64 v[212:213], s[14:15], 0, v[138:139]
	s_add_i32 m0, s16, 0x2000
	s_nop 0
	global_load_lds_dwordx4 v[212:213], off
	v_lshl_add_u64 v[212:213], v[216:217], 0, s[22:23]
	s_mov_b32 m0, s33
	s_nop 0
	global_load_lds_dwordx4 v[212:213], off
	v_lshl_add_u64 v[212:213], v[218:219], 0, s[22:23]
	s_mov_b32 m0, s36
	s_nop 0
	global_load_lds_dwordx4 v[212:213], off
	s_waitcnt vmcnt(8)
	s_waitcnt lgkmcnt(0)
	s_barrier
	s_setprio 1
	v_mfma_f32_16x16x32_bf16 v[62:65], v[130:133], v[180:183], v[62:65]
	v_mfma_f32_16x16x32_bf16 v[54:57], v[150:153], v[180:183], v[54:57]
	v_mfma_f32_16x16x32_bf16 v[46:49], v[130:133], v[188:191], v[46:49]
	v_mfma_f32_16x16x32_bf16 v[38:41], v[150:153], v[188:191], v[38:41]
	v_mfma_f32_16x16x32_bf16 v[30:33], v[130:133], v[196:199], v[30:33]
	v_mfma_f32_16x16x32_bf16 v[22:25], v[150:153], v[196:199], v[22:25]
	v_mfma_f32_16x16x32_bf16 v[14:17], v[130:133], v[204:207], v[14:17]
	v_mfma_f32_16x16x32_bf16 v[6:9], v[150:153], v[204:207], v[6:9]
	v_mfma_f32_16x16x32_bf16 v[62:65], v[134:137], v[184:187], v[62:65]
	v_mfma_f32_16x16x32_bf16 v[54:57], v[154:157], v[184:187], v[54:57]
	v_mfma_f32_16x16x32_bf16 v[46:49], v[134:137], v[192:195], v[46:49]
	v_mfma_f32_16x16x32_bf16 v[38:41], v[154:157], v[192:195], v[38:41]
	v_mfma_f32_16x16x32_bf16 v[30:33], v[134:137], v[200:203], v[30:33]
	v_mfma_f32_16x16x32_bf16 v[22:25], v[154:157], v[200:203], v[22:25]
	v_mfma_f32_16x16x32_bf16 v[14:17], v[134:137], v[208:211], v[14:17]
	v_mfma_f32_16x16x32_bf16 v[6:9], v[154:157], v[208:211], v[6:9]
	v_mfma_f32_16x16x32_bf16 v[58:61], v[158:161], v[180:183], v[58:61]
	v_mfma_f32_16x16x32_bf16 v[50:53], v[166:169], v[180:183], v[50:53]
	v_mfma_f32_16x16x32_bf16 v[42:45], v[158:161], v[188:191], v[42:45]
	v_mfma_f32_16x16x32_bf16 v[34:37], v[166:169], v[188:191], v[34:37]
	v_mfma_f32_16x16x32_bf16 v[26:29], v[158:161], v[196:199], v[26:29]
	v_mfma_f32_16x16x32_bf16 v[18:21], v[166:169], v[196:199], v[18:21]
	v_mfma_f32_16x16x32_bf16 v[10:13], v[158:161], v[204:207], v[10:13]
	v_mfma_f32_16x16x32_bf16 v[2:5], v[166:169], v[204:207], v[2:5]
	v_mfma_f32_16x16x32_bf16 v[58:61], v[162:165], v[184:187], v[58:61]
	v_mfma_f32_16x16x32_bf16 v[50:53], v[176:179], v[184:187], v[50:53]
	v_mfma_f32_16x16x32_bf16 v[42:45], v[162:165], v[192:195], v[42:45]
	v_mfma_f32_16x16x32_bf16 v[34:37], v[176:179], v[192:195], v[34:37]
	v_mfma_f32_16x16x32_bf16 v[26:29], v[162:165], v[200:203], v[26:29]
	v_mfma_f32_16x16x32_bf16 v[18:21], v[176:179], v[200:203], v[18:21]
	v_mfma_f32_16x16x32_bf16 v[10:13], v[162:165], v[208:211], v[10:13]
	v_mfma_f32_16x16x32_bf16 v[2:5], v[176:179], v[208:211], v[2:5]
	s_setprio 0
	s_barrier
	s_add_i32 s41, s41, 2
	s_add_u32 s2, s2, 0x100
	s_addc_u32 s3, s3, 0
	s_cmp_gt_u32 s41, 29
	s_mov_b64 s[14:15], s[0:1]
.LBB0_1738:
	s_add_u32 s0, s14, 0x100
	s_addc_u32 s1, s15, 0
	s_add_i32 s42, 0, 0x10000
	s_cmp_eq_u32 s41, 28
	s_cselect_b32 s19, s11, s1
	s_cselect_b32 s18, s10, s0
	s_cselect_b32 s17, s13, s3
	s_cselect_b32 s16, s12, s2
	s_add_i32 s43, 0, 0x14000
	v_add_u32_e32 v154, s42, v171
	v_add_u32_e32 v175, s43, v171
	ds_read_b128 v[130:133], v154
	ds_read_b128 v[134:137], v154 offset:1024
	ds_read_b128 v[150:153], v154 offset:2048
	ds_read_b128 v[154:157], v154 offset:3072
	ds_read_b128 v[158:161], v175
	ds_read_b128 v[162:165], v175 offset:1024
	ds_read_b128 v[166:169], v175 offset:2048
	ds_read_b128 v[176:179], v175 offset:3072
	v_lshl_add_u64 v[212:213], s[14:15], 0, v[146:147]
	s_add_i32 m0, s24, 0xc000
	ds_read_b128 v[180:183], v174
	ds_read_b128 v[184:187], v174 offset:1024
	ds_read_b128 v[188:191], v174 offset:2048
	ds_read_b128 v[192:195], v174 offset:3072
	ds_read_b128 v[196:199], v174 offset:4096
	ds_read_b128 v[200:203], v174 offset:5120
	ds_read_b128 v[204:207], v174 offset:6144
	ds_read_b128 v[208:211], v174 offset:7168
	global_load_lds_dwordx4 v[212:213], off
	v_lshl_add_u64 v[212:213], s[14:15], 0, v[148:149]
	s_add_i32 m0, s24, 0xe000
	s_nop 0
	global_load_lds_dwordx4 v[212:213], off
	s_waitcnt vmcnt(8)
	s_waitcnt lgkmcnt(0)
	s_barrier
	s_setprio 1
	v_mfma_f32_16x16x32_bf16 v[126:129], v[130:133], v[180:183], v[126:129]
	v_mfma_f32_16x16x32_bf16 v[118:121], v[150:153], v[180:183], v[118:121]
	v_mfma_f32_16x16x32_bf16 v[110:113], v[130:133], v[188:191], v[110:113]
	v_mfma_f32_16x16x32_bf16 v[102:105], v[150:153], v[188:191], v[102:105]
	v_mfma_f32_16x16x32_bf16 v[94:97], v[130:133], v[196:199], v[94:97]
	v_mfma_f32_16x16x32_bf16 v[86:89], v[150:153], v[196:199], v[86:89]
	v_mfma_f32_16x16x32_bf16 v[78:81], v[130:133], v[204:207], v[78:81]
	v_mfma_f32_16x16x32_bf16 v[70:73], v[150:153], v[204:207], v[70:73]
	v_mfma_f32_16x16x32_bf16 v[126:129], v[134:137], v[184:187], v[126:129]
	v_mfma_f32_16x16x32_bf16 v[118:121], v[154:157], v[184:187], v[118:121]
	v_mfma_f32_16x16x32_bf16 v[110:113], v[134:137], v[192:195], v[110:113]
	v_mfma_f32_16x16x32_bf16 v[102:105], v[154:157], v[192:195], v[102:105]
	v_mfma_f32_16x16x32_bf16 v[94:97], v[134:137], v[200:203], v[94:97]
	v_mfma_f32_16x16x32_bf16 v[86:89], v[154:157], v[200:203], v[86:89]
	v_mfma_f32_16x16x32_bf16 v[78:81], v[134:137], v[208:211], v[78:81]
	v_mfma_f32_16x16x32_bf16 v[70:73], v[154:157], v[208:211], v[70:73]
	v_mfma_f32_16x16x32_bf16 v[122:125], v[158:161], v[180:183], v[122:125]
	v_mfma_f32_16x16x32_bf16 v[114:117], v[166:169], v[180:183], v[114:117]
	v_mfma_f32_16x16x32_bf16 v[106:109], v[158:161], v[188:191], v[106:109]
	v_mfma_f32_16x16x32_bf16 v[98:101], v[166:169], v[188:191], v[98:101]
	v_mfma_f32_16x16x32_bf16 v[90:93], v[158:161], v[196:199], v[90:93]
	v_mfma_f32_16x16x32_bf16 v[82:85], v[166:169], v[196:199], v[82:85]
	v_mfma_f32_16x16x32_bf16 v[74:77], v[158:161], v[204:207], v[74:77]
	v_mfma_f32_16x16x32_bf16 v[66:69], v[166:169], v[204:207], v[66:69]
	v_mfma_f32_16x16x32_bf16 v[122:125], v[162:165], v[184:187], v[122:125]
	v_mfma_f32_16x16x32_bf16 v[114:117], v[176:179], v[184:187], v[114:117]
	v_mfma_f32_16x16x32_bf16 v[106:109], v[162:165], v[192:195], v[106:109]
	v_mfma_f32_16x16x32_bf16 v[98:101], v[176:179], v[192:195], v[98:101]
	v_mfma_f32_16x16x32_bf16 v[90:93], v[162:165], v[200:203], v[90:93]
	v_mfma_f32_16x16x32_bf16 v[82:85], v[176:179], v[200:203], v[82:85]
	v_mfma_f32_16x16x32_bf16 v[74:77], v[162:165], v[208:211], v[74:77]
	v_mfma_f32_16x16x32_bf16 v[66:69], v[176:179], v[208:211], v[66:69]
	s_setprio 0
	s_barrier
	s_add_i32 s14, s42, s20
	v_lshl_add_u64 v[212:213], s[16:17], 0, v[0:1]
	s_mov_b32 m0, s14
	ds_read_b128 v[180:183], v174 offset:16384
	ds_read_b128 v[184:187], v174 offset:17408
	ds_read_b128 v[188:191], v174 offset:18432
	ds_read_b128 v[192:195], v174 offset:19456
	ds_read_b128 v[196:199], v174 offset:20480
	ds_read_b128 v[200:203], v174 offset:21504
	ds_read_b128 v[204:207], v174 offset:22528
	ds_read_b128 v[208:211], v174 offset:23552
	global_load_lds_dwordx4 v[212:213], off
	s_add_i32 m0, s14, 0x2000
	s_add_u32 s14, s16, 0x88000
	v_lshl_add_u64 v[214:215], s[16:17], 0, v[138:139]
	s_addc_u32 s15, s17, 0
	s_add_i32 s42, s43, s20
	global_load_lds_dwordx4 v[214:215], off
	v_lshl_add_u64 v[216:217], s[14:15], 0, v[0:1]
	s_mov_b32 m0, s42
	v_lshl_add_u64 v[218:219], s[18:19], 0, v[140:141]
	global_load_lds_dwordx4 v[216:217], off
	v_lshl_add_u64 v[216:217], s[14:15], 0, v[138:139]
	s_add_i32 m0, s42, 0x2000
	s_nop 0
	global_load_lds_dwordx4 v[216:217], off
	v_lshl_add_u64 v[216:217], s[18:19], 0, v[142:143]
	s_mov_b32 m0, s24
	s_nop 0
	global_load_lds_dwordx4 v[216:217], off
	s_mov_b32 m0, s26
	s_nop 0
	global_load_lds_dwordx4 v[218:219], off
	s_waitcnt vmcnt(8)
	s_waitcnt lgkmcnt(0)
	s_barrier
	s_setprio 1
	v_mfma_f32_16x16x32_bf16 v[62:65], v[130:133], v[180:183], v[62:65]
	v_mfma_f32_16x16x32_bf16 v[54:57], v[150:153], v[180:183], v[54:57]
	v_mfma_f32_16x16x32_bf16 v[46:49], v[130:133], v[188:191], v[46:49]
	v_mfma_f32_16x16x32_bf16 v[38:41], v[150:153], v[188:191], v[38:41]
	v_mfma_f32_16x16x32_bf16 v[30:33], v[130:133], v[196:199], v[30:33]
	v_mfma_f32_16x16x32_bf16 v[22:25], v[150:153], v[196:199], v[22:25]
	v_mfma_f32_16x16x32_bf16 v[14:17], v[130:133], v[204:207], v[14:17]
	v_mfma_f32_16x16x32_bf16 v[6:9], v[150:153], v[204:207], v[6:9]
	v_mfma_f32_16x16x32_bf16 v[62:65], v[134:137], v[184:187], v[62:65]
	v_mfma_f32_16x16x32_bf16 v[54:57], v[154:157], v[184:187], v[54:57]
	v_mfma_f32_16x16x32_bf16 v[46:49], v[134:137], v[192:195], v[46:49]
	v_mfma_f32_16x16x32_bf16 v[38:41], v[154:157], v[192:195], v[38:41]
	v_mfma_f32_16x16x32_bf16 v[30:33], v[134:137], v[200:203], v[30:33]
	v_mfma_f32_16x16x32_bf16 v[22:25], v[154:157], v[200:203], v[22:25]
	v_mfma_f32_16x16x32_bf16 v[14:17], v[134:137], v[208:211], v[14:17]
	v_mfma_f32_16x16x32_bf16 v[6:9], v[154:157], v[208:211], v[6:9]
	v_mfma_f32_16x16x32_bf16 v[58:61], v[158:161], v[180:183], v[58:61]
	v_mfma_f32_16x16x32_bf16 v[50:53], v[166:169], v[180:183], v[50:53]
	v_mfma_f32_16x16x32_bf16 v[42:45], v[158:161], v[188:191], v[42:45]
	v_mfma_f32_16x16x32_bf16 v[34:37], v[166:169], v[188:191], v[34:37]
	v_mfma_f32_16x16x32_bf16 v[26:29], v[158:161], v[196:199], v[26:29]
	v_mfma_f32_16x16x32_bf16 v[18:21], v[166:169], v[196:199], v[18:21]
	v_mfma_f32_16x16x32_bf16 v[10:13], v[158:161], v[204:207], v[10:13]
	v_mfma_f32_16x16x32_bf16 v[2:5], v[166:169], v[204:207], v[2:5]
	v_mfma_f32_16x16x32_bf16 v[58:61], v[162:165], v[184:187], v[58:61]
	v_mfma_f32_16x16x32_bf16 v[50:53], v[176:179], v[184:187], v[50:53]
	v_mfma_f32_16x16x32_bf16 v[42:45], v[162:165], v[192:195], v[42:45]
	v_mfma_f32_16x16x32_bf16 v[34:37], v[176:179], v[192:195], v[34:37]
	v_mfma_f32_16x16x32_bf16 v[26:29], v[162:165], v[200:203], v[26:29]
	v_mfma_f32_16x16x32_bf16 v[18:21], v[176:179], v[200:203], v[18:21]
	v_mfma_f32_16x16x32_bf16 v[10:13], v[162:165], v[208:211], v[10:13]
	v_mfma_f32_16x16x32_bf16 v[2:5], v[176:179], v[208:211], v[2:5]
	s_setprio 0
	s_barrier
	s_add_i32 s42, 0, 0x18000
	s_add_i32 s43, 0, 0x1c000
	v_add_u32_e32 v154, s42, v171
	v_add_u32_e32 v175, s43, v171
	ds_read_b128 v[130:133], v154
	ds_read_b128 v[134:137], v154 offset:1024
	ds_read_b128 v[150:153], v154 offset:2048
	ds_read_b128 v[154:157], v154 offset:3072
	ds_read_b128 v[158:161], v175
	ds_read_b128 v[162:165], v175 offset:1024
	ds_read_b128 v[166:169], v175 offset:2048
	ds_read_b128 v[176:179], v175 offset:3072
	s_add_u32 s14, s18, 0x88000
	s_addc_u32 s15, s19, 0
	s_mov_b32 m0, s27
	v_lshl_add_u64 v[220:221], s[14:15], 0, v[142:143]
	ds_read_b128 v[180:183], v174 offset:32768
	ds_read_b128 v[184:187], v174 offset:33792
	ds_read_b128 v[188:191], v174 offset:34816
	ds_read_b128 v[192:195], v174 offset:35840
	ds_read_b128 v[196:199], v174 offset:36864
	ds_read_b128 v[200:203], v174 offset:37888
	ds_read_b128 v[204:207], v174 offset:38912
	ds_read_b128 v[208:211], v174 offset:39936
	global_load_lds_dwordx4 v[220:221], off
	v_lshl_add_u64 v[220:221], s[14:15], 0, v[140:141]
	s_mov_b32 m0, s28
	s_nop 0
	global_load_lds_dwordx4 v[220:221], off
	s_waitcnt vmcnt(8)
	s_waitcnt lgkmcnt(0)
	s_barrier
	s_setprio 1
	v_mfma_f32_16x16x32_bf16 v[126:129], v[130:133], v[180:183], v[126:129]
	v_mfma_f32_16x16x32_bf16 v[118:121], v[150:153], v[180:183], v[118:121]
	v_mfma_f32_16x16x32_bf16 v[110:113], v[130:133], v[188:191], v[110:113]
	v_mfma_f32_16x16x32_bf16 v[102:105], v[150:153], v[188:191], v[102:105]
	v_mfma_f32_16x16x32_bf16 v[94:97], v[130:133], v[196:199], v[94:97]
	v_mfma_f32_16x16x32_bf16 v[86:89], v[150:153], v[196:199], v[86:89]
	v_mfma_f32_16x16x32_bf16 v[78:81], v[130:133], v[204:207], v[78:81]
	v_mfma_f32_16x16x32_bf16 v[70:73], v[150:153], v[204:207], v[70:73]
	v_mfma_f32_16x16x32_bf16 v[126:129], v[134:137], v[184:187], v[126:129]
	v_mfma_f32_16x16x32_bf16 v[118:121], v[154:157], v[184:187], v[118:121]
	v_mfma_f32_16x16x32_bf16 v[110:113], v[134:137], v[192:195], v[110:113]
	v_mfma_f32_16x16x32_bf16 v[102:105], v[154:157], v[192:195], v[102:105]
	v_mfma_f32_16x16x32_bf16 v[94:97], v[134:137], v[200:203], v[94:97]
	v_mfma_f32_16x16x32_bf16 v[86:89], v[154:157], v[200:203], v[86:89]
	v_mfma_f32_16x16x32_bf16 v[78:81], v[134:137], v[208:211], v[78:81]
	v_mfma_f32_16x16x32_bf16 v[70:73], v[154:157], v[208:211], v[70:73]
	v_mfma_f32_16x16x32_bf16 v[122:125], v[158:161], v[180:183], v[122:125]
	v_mfma_f32_16x16x32_bf16 v[114:117], v[166:169], v[180:183], v[114:117]
	v_mfma_f32_16x16x32_bf16 v[106:109], v[158:161], v[188:191], v[106:109]
	v_mfma_f32_16x16x32_bf16 v[98:101], v[166:169], v[188:191], v[98:101]
	v_mfma_f32_16x16x32_bf16 v[90:93], v[158:161], v[196:199], v[90:93]
	v_mfma_f32_16x16x32_bf16 v[82:85], v[166:169], v[196:199], v[82:85]
	v_mfma_f32_16x16x32_bf16 v[74:77], v[158:161], v[204:207], v[74:77]
	v_mfma_f32_16x16x32_bf16 v[66:69], v[166:169], v[204:207], v[66:69]
	v_mfma_f32_16x16x32_bf16 v[122:125], v[162:165], v[184:187], v[122:125]
	v_mfma_f32_16x16x32_bf16 v[114:117], v[176:179], v[184:187], v[114:117]
	v_mfma_f32_16x16x32_bf16 v[106:109], v[162:165], v[192:195], v[106:109]
	v_mfma_f32_16x16x32_bf16 v[98:101], v[176:179], v[192:195], v[98:101]
	v_mfma_f32_16x16x32_bf16 v[90:93], v[162:165], v[200:203], v[90:93]
	v_mfma_f32_16x16x32_bf16 v[82:85], v[176:179], v[200:203], v[82:85]
	v_mfma_f32_16x16x32_bf16 v[74:77], v[162:165], v[208:211], v[74:77]
	v_mfma_f32_16x16x32_bf16 v[66:69], v[176:179], v[208:211], v[66:69]
	s_setprio 0
	s_barrier
	s_add_i32 s14, s42, s20
	v_lshl_add_u64 v[212:213], v[212:213], 0, s[22:23]
	s_mov_b32 m0, s14
	ds_read_b128 v[180:183], v174 offset:49152
	ds_read_b128 v[184:187], v174 offset:50176
	ds_read_b128 v[188:191], v174 offset:51200
	ds_read_b128 v[192:195], v174 offset:52224
	ds_read_b128 v[196:199], v174 offset:53248
	ds_read_b128 v[200:203], v174 offset:54272
	ds_read_b128 v[204:207], v174 offset:55296
	ds_read_b128 v[208:211], v174 offset:56320
	global_load_lds_dwordx4 v[212:213], off
	s_add_i32 m0, s14, 0x2000
	s_add_u32 s14, s16, 0x88080
	v_lshl_add_u64 v[212:213], v[214:215], 0, s[22:23]
	s_addc_u32 s15, s17, 0
	s_add_i32 s16, s43, s20
	global_load_lds_dwordx4 v[212:213], off
	v_lshl_add_u64 v[212:213], s[14:15], 0, v[0:1]
	s_mov_b32 m0, s16
	s_nop 0
	global_load_lds_dwordx4 v[212:213], off
	v_lshl_add_u64 v[212:213], s[14:15], 0, v[138:139]
	s_add_i32 m0, s16, 0x2000
	s_nop 0
	global_load_lds_dwordx4 v[212:213], off
	v_lshl_add_u64 v[212:213], v[216:217], 0, s[22:23]
	s_mov_b32 m0, s33
	s_nop 0
	global_load_lds_dwordx4 v[212:213], off
	v_lshl_add_u64 v[212:213], v[218:219], 0, s[22:23]
	s_mov_b32 m0, s36
	s_nop 0
	global_load_lds_dwordx4 v[212:213], off
	s_waitcnt vmcnt(8)
	s_waitcnt lgkmcnt(0)
	s_barrier
	s_setprio 1
	v_mfma_f32_16x16x32_bf16 v[62:65], v[130:133], v[180:183], v[62:65]
	v_mfma_f32_16x16x32_bf16 v[54:57], v[150:153], v[180:183], v[54:57]
	v_mfma_f32_16x16x32_bf16 v[46:49], v[130:133], v[188:191], v[46:49]
	v_mfma_f32_16x16x32_bf16 v[38:41], v[150:153], v[188:191], v[38:41]
	v_mfma_f32_16x16x32_bf16 v[30:33], v[130:133], v[196:199], v[30:33]
	v_mfma_f32_16x16x32_bf16 v[22:25], v[150:153], v[196:199], v[22:25]
	v_mfma_f32_16x16x32_bf16 v[14:17], v[130:133], v[204:207], v[14:17]
	v_mfma_f32_16x16x32_bf16 v[6:9], v[150:153], v[204:207], v[6:9]
	v_mfma_f32_16x16x32_bf16 v[62:65], v[134:137], v[184:187], v[62:65]
	v_mfma_f32_16x16x32_bf16 v[54:57], v[154:157], v[184:187], v[54:57]
	v_mfma_f32_16x16x32_bf16 v[46:49], v[134:137], v[192:195], v[46:49]
	v_mfma_f32_16x16x32_bf16 v[38:41], v[154:157], v[192:195], v[38:41]
	v_mfma_f32_16x16x32_bf16 v[30:33], v[134:137], v[200:203], v[30:33]
	v_mfma_f32_16x16x32_bf16 v[22:25], v[154:157], v[200:203], v[22:25]
	v_mfma_f32_16x16x32_bf16 v[14:17], v[134:137], v[208:211], v[14:17]
	v_mfma_f32_16x16x32_bf16 v[6:9], v[154:157], v[208:211], v[6:9]
	v_mfma_f32_16x16x32_bf16 v[58:61], v[158:161], v[180:183], v[58:61]
	v_mfma_f32_16x16x32_bf16 v[50:53], v[166:169], v[180:183], v[50:53]
	v_mfma_f32_16x16x32_bf16 v[42:45], v[158:161], v[188:191], v[42:45]
	v_mfma_f32_16x16x32_bf16 v[34:37], v[166:169], v[188:191], v[34:37]
	v_mfma_f32_16x16x32_bf16 v[26:29], v[158:161], v[196:199], v[26:29]
	v_mfma_f32_16x16x32_bf16 v[18:21], v[166:169], v[196:199], v[18:21]
	v_mfma_f32_16x16x32_bf16 v[10:13], v[158:161], v[204:207], v[10:13]
	v_mfma_f32_16x16x32_bf16 v[2:5], v[166:169], v[204:207], v[2:5]
	v_mfma_f32_16x16x32_bf16 v[58:61], v[162:165], v[184:187], v[58:61]
	v_mfma_f32_16x16x32_bf16 v[50:53], v[176:179], v[184:187], v[50:53]
	v_mfma_f32_16x16x32_bf16 v[42:45], v[162:165], v[192:195], v[42:45]
	v_mfma_f32_16x16x32_bf16 v[34:37], v[176:179], v[192:195], v[34:37]
	v_mfma_f32_16x16x32_bf16 v[26:29], v[162:165], v[200:203], v[26:29]
	v_mfma_f32_16x16x32_bf16 v[18:21], v[176:179], v[200:203], v[18:21]
	v_mfma_f32_16x16x32_bf16 v[10:13], v[162:165], v[208:211], v[10:13]
	v_mfma_f32_16x16x32_bf16 v[2:5], v[176:179], v[208:211], v[2:5]
	s_setprio 0
	s_barrier
	s_add_i32 s41, s41, 2
	s_add_u32 s2, s2, 0x100
	s_addc_u32 s3, s3, 0
	s_cmp_gt_u32 s41, 29
	s_mov_b64 s[14:15], s[0:1]
	s_cbranch_scc0 .LBB0_1738
	s_and_b64 vcc, exec, s[8:9]
	s_cbranch_vccz .LBB0_1741
	s_barrier

.LBB0_1867:
	s_add_u32 s2, s18, 0x100
	s_addc_u32 s3, s19, 0
	s_mov_b32 s30, -2
	s_waitcnt lgkmcnt(0)
	s_add_u32 s18, s16, 0x100
	s_addc_u32 s19, s17, 0
	s_add_i32 s38, 0, 0x10000
	s_cmpk_eq_i32 s30, 0x54
	s_cselect_b32 s27, s1, s19
	s_cselect_b32 s26, s0, s18
	s_cselect_b32 s21, s15, s3
	s_cselect_b32 s20, s14, s2
	s_add_i32 s39, 0, 0x14000
	v_add_u32_e32 v142, s38, v179
	v_add_u32_e32 v168, s39, v179
	ds_read_b128 v[114:117], v142
	ds_read_b128 v[126:129], v142 offset:1024
	ds_read_b128 v[130:133], v142 offset:2048
	ds_read_b128 v[142:145], v142 offset:3072
	ds_read_b128 v[146:149], v168
	ds_read_b128 v[150:153], v168 offset:1024
	ds_read_b128 v[154:157], v168 offset:2048
	ds_read_b128 v[168:171], v168 offset:3072
	v_lshl_add_u64 v[176:177], s[16:17], 0, v[164:165]
	s_add_i32 m0, s40, 0xc000
	ds_read_b128 v[172:175], v184
	ds_read_b128 v[186:189], v184 offset:1024
	ds_read_b128 v[190:193], v184 offset:2048
	ds_read_b128 v[194:197], v184 offset:3072
	ds_read_b128 v[198:201], v184 offset:4096
	ds_read_b128 v[202:205], v184 offset:5120
	ds_read_b128 v[206:209], v184 offset:6144
	ds_read_b128 v[210:213], v184 offset:7168
	global_load_lds_dwordx4 v[176:177], off
	v_lshl_add_u64 v[176:177], s[16:17], 0, v[166:167]
	s_add_i32 m0, s40, 0xe000
	s_nop 0
	global_load_lds_dwordx4 v[176:177], off
	s_waitcnt vmcnt(8)
	s_waitcnt lgkmcnt(0)
	s_barrier
	s_setprio 1
	v_mfma_f32_16x16x32_bf16 v[138:141], v[114:117], v[172:175], 0
	v_mfma_f32_16x16x32_bf16 v[134:137], v[130:133], v[172:175], 0
	v_mfma_f32_16x16x32_bf16 v[110:113], v[114:117], v[190:193], 0
	v_mfma_f32_16x16x32_bf16 v[106:109], v[130:133], v[190:193], 0
	v_mfma_f32_16x16x32_bf16 v[94:97], v[114:117], v[198:201], 0
	v_mfma_f32_16x16x32_bf16 v[90:93], v[130:133], v[198:201], 0
	v_mfma_f32_16x16x32_bf16 v[78:81], v[114:117], v[206:209], 0
	v_mfma_f32_16x16x32_bf16 v[74:77], v[130:133], v[206:209], 0
	v_mfma_f32_16x16x32_bf16 v[138:141], v[126:129], v[186:189], v[138:141]
	v_mfma_f32_16x16x32_bf16 v[134:137], v[142:145], v[186:189], v[134:137]
	v_mfma_f32_16x16x32_bf16 v[110:113], v[126:129], v[194:197], v[110:113]
	v_mfma_f32_16x16x32_bf16 v[106:109], v[142:145], v[194:197], v[106:109]
	v_mfma_f32_16x16x32_bf16 v[94:97], v[126:129], v[202:205], v[94:97]
	v_mfma_f32_16x16x32_bf16 v[90:93], v[142:145], v[202:205], v[90:93]
	v_mfma_f32_16x16x32_bf16 v[78:81], v[126:129], v[210:213], v[78:81]
	v_mfma_f32_16x16x32_bf16 v[74:77], v[142:145], v[210:213], v[74:77]
	v_mfma_f32_16x16x32_bf16 v[122:125], v[146:149], v[172:175], 0
	v_mfma_f32_16x16x32_bf16 v[118:121], v[154:157], v[172:175], 0
	v_mfma_f32_16x16x32_bf16 v[102:105], v[146:149], v[190:193], 0
	v_mfma_f32_16x16x32_bf16 v[98:101], v[154:157], v[190:193], 0
	v_mfma_f32_16x16x32_bf16 v[86:89], v[146:149], v[198:201], 0
	v_mfma_f32_16x16x32_bf16 v[82:85], v[154:157], v[198:201], 0
	v_mfma_f32_16x16x32_bf16 v[70:73], v[146:149], v[206:209], 0
	v_mfma_f32_16x16x32_bf16 v[66:69], v[154:157], v[206:209], 0
	v_mfma_f32_16x16x32_bf16 v[122:125], v[150:153], v[186:189], v[122:125]
	v_mfma_f32_16x16x32_bf16 v[118:121], v[168:171], v[186:189], v[118:121]
	v_mfma_f32_16x16x32_bf16 v[102:105], v[150:153], v[194:197], v[102:105]
	v_mfma_f32_16x16x32_bf16 v[98:101], v[168:171], v[194:197], v[98:101]
	v_mfma_f32_16x16x32_bf16 v[86:89], v[150:153], v[202:205], v[86:89]
	v_mfma_f32_16x16x32_bf16 v[82:85], v[168:171], v[202:205], v[82:85]
	v_mfma_f32_16x16x32_bf16 v[70:73], v[150:153], v[210:213], v[70:73]
	v_mfma_f32_16x16x32_bf16 v[66:69], v[168:171], v[210:213], v[66:69]
	s_setprio 0
	s_barrier
	s_add_i32 s16, s38, s29
	v_lshl_add_u64 v[176:177], s[20:21], 0, v[0:1]
	s_mov_b32 m0, s16
	ds_read_b128 v[172:175], v184 offset:16384
	ds_read_b128 v[186:189], v184 offset:17408
	ds_read_b128 v[190:193], v184 offset:18432
	ds_read_b128 v[194:197], v184 offset:19456
	ds_read_b128 v[198:201], v184 offset:20480
	ds_read_b128 v[202:205], v184 offset:21504
	ds_read_b128 v[206:209], v184 offset:22528
	ds_read_b128 v[210:213], v184 offset:23552
	global_load_lds_dwordx4 v[176:177], off
	s_add_i32 m0, s16, 0x2000
	s_add_u32 s16, s20, 0x5a000
	v_lshl_add_u64 v[214:215], s[20:21], 0, v[162:163]
	s_addc_u32 s17, s21, 0
	s_add_i32 s38, s39, s29
	global_load_lds_dwordx4 v[214:215], off
	v_lshl_add_u64 v[216:217], s[16:17], 0, v[0:1]
	s_mov_b32 m0, s38
	v_lshl_add_u64 v[218:219], s[26:27], 0, v[160:161]
	global_load_lds_dwordx4 v[216:217], off
	v_lshl_add_u64 v[216:217], s[16:17], 0, v[162:163]
	s_add_i32 m0, s38, 0x2000
	s_nop 0
	global_load_lds_dwordx4 v[216:217], off
	v_lshl_add_u64 v[216:217], s[26:27], 0, v[158:159]
	s_mov_b32 m0, s40
	s_nop 0
	global_load_lds_dwordx4 v[216:217], off
	s_mov_b32 m0, s41
	s_nop 0
	global_load_lds_dwordx4 v[218:219], off
	s_waitcnt vmcnt(8)
	s_waitcnt lgkmcnt(0)
	s_barrier
	s_setprio 1
	v_mfma_f32_16x16x32_bf16 v[62:65], v[114:117], v[172:175], 0
	v_mfma_f32_16x16x32_bf16 v[58:61], v[130:133], v[172:175], 0
	v_mfma_f32_16x16x32_bf16 v[46:49], v[114:117], v[190:193], 0
	v_mfma_f32_16x16x32_bf16 v[42:45], v[130:133], v[190:193], 0
	v_mfma_f32_16x16x32_bf16 v[30:33], v[114:117], v[198:201], 0
	v_mfma_f32_16x16x32_bf16 v[26:29], v[130:133], v[198:201], 0
	v_mfma_f32_16x16x32_bf16 v[14:17], v[114:117], v[206:209], 0
	v_mfma_f32_16x16x32_bf16 v[10:13], v[130:133], v[206:209], 0
	v_mfma_f32_16x16x32_bf16 v[62:65], v[126:129], v[186:189], v[62:65]
	v_mfma_f32_16x16x32_bf16 v[58:61], v[142:145], v[186:189], v[58:61]
	v_mfma_f32_16x16x32_bf16 v[46:49], v[126:129], v[194:197], v[46:49]
	v_mfma_f32_16x16x32_bf16 v[42:45], v[142:145], v[194:197], v[42:45]
	v_mfma_f32_16x16x32_bf16 v[30:33], v[126:129], v[202:205], v[30:33]
	v_mfma_f32_16x16x32_bf16 v[26:29], v[142:145], v[202:205], v[26:29]
	v_mfma_f32_16x16x32_bf16 v[14:17], v[126:129], v[210:213], v[14:17]
	v_mfma_f32_16x16x32_bf16 v[10:13], v[142:145], v[210:213], v[10:13]
	v_mfma_f32_16x16x32_bf16 v[54:57], v[146:149], v[172:175], 0
	v_mfma_f32_16x16x32_bf16 v[50:53], v[154:157], v[172:175], 0
	v_mfma_f32_16x16x32_bf16 v[38:41], v[146:149], v[190:193], 0
	v_mfma_f32_16x16x32_bf16 v[34:37], v[154:157], v[190:193], 0
	v_mfma_f32_16x16x32_bf16 v[22:25], v[146:149], v[198:201], 0
	v_mfma_f32_16x16x32_bf16 v[18:21], v[154:157], v[198:201], 0
	v_mfma_f32_16x16x32_bf16 v[6:9], v[146:149], v[206:209], 0
	v_mfma_f32_16x16x32_bf16 v[2:5], v[154:157], v[206:209], 0
	v_mfma_f32_16x16x32_bf16 v[54:57], v[150:153], v[186:189], v[54:57]
	v_mfma_f32_16x16x32_bf16 v[50:53], v[168:171], v[186:189], v[50:53]
	v_mfma_f32_16x16x32_bf16 v[38:41], v[150:153], v[194:197], v[38:41]
	v_mfma_f32_16x16x32_bf16 v[34:37], v[168:171], v[194:197], v[34:37]
	v_mfma_f32_16x16x32_bf16 v[22:25], v[150:153], v[202:205], v[22:25]
	v_mfma_f32_16x16x32_bf16 v[18:21], v[168:171], v[202:205], v[18:21]
	v_mfma_f32_16x16x32_bf16 v[6:9], v[150:153], v[210:213], v[6:9]
	v_mfma_f32_16x16x32_bf16 v[2:5], v[168:171], v[210:213], v[2:5]
	s_setprio 0
	s_barrier
	s_add_i32 s38, 0, 0x18000
	s_add_i32 s39, 0, 0x1c000
	v_add_u32_e32 v142, s38, v179
	v_add_u32_e32 v168, s39, v179
	ds_read_b128 v[114:117], v142
	ds_read_b128 v[126:129], v142 offset:1024
	ds_read_b128 v[130:133], v142 offset:2048
	ds_read_b128 v[142:145], v142 offset:3072
	ds_read_b128 v[146:149], v168
	ds_read_b128 v[150:153], v168 offset:1024
	ds_read_b128 v[154:157], v168 offset:2048
	ds_read_b128 v[168:171], v168 offset:3072
	s_add_u32 s16, s26, 0x168000
	s_addc_u32 s17, s27, 0
	s_mov_b32 m0, s42
	v_lshl_add_u64 v[220:221], s[16:17], 0, v[158:159]
	ds_read_b128 v[172:175], v184 offset:32768
	ds_read_b128 v[186:189], v184 offset:33792
	ds_read_b128 v[190:193], v184 offset:34816
	ds_read_b128 v[194:197], v184 offset:35840
	ds_read_b128 v[198:201], v184 offset:36864
	ds_read_b128 v[202:205], v184 offset:37888
	ds_read_b128 v[206:209], v184 offset:38912
	ds_read_b128 v[210:213], v184 offset:39936
	global_load_lds_dwordx4 v[220:221], off
	v_lshl_add_u64 v[220:221], s[16:17], 0, v[160:161]
	s_mov_b32 m0, s43
	s_nop 0
	global_load_lds_dwordx4 v[220:221], off
	s_waitcnt vmcnt(8)
	s_waitcnt lgkmcnt(0)
	s_barrier
	s_setprio 1
	v_mfma_f32_16x16x32_bf16 v[138:141], v[114:117], v[172:175], v[138:141]
	v_mfma_f32_16x16x32_bf16 v[134:137], v[130:133], v[172:175], v[134:137]
	v_mfma_f32_16x16x32_bf16 v[110:113], v[114:117], v[190:193], v[110:113]
	v_mfma_f32_16x16x32_bf16 v[106:109], v[130:133], v[190:193], v[106:109]
	v_mfma_f32_16x16x32_bf16 v[94:97], v[114:117], v[198:201], v[94:97]
	v_mfma_f32_16x16x32_bf16 v[90:93], v[130:133], v[198:201], v[90:93]
	v_mfma_f32_16x16x32_bf16 v[78:81], v[114:117], v[206:209], v[78:81]
	v_mfma_f32_16x16x32_bf16 v[74:77], v[130:133], v[206:209], v[74:77]
	v_mfma_f32_16x16x32_bf16 v[138:141], v[126:129], v[186:189], v[138:141]
	v_mfma_f32_16x16x32_bf16 v[134:137], v[142:145], v[186:189], v[134:137]
	v_mfma_f32_16x16x32_bf16 v[110:113], v[126:129], v[194:197], v[110:113]
	v_mfma_f32_16x16x32_bf16 v[106:109], v[142:145], v[194:197], v[106:109]
	v_mfma_f32_16x16x32_bf16 v[94:97], v[126:129], v[202:205], v[94:97]
	v_mfma_f32_16x16x32_bf16 v[90:93], v[142:145], v[202:205], v[90:93]
	v_mfma_f32_16x16x32_bf16 v[78:81], v[126:129], v[210:213], v[78:81]
	v_mfma_f32_16x16x32_bf16 v[74:77], v[142:145], v[210:213], v[74:77]
	v_mfma_f32_16x16x32_bf16 v[122:125], v[146:149], v[172:175], v[122:125]
	v_mfma_f32_16x16x32_bf16 v[118:121], v[154:157], v[172:175], v[118:121]
	v_mfma_f32_16x16x32_bf16 v[102:105], v[146:149], v[190:193], v[102:105]
	v_mfma_f32_16x16x32_bf16 v[98:101], v[154:157], v[190:193], v[98:101]
	v_mfma_f32_16x16x32_bf16 v[86:89], v[146:149], v[198:201], v[86:89]
	v_mfma_f32_16x16x32_bf16 v[82:85], v[154:157], v[198:201], v[82:85]
	v_mfma_f32_16x16x32_bf16 v[70:73], v[146:149], v[206:209], v[70:73]
	v_mfma_f32_16x16x32_bf16 v[66:69], v[154:157], v[206:209], v[66:69]
	v_mfma_f32_16x16x32_bf16 v[122:125], v[150:153], v[186:189], v[122:125]
	v_mfma_f32_16x16x32_bf16 v[118:121], v[168:171], v[186:189], v[118:121]
	v_mfma_f32_16x16x32_bf16 v[102:105], v[150:153], v[194:197], v[102:105]
	v_mfma_f32_16x16x32_bf16 v[98:101], v[168:171], v[194:197], v[98:101]
	v_mfma_f32_16x16x32_bf16 v[86:89], v[150:153], v[202:205], v[86:89]
	v_mfma_f32_16x16x32_bf16 v[82:85], v[168:171], v[202:205], v[82:85]
	v_mfma_f32_16x16x32_bf16 v[70:73], v[150:153], v[210:213], v[70:73]
	v_mfma_f32_16x16x32_bf16 v[66:69], v[168:171], v[210:213], v[66:69]
	s_setprio 0
	s_barrier
	s_add_i32 s16, s38, s29
	v_lshl_add_u64 v[176:177], v[176:177], 0, s[22:23]
	s_mov_b32 m0, s16
	ds_read_b128 v[172:175], v184 offset:49152
	ds_read_b128 v[186:189], v184 offset:50176
	ds_read_b128 v[190:193], v184 offset:51200
	ds_read_b128 v[194:197], v184 offset:52224
	ds_read_b128 v[198:201], v184 offset:53248
	ds_read_b128 v[202:205], v184 offset:54272
	ds_read_b128 v[206:209], v184 offset:55296
	ds_read_b128 v[210:213], v184 offset:56320
	global_load_lds_dwordx4 v[176:177], off
	s_add_i32 m0, s16, 0x2000
	s_add_u32 s16, s20, 0x5a080
	v_lshl_add_u64 v[176:177], v[214:215], 0, s[22:23]
	s_addc_u32 s17, s21, 0
	s_add_i32 s20, s39, s29
	global_load_lds_dwordx4 v[176:177], off
	v_lshl_add_u64 v[176:177], s[16:17], 0, v[0:1]
	s_mov_b32 m0, s20
	s_nop 0
	global_load_lds_dwordx4 v[176:177], off
	v_lshl_add_u64 v[176:177], s[16:17], 0, v[162:163]
	s_add_i32 m0, s20, 0x2000
	s_nop 0
	global_load_lds_dwordx4 v[176:177], off
	v_lshl_add_u64 v[176:177], v[216:217], 0, s[22:23]
	s_mov_b32 m0, s44
	s_nop 0
	global_load_lds_dwordx4 v[176:177], off
	v_lshl_add_u64 v[176:177], v[218:219], 0, s[22:23]
	s_mov_b32 m0, s45
	s_nop 0
	global_load_lds_dwordx4 v[176:177], off
	s_waitcnt vmcnt(8)
	s_waitcnt lgkmcnt(0)
	s_barrier
	s_setprio 1
	v_mfma_f32_16x16x32_bf16 v[62:65], v[114:117], v[172:175], v[62:65]
	v_mfma_f32_16x16x32_bf16 v[58:61], v[130:133], v[172:175], v[58:61]
	v_mfma_f32_16x16x32_bf16 v[46:49], v[114:117], v[190:193], v[46:49]
	v_mfma_f32_16x16x32_bf16 v[42:45], v[130:133], v[190:193], v[42:45]
	v_mfma_f32_16x16x32_bf16 v[30:33], v[114:117], v[198:201], v[30:33]
	v_mfma_f32_16x16x32_bf16 v[26:29], v[130:133], v[198:201], v[26:29]
	v_mfma_f32_16x16x32_bf16 v[14:17], v[114:117], v[206:209], v[14:17]
	v_mfma_f32_16x16x32_bf16 v[10:13], v[130:133], v[206:209], v[10:13]
	v_mfma_f32_16x16x32_bf16 v[62:65], v[126:129], v[186:189], v[62:65]
	v_mfma_f32_16x16x32_bf16 v[58:61], v[142:145], v[186:189], v[58:61]
	v_mfma_f32_16x16x32_bf16 v[46:49], v[126:129], v[194:197], v[46:49]
	v_mfma_f32_16x16x32_bf16 v[42:45], v[142:145], v[194:197], v[42:45]
	v_mfma_f32_16x16x32_bf16 v[30:33], v[126:129], v[202:205], v[30:33]
	v_mfma_f32_16x16x32_bf16 v[26:29], v[142:145], v[202:205], v[26:29]
	v_mfma_f32_16x16x32_bf16 v[14:17], v[126:129], v[210:213], v[14:17]
	v_mfma_f32_16x16x32_bf16 v[10:13], v[142:145], v[210:213], v[10:13]
	v_mfma_f32_16x16x32_bf16 v[54:57], v[146:149], v[172:175], v[54:57]
	v_mfma_f32_16x16x32_bf16 v[50:53], v[154:157], v[172:175], v[50:53]
	v_mfma_f32_16x16x32_bf16 v[38:41], v[146:149], v[190:193], v[38:41]
	v_mfma_f32_16x16x32_bf16 v[34:37], v[154:157], v[190:193], v[34:37]
	v_mfma_f32_16x16x32_bf16 v[22:25], v[146:149], v[198:201], v[22:25]
	v_mfma_f32_16x16x32_bf16 v[18:21], v[154:157], v[198:201], v[18:21]
	v_mfma_f32_16x16x32_bf16 v[6:9], v[146:149], v[206:209], v[6:9]
	v_mfma_f32_16x16x32_bf16 v[2:5], v[154:157], v[206:209], v[2:5]
	v_mfma_f32_16x16x32_bf16 v[54:57], v[150:153], v[186:189], v[54:57]
	v_mfma_f32_16x16x32_bf16 v[50:53], v[168:171], v[186:189], v[50:53]
	v_mfma_f32_16x16x32_bf16 v[38:41], v[150:153], v[194:197], v[38:41]
	v_mfma_f32_16x16x32_bf16 v[34:37], v[168:171], v[194:197], v[34:37]
	v_mfma_f32_16x16x32_bf16 v[22:25], v[150:153], v[202:205], v[22:25]
	v_mfma_f32_16x16x32_bf16 v[18:21], v[168:171], v[202:205], v[18:21]
	v_mfma_f32_16x16x32_bf16 v[6:9], v[150:153], v[210:213], v[6:9]
	v_mfma_f32_16x16x32_bf16 v[2:5], v[168:171], v[210:213], v[2:5]
	s_setprio 0
	s_barrier
	s_add_i32 s30, s30, 2
	s_add_u32 s2, s2, 0x100
	s_addc_u32 s3, s3, 0
	s_cmpk_gt_u32 s30, 0x55
	s_mov_b64 s[16:17], s[18:19]
.LBB0_1868:
	s_add_u32 s18, s16, 0x100
	s_addc_u32 s19, s17, 0
	s_add_i32 s38, 0, 0x10000
	s_cmpk_eq_i32 s30, 0x54
	s_cselect_b32 s27, s1, s19
	s_cselect_b32 s26, s0, s18
	s_cselect_b32 s21, s15, s3
	s_cselect_b32 s20, s14, s2
	s_add_i32 s39, 0, 0x14000
	v_add_u32_e32 v142, s38, v179
	v_add_u32_e32 v168, s39, v179
	ds_read_b128 v[114:117], v142
	ds_read_b128 v[126:129], v142 offset:1024
	ds_read_b128 v[130:133], v142 offset:2048
	ds_read_b128 v[142:145], v142 offset:3072
	ds_read_b128 v[146:149], v168
	ds_read_b128 v[150:153], v168 offset:1024
	ds_read_b128 v[154:157], v168 offset:2048
	ds_read_b128 v[168:171], v168 offset:3072
	v_lshl_add_u64 v[176:177], s[16:17], 0, v[164:165]
	s_add_i32 m0, s40, 0xc000
	ds_read_b128 v[172:175], v184
	ds_read_b128 v[186:189], v184 offset:1024
	ds_read_b128 v[190:193], v184 offset:2048
	ds_read_b128 v[194:197], v184 offset:3072
	ds_read_b128 v[198:201], v184 offset:4096
	ds_read_b128 v[202:205], v184 offset:5120
	ds_read_b128 v[206:209], v184 offset:6144
	ds_read_b128 v[210:213], v184 offset:7168
	global_load_lds_dwordx4 v[176:177], off
	v_lshl_add_u64 v[176:177], s[16:17], 0, v[166:167]
	s_add_i32 m0, s40, 0xe000
	s_nop 0
	global_load_lds_dwordx4 v[176:177], off
	s_waitcnt vmcnt(8)
	s_waitcnt lgkmcnt(0)
	s_barrier
	s_setprio 1
	v_mfma_f32_16x16x32_bf16 v[138:141], v[114:117], v[172:175], v[138:141]
	v_mfma_f32_16x16x32_bf16 v[134:137], v[130:133], v[172:175], v[134:137]
	v_mfma_f32_16x16x32_bf16 v[110:113], v[114:117], v[190:193], v[110:113]
	v_mfma_f32_16x16x32_bf16 v[106:109], v[130:133], v[190:193], v[106:109]
	v_mfma_f32_16x16x32_bf16 v[94:97], v[114:117], v[198:201], v[94:97]
	v_mfma_f32_16x16x32_bf16 v[90:93], v[130:133], v[198:201], v[90:93]
	v_mfma_f32_16x16x32_bf16 v[78:81], v[114:117], v[206:209], v[78:81]
	v_mfma_f32_16x16x32_bf16 v[74:77], v[130:133], v[206:209], v[74:77]
	v_mfma_f32_16x16x32_bf16 v[138:141], v[126:129], v[186:189], v[138:141]
	v_mfma_f32_16x16x32_bf16 v[134:137], v[142:145], v[186:189], v[134:137]
	v_mfma_f32_16x16x32_bf16 v[110:113], v[126:129], v[194:197], v[110:113]
	v_mfma_f32_16x16x32_bf16 v[106:109], v[142:145], v[194:197], v[106:109]
	v_mfma_f32_16x16x32_bf16 v[94:97], v[126:129], v[202:205], v[94:97]
	v_mfma_f32_16x16x32_bf16 v[90:93], v[142:145], v[202:205], v[90:93]
	v_mfma_f32_16x16x32_bf16 v[78:81], v[126:129], v[210:213], v[78:81]
	v_mfma_f32_16x16x32_bf16 v[74:77], v[142:145], v[210:213], v[74:77]
	v_mfma_f32_16x16x32_bf16 v[122:125], v[146:149], v[172:175], v[122:125]
	v_mfma_f32_16x16x32_bf16 v[118:121], v[154:157], v[172:175], v[118:121]
	v_mfma_f32_16x16x32_bf16 v[102:105], v[146:149], v[190:193], v[102:105]
	v_mfma_f32_16x16x32_bf16 v[98:101], v[154:157], v[190:193], v[98:101]
	v_mfma_f32_16x16x32_bf16 v[86:89], v[146:149], v[198:201], v[86:89]
	v_mfma_f32_16x16x32_bf16 v[82:85], v[154:157], v[198:201], v[82:85]
	v_mfma_f32_16x16x32_bf16 v[70:73], v[146:149], v[206:209], v[70:73]
	v_mfma_f32_16x16x32_bf16 v[66:69], v[154:157], v[206:209], v[66:69]
	v_mfma_f32_16x16x32_bf16 v[122:125], v[150:153], v[186:189], v[122:125]
	v_mfma_f32_16x16x32_bf16 v[118:121], v[168:171], v[186:189], v[118:121]
	v_mfma_f32_16x16x32_bf16 v[102:105], v[150:153], v[194:197], v[102:105]
	v_mfma_f32_16x16x32_bf16 v[98:101], v[168:171], v[194:197], v[98:101]
	v_mfma_f32_16x16x32_bf16 v[86:89], v[150:153], v[202:205], v[86:89]
	v_mfma_f32_16x16x32_bf16 v[82:85], v[168:171], v[202:205], v[82:85]
	v_mfma_f32_16x16x32_bf16 v[70:73], v[150:153], v[210:213], v[70:73]
	v_mfma_f32_16x16x32_bf16 v[66:69], v[168:171], v[210:213], v[66:69]
	s_setprio 0
	s_barrier
	s_add_i32 s16, s38, s29
	v_lshl_add_u64 v[176:177], s[20:21], 0, v[0:1]
	s_mov_b32 m0, s16
	ds_read_b128 v[172:175], v184 offset:16384
	ds_read_b128 v[186:189], v184 offset:17408
	ds_read_b128 v[190:193], v184 offset:18432
	ds_read_b128 v[194:197], v184 offset:19456
	ds_read_b128 v[198:201], v184 offset:20480
	ds_read_b128 v[202:205], v184 offset:21504
	ds_read_b128 v[206:209], v184 offset:22528
	ds_read_b128 v[210:213], v184 offset:23552
	global_load_lds_dwordx4 v[176:177], off
	s_add_i32 m0, s16, 0x2000
	s_add_u32 s16, s20, 0x5a000
	v_lshl_add_u64 v[214:215], s[20:21], 0, v[162:163]
	s_addc_u32 s17, s21, 0
	s_add_i32 s38, s39, s29
	global_load_lds_dwordx4 v[214:215], off
	v_lshl_add_u64 v[216:217], s[16:17], 0, v[0:1]
	s_mov_b32 m0, s38
	v_lshl_add_u64 v[218:219], s[26:27], 0, v[160:161]
	global_load_lds_dwordx4 v[216:217], off
	v_lshl_add_u64 v[216:217], s[16:17], 0, v[162:163]
	s_add_i32 m0, s38, 0x2000
	s_nop 0
	global_load_lds_dwordx4 v[216:217], off
	v_lshl_add_u64 v[216:217], s[26:27], 0, v[158:159]
	s_mov_b32 m0, s40
	s_nop 0
	global_load_lds_dwordx4 v[216:217], off
	s_mov_b32 m0, s41
	s_nop 0
	global_load_lds_dwordx4 v[218:219], off
	s_waitcnt vmcnt(8)
	s_waitcnt lgkmcnt(0)
	s_barrier
	s_setprio 1
	v_mfma_f32_16x16x32_bf16 v[62:65], v[114:117], v[172:175], v[62:65]
	v_mfma_f32_16x16x32_bf16 v[58:61], v[130:133], v[172:175], v[58:61]
	v_mfma_f32_16x16x32_bf16 v[46:49], v[114:117], v[190:193], v[46:49]
	v_mfma_f32_16x16x32_bf16 v[42:45], v[130:133], v[190:193], v[42:45]
	v_mfma_f32_16x16x32_bf16 v[30:33], v[114:117], v[198:201], v[30:33]
	v_mfma_f32_16x16x32_bf16 v[26:29], v[130:133], v[198:201], v[26:29]
	v_mfma_f32_16x16x32_bf16 v[14:17], v[114:117], v[206:209], v[14:17]
	v_mfma_f32_16x16x32_bf16 v[10:13], v[130:133], v[206:209], v[10:13]
	v_mfma_f32_16x16x32_bf16 v[62:65], v[126:129], v[186:189], v[62:65]
	v_mfma_f32_16x16x32_bf16 v[58:61], v[142:145], v[186:189], v[58:61]
	v_mfma_f32_16x16x32_bf16 v[46:49], v[126:129], v[194:197], v[46:49]
	v_mfma_f32_16x16x32_bf16 v[42:45], v[142:145], v[194:197], v[42:45]
	v_mfma_f32_16x16x32_bf16 v[30:33], v[126:129], v[202:205], v[30:33]
	v_mfma_f32_16x16x32_bf16 v[26:29], v[142:145], v[202:205], v[26:29]
	v_mfma_f32_16x16x32_bf16 v[14:17], v[126:129], v[210:213], v[14:17]
	v_mfma_f32_16x16x32_bf16 v[10:13], v[142:145], v[210:213], v[10:13]
	v_mfma_f32_16x16x32_bf16 v[54:57], v[146:149], v[172:175], v[54:57]
	v_mfma_f32_16x16x32_bf16 v[50:53], v[154:157], v[172:175], v[50:53]
	v_mfma_f32_16x16x32_bf16 v[38:41], v[146:149], v[190:193], v[38:41]
	v_mfma_f32_16x16x32_bf16 v[34:37], v[154:157], v[190:193], v[34:37]
	v_mfma_f32_16x16x32_bf16 v[22:25], v[146:149], v[198:201], v[22:25]
	v_mfma_f32_16x16x32_bf16 v[18:21], v[154:157], v[198:201], v[18:21]
	v_mfma_f32_16x16x32_bf16 v[6:9], v[146:149], v[206:209], v[6:9]
	v_mfma_f32_16x16x32_bf16 v[2:5], v[154:157], v[206:209], v[2:5]
	v_mfma_f32_16x16x32_bf16 v[54:57], v[150:153], v[186:189], v[54:57]
	v_mfma_f32_16x16x32_bf16 v[50:53], v[168:171], v[186:189], v[50:53]
	v_mfma_f32_16x16x32_bf16 v[38:41], v[150:153], v[194:197], v[38:41]
	v_mfma_f32_16x16x32_bf16 v[34:37], v[168:171], v[194:197], v[34:37]
	v_mfma_f32_16x16x32_bf16 v[22:25], v[150:153], v[202:205], v[22:25]
	v_mfma_f32_16x16x32_bf16 v[18:21], v[168:171], v[202:205], v[18:21]
	v_mfma_f32_16x16x32_bf16 v[6:9], v[150:153], v[210:213], v[6:9]
	v_mfma_f32_16x16x32_bf16 v[2:5], v[168:171], v[210:213], v[2:5]
	s_setprio 0
	s_barrier
	s_add_i32 s38, 0, 0x18000
	s_add_i32 s39, 0, 0x1c000
	v_add_u32_e32 v142, s38, v179
	v_add_u32_e32 v168, s39, v179
	ds_read_b128 v[114:117], v142
	ds_read_b128 v[126:129], v142 offset:1024
	ds_read_b128 v[130:133], v142 offset:2048
	ds_read_b128 v[142:145], v142 offset:3072
	ds_read_b128 v[146:149], v168
	ds_read_b128 v[150:153], v168 offset:1024
	ds_read_b128 v[154:157], v168 offset:2048
	ds_read_b128 v[168:171], v168 offset:3072
	s_add_u32 s16, s26, 0x168000
	s_addc_u32 s17, s27, 0
	s_mov_b32 m0, s42
	v_lshl_add_u64 v[220:221], s[16:17], 0, v[158:159]
	ds_read_b128 v[172:175], v184 offset:32768
	ds_read_b128 v[186:189], v184 offset:33792
	ds_read_b128 v[190:193], v184 offset:34816
	ds_read_b128 v[194:197], v184 offset:35840
	ds_read_b128 v[198:201], v184 offset:36864
	ds_read_b128 v[202:205], v184 offset:37888
	ds_read_b128 v[206:209], v184 offset:38912
	ds_read_b128 v[210:213], v184 offset:39936
	global_load_lds_dwordx4 v[220:221], off
	v_lshl_add_u64 v[220:221], s[16:17], 0, v[160:161]
	s_mov_b32 m0, s43
	s_nop 0
	global_load_lds_dwordx4 v[220:221], off
	s_waitcnt vmcnt(8)
	s_waitcnt lgkmcnt(0)
	s_barrier
	s_setprio 1
	v_mfma_f32_16x16x32_bf16 v[138:141], v[114:117], v[172:175], v[138:141]
	v_mfma_f32_16x16x32_bf16 v[134:137], v[130:133], v[172:175], v[134:137]
	v_mfma_f32_16x16x32_bf16 v[110:113], v[114:117], v[190:193], v[110:113]
	v_mfma_f32_16x16x32_bf16 v[106:109], v[130:133], v[190:193], v[106:109]
	v_mfma_f32_16x16x32_bf16 v[94:97], v[114:117], v[198:201], v[94:97]
	v_mfma_f32_16x16x32_bf16 v[90:93], v[130:133], v[198:201], v[90:93]
	v_mfma_f32_16x16x32_bf16 v[78:81], v[114:117], v[206:209], v[78:81]
	v_mfma_f32_16x16x32_bf16 v[74:77], v[130:133], v[206:209], v[74:77]
	v_mfma_f32_16x16x32_bf16 v[138:141], v[126:129], v[186:189], v[138:141]
	v_mfma_f32_16x16x32_bf16 v[134:137], v[142:145], v[186:189], v[134:137]
	v_mfma_f32_16x16x32_bf16 v[110:113], v[126:129], v[194:197], v[110:113]
	v_mfma_f32_16x16x32_bf16 v[106:109], v[142:145], v[194:197], v[106:109]
	v_mfma_f32_16x16x32_bf16 v[94:97], v[126:129], v[202:205], v[94:97]
	v_mfma_f32_16x16x32_bf16 v[90:93], v[142:145], v[202:205], v[90:93]
	v_mfma_f32_16x16x32_bf16 v[78:81], v[126:129], v[210:213], v[78:81]
	v_mfma_f32_16x16x32_bf16 v[74:77], v[142:145], v[210:213], v[74:77]
	v_mfma_f32_16x16x32_bf16 v[122:125], v[146:149], v[172:175], v[122:125]
	v_mfma_f32_16x16x32_bf16 v[118:121], v[154:157], v[172:175], v[118:121]
	v_mfma_f32_16x16x32_bf16 v[102:105], v[146:149], v[190:193], v[102:105]
	v_mfma_f32_16x16x32_bf16 v[98:101], v[154:157], v[190:193], v[98:101]
	v_mfma_f32_16x16x32_bf16 v[86:89], v[146:149], v[198:201], v[86:89]
	v_mfma_f32_16x16x32_bf16 v[82:85], v[154:157], v[198:201], v[82:85]
	v_mfma_f32_16x16x32_bf16 v[70:73], v[146:149], v[206:209], v[70:73]
	v_mfma_f32_16x16x32_bf16 v[66:69], v[154:157], v[206:209], v[66:69]
	v_mfma_f32_16x16x32_bf16 v[122:125], v[150:153], v[186:189], v[122:125]
	v_mfma_f32_16x16x32_bf16 v[118:121], v[168:171], v[186:189], v[118:121]
	v_mfma_f32_16x16x32_bf16 v[102:105], v[150:153], v[194:197], v[102:105]
	v_mfma_f32_16x16x32_bf16 v[98:101], v[168:171], v[194:197], v[98:101]
	v_mfma_f32_16x16x32_bf16 v[86:89], v[150:153], v[202:205], v[86:89]
	v_mfma_f32_16x16x32_bf16 v[82:85], v[168:171], v[202:205], v[82:85]
	v_mfma_f32_16x16x32_bf16 v[70:73], v[150:153], v[210:213], v[70:73]
	v_mfma_f32_16x16x32_bf16 v[66:69], v[168:171], v[210:213], v[66:69]
	s_setprio 0
	s_barrier
	s_add_i32 s16, s38, s29
	v_lshl_add_u64 v[176:177], v[176:177], 0, s[22:23]
	s_mov_b32 m0, s16
	ds_read_b128 v[172:175], v184 offset:49152
	ds_read_b128 v[186:189], v184 offset:50176
	ds_read_b128 v[190:193], v184 offset:51200
	ds_read_b128 v[194:197], v184 offset:52224
	ds_read_b128 v[198:201], v184 offset:53248
	ds_read_b128 v[202:205], v184 offset:54272
	ds_read_b128 v[206:209], v184 offset:55296
	ds_read_b128 v[210:213], v184 offset:56320
	global_load_lds_dwordx4 v[176:177], off
	s_add_i32 m0, s16, 0x2000
	s_add_u32 s16, s20, 0x5a080
	v_lshl_add_u64 v[176:177], v[214:215], 0, s[22:23]
	s_addc_u32 s17, s21, 0
	s_add_i32 s20, s39, s29
	global_load_lds_dwordx4 v[176:177], off
	v_lshl_add_u64 v[176:177], s[16:17], 0, v[0:1]
	s_mov_b32 m0, s20
	s_nop 0
	global_load_lds_dwordx4 v[176:177], off
	v_lshl_add_u64 v[176:177], s[16:17], 0, v[162:163]
	s_add_i32 m0, s20, 0x2000
	s_nop 0
	global_load_lds_dwordx4 v[176:177], off
	v_lshl_add_u64 v[176:177], v[216:217], 0, s[22:23]
	s_mov_b32 m0, s44
	s_nop 0
	global_load_lds_dwordx4 v[176:177], off
	v_lshl_add_u64 v[176:177], v[218:219], 0, s[22:23]
	s_mov_b32 m0, s45
	s_nop 0
	global_load_lds_dwordx4 v[176:177], off
	s_waitcnt vmcnt(8)
	s_waitcnt lgkmcnt(0)
	s_barrier
	s_setprio 1
	v_mfma_f32_16x16x32_bf16 v[62:65], v[114:117], v[172:175], v[62:65]
	v_mfma_f32_16x16x32_bf16 v[58:61], v[130:133], v[172:175], v[58:61]
	v_mfma_f32_16x16x32_bf16 v[46:49], v[114:117], v[190:193], v[46:49]
	v_mfma_f32_16x16x32_bf16 v[42:45], v[130:133], v[190:193], v[42:45]
	v_mfma_f32_16x16x32_bf16 v[30:33], v[114:117], v[198:201], v[30:33]
	v_mfma_f32_16x16x32_bf16 v[26:29], v[130:133], v[198:201], v[26:29]
	v_mfma_f32_16x16x32_bf16 v[14:17], v[114:117], v[206:209], v[14:17]
	v_mfma_f32_16x16x32_bf16 v[10:13], v[130:133], v[206:209], v[10:13]
	v_mfma_f32_16x16x32_bf16 v[62:65], v[126:129], v[186:189], v[62:65]
	v_mfma_f32_16x16x32_bf16 v[58:61], v[142:145], v[186:189], v[58:61]
	v_mfma_f32_16x16x32_bf16 v[46:49], v[126:129], v[194:197], v[46:49]
	v_mfma_f32_16x16x32_bf16 v[42:45], v[142:145], v[194:197], v[42:45]
	v_mfma_f32_16x16x32_bf16 v[30:33], v[126:129], v[202:205], v[30:33]
	v_mfma_f32_16x16x32_bf16 v[26:29], v[142:145], v[202:205], v[26:29]
	v_mfma_f32_16x16x32_bf16 v[14:17], v[126:129], v[210:213], v[14:17]
	v_mfma_f32_16x16x32_bf16 v[10:13], v[142:145], v[210:213], v[10:13]
	v_mfma_f32_16x16x32_bf16 v[54:57], v[146:149], v[172:175], v[54:57]
	v_mfma_f32_16x16x32_bf16 v[50:53], v[154:157], v[172:175], v[50:53]
	v_mfma_f32_16x16x32_bf16 v[38:41], v[146:149], v[190:193], v[38:41]
	v_mfma_f32_16x16x32_bf16 v[34:37], v[154:157], v[190:193], v[34:37]
	v_mfma_f32_16x16x32_bf16 v[22:25], v[146:149], v[198:201], v[22:25]
	v_mfma_f32_16x16x32_bf16 v[18:21], v[154:157], v[198:201], v[18:21]
	v_mfma_f32_16x16x32_bf16 v[6:9], v[146:149], v[206:209], v[6:9]
	v_mfma_f32_16x16x32_bf16 v[2:5], v[154:157], v[206:209], v[2:5]
	v_mfma_f32_16x16x32_bf16 v[54:57], v[150:153], v[186:189], v[54:57]
	v_mfma_f32_16x16x32_bf16 v[50:53], v[168:171], v[186:189], v[50:53]
	v_mfma_f32_16x16x32_bf16 v[38:41], v[150:153], v[194:197], v[38:41]
	v_mfma_f32_16x16x32_bf16 v[34:37], v[168:171], v[194:197], v[34:37]
	v_mfma_f32_16x16x32_bf16 v[22:25], v[150:153], v[202:205], v[22:25]
	v_mfma_f32_16x16x32_bf16 v[18:21], v[168:171], v[202:205], v[18:21]
	v_mfma_f32_16x16x32_bf16 v[6:9], v[150:153], v[210:213], v[6:9]
	v_mfma_f32_16x16x32_bf16 v[2:5], v[168:171], v[210:213], v[2:5]
	s_setprio 0
	s_barrier
	s_add_i32 s30, s30, 2
	s_add_u32 s2, s2, 0x100
	s_addc_u32 s3, s3, 0
	s_cmpk_gt_u32 s30, 0x55
	s_mov_b64 s[16:17], s[18:19]
	s_cbranch_scc0 .LBB0_1868
	s_and_b64 vcc, exec, s[10:11]
	s_cbranch_vccz .LBB0_1871
	s_barrier
